# w_in epilogue: every tile class (XA, Q, K|V, U, gates) has a straight-line path per wave parity, rope table quads loaded once per 16-row block; generic epilogue removed
# speedup vs baseline: 1.0070x; 1.0070x over previous
;     __device__ __forceinline__ void operator()(const f32x4 (&acc)[2][2][4][2], const Unit& u, int wr, int wc, int fr, int fq) const {
;         const int pn = u.pn;
; #pragma unroll
;         for (int ai = 0; ai < 2; ++ai)
; #pragma unroll
;             for (int m = 0; m < 4; ++m) { const int row = u.pm * 256 + ai * 128 + wr * 64 + m * 16 + fr;
; #pragma unroll
;                 for (int bj = 0; bj < 2; ++bj)
; #pragma unroll
;                     for (int n = 0; n < 2; ++n) { const int tc = bj * 128 + wc * 32 + 8 * fq + 4 * n; f32x4 v = acc[ai][bj][m][n];
;                         if (pn < 2) { *(f32x4*)(XA + (size_t)row * 512 + pn * 256 + tc) = v; }
;                         else if (pn <= 4) {
;                             const bool isv = (pn == 4 && bj == 1);
;                             if (!isv && (wc & 1) == 0) {
;                                 const int tix = row < cfg::MP ? (row & 2047) : 2048 + (row & 3);
;                                 const f32x4 cs = *(const f32x4*)(ropec + tix * 8 + 4 * n), sn = *(const f32x4*)(ropes + tix * 8 + 4 * n);
; #pragma unroll
;                                 for (int i = 0; i < 4; ++i) { const float p = shx16(v[i], fq & 1); const float rv = v[i] * cs[i] + (fq == 0 ? -p : p) * sn[i]; v[i] = fq < 2 ? rv : v[i]; }
;                             }
;                             if (pn < 4) st_bf4(Q + (size_t)row * 512 + (pn - 2) * 256 + tc, v);
;                             else { st_bf4((bj == 0 ? KB : VB) + (size_t)row * 128 + (tc & 127), v);
;                                 bool w = false; size_t o = 0;
;                                 if (row < cfg::MP) { const int t = row & 2047; if (t >= 1920) { w = true; o = (bj == 0 ? cfg::OFF_KP : cfg::OFF_VP) + ((size_t)(layer * 8 + (row >> 11)) * 128 + (t - 1920)) * 128 + (tc & 127); } }
;                                 else { const int rs = row - cfg::MP; w = true; o = (bj == 0 ? cfg::OFF_KS : cfg::OFF_VS) + ((size_t)(layer * 128 + (rs >> 2)) * 128 + 124 + (rs & 3)) * 128 + (tc & 127); }
;                                 if (w) *(f32x4*)(out + o) = v; }
;                         }
;                         else if (pn < 7) { *(f32x4*)(U + (size_t)row * 512 + (pn - 5) * 256 + tc) = v; }
;                         else { f32x4 s; s[0] = sigm(v[0]); s[1] = sigm(v[1]); s[2] = sigm(v[2]); s[3] = sigm(v[3]); st_bf4(GT + (size_t)row * 3072 + (pn - 7) * 256 + tc, s); }
.Lsp_notq:
	s_and_b64 vcc, exec, s[76:77]
	s_cbranch_vccnz .Lsp_kv1
	s_branch .Lsp_kv0
.LBB0_1034:
.LBB0_1036:
.LBB0_1037:
.LBB0_1040:
.LBB0_1042:
.LBB0_1043:
.LBB0_1044:
.LBB0_1045:
.LBB0_1047:
.LBB0_1051:
.LBB0_1053:
.LBB0_1054:
.LBB0_1057:
.LBB0_1059:
.LBB0_1060:
.LBB0_1061:
.LBB0_1062:
.LBB0_1064:
.LBB0_1068:
.LBB0_1070:
.LBB0_1071:
.LBB0_1074:
.LBB0_1076:
.LBB0_1077:
.LBB0_1078:
.LBB0_1079:
.LBB0_1080:
.LBB0_1083:
.LBB0_1085:
.LBB0_1086:
.LBB0_1089:
.LBB0_1091:
.LBB0_1092:
.LBB0_1093:
.LBB0_1094:
.LBB0_1095:
.LBB0_1096:
.LBB0_1097:
.LBB0_1098:
.LBB0_1102:
.LBB0_1104:
.LBB0_1105:
.LBB0_1108:
.LBB0_1110:
.LBB0_1111:
.LBB0_1112:
.LBB0_1113:
.LBB0_1114:
.LBB0_1117:
.LBB0_1119:
.LBB0_1120:
.LBB0_1123:
.LBB0_1125:
.LBB0_1126:
.LBB0_1127:
.LBB0_1128:
.LBB0_1129:
.LBB0_1130:
.LBB0_1131:
.LBB0_1132:
.LBB0_1136:
.LBB0_1138:
.LBB0_1139:
.LBB0_1142:
.LBB0_1144:
.LBB0_1145:
.LBB0_1146:
.LBB0_1147:
.LBB0_1148:
.LBB0_1151:
.LBB0_1153:
.LBB0_1154:
.LBB0_1157:
.LBB0_1159:
.LBB0_1160:
.LBB0_1161:
.LBB0_1162:
.LBB0_1163:
.LBB0_1164:
.LBB0_1165:
.LBB0_1166:
.LBB0_1170:
.LBB0_1172:
.LBB0_1173:
.LBB0_1176:
.LBB0_1178:
.LBB0_1179:
.LBB0_1180:
.LBB0_1181:
.LBB0_1182:
.LBB0_1185:
.LBB0_1187:
.LBB0_1188:
.LBB0_1191:
.LBB0_1193:
.LBB0_1194:
.LBB0_1195:
.LBB0_1196:
.LBB0_1197:
.LBB0_1198:
.LBB0_1199:
.LBB0_1200:
.LBB0_1204:
.LBB0_1206:
.LBB0_1207:
.LBB0_1210:
.LBB0_1212:
.LBB0_1213:
.LBB0_1214:
.LBB0_1215:
.LBB0_1216:
.LBB0_1219:
.LBB0_1221:
.LBB0_1222:
.LBB0_1225:
.LBB0_1227:
.LBB0_1228:
.LBB0_1229:
.LBB0_1230:
.LBB0_1231:
.LBB0_1232:
.LBB0_1233:
.LBB0_1234:
.LBB0_1238:
.LBB0_1240:
.LBB0_1241:
.LBB0_1244:
.LBB0_1246:
.LBB0_1247:
.LBB0_1248:
.LBB0_1249:
.LBB0_1250:
.LBB0_1253:
.LBB0_1255:
.LBB0_1256:
.LBB0_1259:
.LBB0_1261:
.LBB0_1262:
.LBB0_1263:
.LBB0_1264:
.LBB0_1265:
.LBB0_1266:
.LBB0_1267:
.LBB0_1268:
.LBB0_1272:
.LBB0_1274:
.LBB0_1275:
.LBB0_1278:
.LBB0_1280:
.LBB0_1281:
.LBB0_1282:
.LBB0_1283:
.LBB0_1284:
.LBB0_1287:
.LBB0_1289:
.LBB0_1290:
.LBB0_1293:
.LBB0_1295:
.LBB0_1296:
.LBB0_1297:
.LBB0_1298:
.LBB0_1299:
.LBB0_1300:
.LBB0_1301:
.LBB0_1302:
.LBB0_1306:
.LBB0_1308:
.LBB0_1309:
.LBB0_1312:
.LBB0_1314:
.LBB0_1315:
.LBB0_1316:
.LBB0_1317:
.LBB0_1318:
.LBB0_1321:
.LBB0_1323:
.LBB0_1324:
.LBB0_1327:
.LBB0_1329:
.LBB0_1330:
.LBB0_1331:
.LBB0_1332:
.LBB0_1333:
.LBB0_1334:
.LBB0_1335:
.LBB0_1336:
.LBB0_1340:
.LBB0_1342:
.LBB0_1343:
.LBB0_1346:
.LBB0_1348:
.LBB0_1349:
.LBB0_1350:
.LBB0_1351:
.LBB0_1352:
.LBB0_1355:
.LBB0_1357:
.LBB0_1358:
.LBB0_1361:
.LBB0_1363:
.LBB0_1364:
.LBB0_1365:
.LBB0_1366:
.LBB0_1367:
.LBB0_1368:
.LBB0_1369:
.LBB0_1370:
.LBB0_1374:
.LBB0_1376:
.LBB0_1377:
.LBB0_1380:
.LBB0_1382:
.LBB0_1383:
.LBB0_1384:
.LBB0_1385:
.LBB0_1386:
.LBB0_1389:
.LBB0_1391:
.LBB0_1392:
.LBB0_1395:
.LBB0_1397:
.LBB0_1398:
.LBB0_1399:
.LBB0_1400:
.LBB0_1401:
.LBB0_1402:
.LBB0_1403:
.LBB0_1404:
.LBB0_1408:
.LBB0_1410:
.LBB0_1411:
.LBB0_1414:
.LBB0_1416:
.LBB0_1417:
.LBB0_1418:
.LBB0_1419:
.LBB0_1420:
.LBB0_1423:
.LBB0_1425:
.LBB0_1426:
.LBB0_1429:
.LBB0_1431:
.LBB0_1432:
.LBB0_1433:
.LBB0_1434:
.LBB0_1435:
.LBB0_1436:
.LBB0_1437:
.LBB0_1438:
.LBB0_1442:
.LBB0_1444:
.LBB0_1445:
.LBB0_1448:
.LBB0_1450:
.LBB0_1451:
.LBB0_1452:
.LBB0_1453:
.LBB0_1454:
.LBB0_1457:
.LBB0_1459:
.LBB0_1460:
.LBB0_1463:
.LBB0_1465:
.LBB0_1466:
.LBB0_1467:
.LBB0_1468:
.LBB0_1469:
.LBB0_1470:
.LBB0_1471:
.LBB0_1472:
.LBB0_1476:
.LBB0_1478:
.LBB0_1479:
.LBB0_1482:
.LBB0_1484:
.LBB0_1485:
.LBB0_1486:
.LBB0_1487:
.LBB0_1488:
.LBB0_1491:
.LBB0_1493:
.LBB0_1494:
.LBB0_1497:
.LBB0_1499:
.LBB0_1500:
.LBB0_1501:
.LBB0_1502:
.LBB0_1503:
.LBB0_1504:
.LBB0_1505:
.LBB0_1506:
.LBB0_1510:
.LBB0_1512:
.LBB0_1513:
.LBB0_1516:
.LBB0_1518:
.LBB0_1519:
.LBB0_1520:
.LBB0_1521:
.LBB0_1522:
.LBB0_1525:
.LBB0_1527:
.LBB0_1528:
.LBB0_1531:
.LBB0_1533:
.LBB0_1534:
.LBB0_1535:
.LBB0_1536:
.LBB0_1537:
.LBB0_1538:
.LBB0_1539:
.LBB0_1540:
.LBB0_1544:
.LBB0_1546:
.LBB0_1547:
.LBB0_1550:
.LBB0_1552:
.LBB0_1553:
.LBB0_1554:
.LBB0_1555:
.LBB0_1557:
.LBB0_1561:
.LBB0_1563:
.LBB0_1564:
.LBB0_1567:
.LBB0_1569:
.LBB0_1570:
.LBB0_1571:
.LBB0_1572:
.LBB0_1574:
	s_andn2_b64 vcc, exec, s[12:13]
	s_mov_b64 s[0:1], -1
	s_movk_i32 s96, 0x200
	s_mov_b32 s97, 0x200000
	s_cbranch_vccnz .LBB0_1019
	v_readlane_b32 s0, v254, 54
	v_readlane_b32 s1, v254, 55
	s_andn2_b64 vcc, exec, s[0:1]
	s_cbranch_vccnz .LBB0_1018
	s_barrier
	s_branch .LBB0_1018

; __device__ __forceinline__ float shx16(float v, int odd  ) { const unsigned x = __builtin_bit_cast(unsigned, v); auto r = __builtin_amdgcn_permlane16_swap(x, x, false, false); return __builtin_bit_cast(float, odd ? r[0] : r[1]); }
; __device__ __forceinline__ void st_bf4(bf16_t* p, const f32x4 v) { u32x2 w; w.x = cvt_pk_bf16(v[0], v[1]); w.y = cvt_pk_bf16(v[2], v[3]); *(u32x2*)p = w; }
;     __device__ __forceinline__ void operator()(const f32x4 (&acc)[2][2][4][2], const Unit& u, int wr, int wc, int fr, int fq) const {
;     ...
;                             const bool isv = (pn == 4 && bj == 1);
;                             if (!isv && (wc & 1) == 0) {
;                                 const int tix = row < cfg::MP ? (row & 2047) : 2048 + (row & 3);
;                                 const f32x4 cs = *(const f32x4*)(ropec + tix * 8 + 4 * n), sn = *(const f32x4*)(ropes + tix * 8 + 4 * n);
; #pragma unroll
;                                 for (int i = 0; i < 4; ++i) { const float p = shx16(v[i], fq & 1); const float rv = v[i] * cs[i] + (fq == 0 ? -p : p) * sn[i]; v[i] = fq < 2 ? rv : v[i]; }
;                             }
;                             if (pn < 4) st_bf4(Q + (size_t)row * 512 + (pn - 2) * 256 + tc, v);
;                             else { st_bf4((bj == 0 ? KB : VB) + (size_t)row * 128 + (tc & 127), v);
;                                 bool w = false; size_t o = 0;
;                                 if (row < cfg::MP) { const int t = row & 2047; if (t >= 1920) { w = true; o = (bj == 0 ? cfg::OFF_KP : cfg::OFF_VP) + ((size_t)(layer * 8 + (row >> 11)) * 128 + (t - 1920)) * 128 + (tc & 127); } }
;                                 else { const int rs = row - cfg::MP; w = true; o = (bj == 0 ? cfg::OFF_KS : cfg::OFF_VS) + ((size_t)(layer * 128 + (rs >> 2)) * 128 + 124 + (rs & 3)) * 128 + (tc & 127); }
;                                 if (w) *(f32x4*)(out + o) = v; }
.Lsp_kv0:
	s_nop 7
	v_lshlrev_b32_e32 v96, 2, v203
	global_load_dwordx4 v[208:211], v96, s[44:45]
	global_load_dwordx4 v[212:215], v96, s[4:5]
	global_load_dwordx4 v[216:219], v96, s[44:45] offset:16
	global_load_dwordx4 v[220:223], v96, s[4:5] offset:16
	v_mov_b32_e32 v96, v126
	v_mov_b32_e32 v146, v126
	s_nop 1
	v_permlane16_swap_b32_e32 v96, v146
	v_cndmask_b32_e64 v96, v96, v146, s[6:7]
	v_cndmask_b32_e64 v147, v96, -v96, s[10:11]
	v_mov_b32_e32 v148, v126
	s_waitcnt vmcnt(2)
	v_mov_b32_e32 v146, v208
	v_mov_b32_e32 v149, v212
	v_pk_mul_f32 v[146:147], v[148:149], v[146:147]
	v_mov_b32_e32 v186, v127
	v_add_f32_e32 v96, v146, v147
	v_cndmask_b32_e64 v130, v126, v96, s[8:9]
	v_mov_b32_e32 v96, v127
	v_mov_b32_e32 v146, v127
	s_nop 1
	v_permlane16_swap_b32_e32 v96, v146
	v_cndmask_b32_e64 v96, v96, v146, s[6:7]
	v_cndmask_b32_e64 v147, v96, -v96, s[10:11]
	v_mov_b32_e32 v146, v209
	v_mov_b32_e32 v187, v213
	v_pk_mul_f32 v[146:147], v[186:187], v[146:147]
	v_mov_b32_e32 v148, v128
	v_add_f32_e32 v96, v146, v147
	v_cndmask_b32_e64 v131, v127, v96, s[8:9]
	v_mov_b32_e32 v96, v128
	v_mov_b32_e32 v146, v128
	s_nop 1
	v_permlane16_swap_b32_e32 v96, v146
	v_cndmask_b32_e64 v96, v96, v146, s[6:7]
	v_cndmask_b32_e64 v147, v96, -v96, s[10:11]
	v_mov_b32_e32 v149, v214
	v_mov_b32_e32 v146, v210
	v_pk_mul_f32 v[146:147], v[148:149], v[146:147]
	v_mov_b32_e32 v188, v129
	v_add_f32_e32 v96, v146, v147
	v_cndmask_b32_e64 v132, v128, v96, s[8:9]
	v_mov_b32_e32 v96, v129
	v_mov_b32_e32 v146, v129
	s_nop 1
	v_permlane16_swap_b32_e32 v96, v146
	v_cndmask_b32_e64 v96, v96, v146, s[6:7]
	v_cndmask_b32_e64 v147, v96, -v96, s[10:11]
	v_mov_b32_e32 v146, v211
	v_mov_b32_e32 v189, v215
	v_pk_mul_f32 v[146:147], v[188:189], v[146:147]
	v_mov_b32_e32 v173, v130
	v_add_f32_e32 v96, v146, v147
	v_cndmask_b32_e64 v133, v129, v96, s[8:9]
	v_mov_b32_e32 v205, v131
	v_mov_b32_e32 v204, v132
	v_mov_b32_e32 v206, v133
	v_lshl_add_u64 v[146:147], v[154:155], 0, v[176:177]
	v_cvt_pk_bf16_f32 v148, v173, v205
	v_cvt_pk_bf16_f32 v149, v204, v206
	global_store_dwordx2 v[146:147], v[148:149], off
	s_and_saveexec_b64 s[16:17], s[20:21]
	s_xor_b64 s[16:17], exec, s[16:17]
	s_mov_b64 s[14:15], exec
	v_add_u32_e32 v186, s87, v202
	s_or_saveexec_b64 s[16:17], s[16:17]
	v_mov_b64_e32 v[188:189], v[160:161]
	s_xor_b64 exec, exec, s[16:17]
	s_and_saveexec_b64 s[80:81], s[18:19]
	v_readlane_b32 s86, v254, 37
	s_add_i32 vcc_lo, s75, s86
	s_or_b64 s[92:93], s[14:15], exec
	v_readlane_b32 s87, v254, 38
	s_or_b64 exec, exec, s[80:81]
	s_andn2_b64 s[14:15], s[14:15], exec
	s_and_b64 s[80:81], s[92:93], exec
	v_mov_b32_e32 v186, vcc_lo
	s_or_b64 s[14:15], s[14:15], s[80:81]
	v_mov_b64_e32 v[188:189], v[184:185]
	v_readlane_b32 s86, v254, 63
	v_readlane_b32 s87, v255, 0
	s_or_b64 exec, exec, s[16:17]
	s_and_saveexec_b64 s[16:17], s[14:15]
	v_ashrrev_i32_e32 v187, 31, v186
	v_lshl_add_u64 v[146:147], v[188:189], 2, v[156:157]
	v_lshlrev_b64 v[148:149], 16, v[186:187]
	v_lshl_add_u64 v[146:147], v[146:147], 0, v[148:149]
	global_store_dwordx4 v[146:147], v[130:133], off
	s_or_b64 exec, exec, s[16:17]
	s_ashr_i32 s93, s0, 31
	s_mov_b32 s92, s0
	v_lshlrev_b32_e32 v130, 2, v142
	v_lshlrev_b32_e32 v96, 2, v203
	v_mov_b32_e32 v96, v122
	v_mov_b32_e32 v131, v122
	s_nop 1
	v_permlane16_swap_b32_e32 v96, v131
	v_cndmask_b32_e64 v96, v96, v131, s[6:7]
	v_cndmask_b32_e64 v147, v96, -v96, s[10:11]
	v_mov_b32_e32 v148, v122
	v_mov_b32_e32 v131, v123
	s_waitcnt vmcnt(1)
	v_mov_b32_e32 v146, v216
	v_mov_b32_e32 v149, v220
	v_pk_mul_f32 v[146:147], v[148:149], v[146:147]
	v_mov_b32_e32 v186, v123
	v_add_f32_e32 v96, v146, v147
	v_cndmask_b32_e64 v126, v122, v96, s[8:9]
	v_mov_b32_e32 v96, v123
	s_nop 1
	v_permlane16_swap_b32_e32 v96, v131
	v_cndmask_b32_e64 v96, v96, v131, s[6:7]
	v_cndmask_b32_e64 v147, v96, -v96, s[10:11]
	v_mov_b32_e32 v146, v217
	v_mov_b32_e32 v187, v221
	v_pk_mul_f32 v[146:147], v[186:187], v[146:147]
	v_mov_b32_e32 v131, v124
	v_add_f32_e32 v96, v146, v147
	v_cndmask_b32_e64 v127, v123, v96, s[8:9]
	v_mov_b32_e32 v96, v124
	s_nop 1
	v_permlane16_swap_b32_e32 v96, v131
	v_cndmask_b32_e64 v96, v96, v131, s[6:7]
	v_cndmask_b32_e64 v147, v96, -v96, s[10:11]
	v_mov_b32_e32 v148, v124
	v_mov_b32_e32 v149, v222
	v_mov_b32_e32 v146, v218
	v_pk_mul_f32 v[146:147], v[148:149], v[146:147]
	v_mov_b32_e32 v131, v125
	v_add_f32_e32 v96, v146, v147
	v_cndmask_b32_e64 v128, v124, v96, s[8:9]
	v_mov_b32_e32 v96, v125
	s_nop 1
	v_permlane16_swap_b32_e32 v96, v131
	v_cndmask_b32_e64 v96, v96, v131, s[6:7]
	v_cndmask_b32_e64 v147, v96, -v96, s[10:11]
	v_mov_b32_e32 v188, v125
	v_mov_b32_e32 v146, v219
	v_mov_b32_e32 v189, v223
	v_pk_mul_f32 v[146:147], v[188:189], v[146:147]
	v_mov_b32_e32 v131, v126
	v_add_f32_e32 v96, v146, v147
	v_cndmask_b32_e64 v129, v125, v96, s[8:9]
	v_mov_b32_e32 v204, v127
	v_mov_b32_e32 v173, v128
	v_mov_b32_e32 v205, v129
	v_lshl_add_u64 v[146:147], v[164:165], 0, v[176:177]
	v_cvt_pk_bf16_f32 v148, v131, v204
	v_cvt_pk_bf16_f32 v149, v173, v205
	global_store_dwordx2 v[146:147], v[148:149], off
	s_and_saveexec_b64 s[78:79], s[20:21]
	s_xor_b64 s[78:79], exec, s[78:79]
	s_mov_b64 s[70:71], exec
	v_add_u32_e32 v186, s87, v202
	s_or_saveexec_b64 s[78:79], s[78:79]
	v_mov_b64_e32 v[188:189], v[160:161]
	s_xor_b64 exec, exec, s[78:79]
	s_and_saveexec_b64 s[80:81], s[18:19]
	v_readlane_b32 s86, v254, 37
	s_add_i32 s46, s75, s86
	s_or_b64 vcc, s[70:71], exec
	v_readlane_b32 s87, v254, 38
	s_or_b64 exec, exec, s[80:81]
	s_andn2_b64 s[70:71], s[70:71], exec
	s_and_b64 s[80:81], vcc, exec
	v_mov_b32_e32 v186, s46
	s_or_b64 s[70:71], s[70:71], s[80:81]
	v_mov_b64_e32 v[188:189], v[184:185]
; __device__ __forceinline__ float shx16(float v, int odd  ) { const unsigned x = __builtin_bit_cast(unsigned, v); auto r = __builtin_amdgcn_permlane16_swap(x, x, false, false); return __builtin_bit_cast(float, odd ? r[0] : r[1]); }
; __device__ __forceinline__ void st_bf4(bf16_t* p, const f32x4 v) { u32x2 w; w.x = cvt_pk_bf16(v[0], v[1]); w.y = cvt_pk_bf16(v[2], v[3]); *(u32x2*)p = w; }
;     __device__ __forceinline__ void operator()(const f32x4 (&acc)[2][2][4][2], const Unit& u, int wr, int wc, int fr, int fq) const {
;     ...
;                                 const int tix = row < cfg::MP ? (row & 2047) : 2048 + (row & 3);
;                                 const f32x4 cs = *(const f32x4*)(ropec + tix * 8 + 4 * n), sn = *(const f32x4*)(ropes + tix * 8 + 4 * n);
; #pragma unroll
;                                 for (int i = 0; i < 4; ++i) { const float p = shx16(v[i], fq & 1); const float rv = v[i] * cs[i] + (fq == 0 ? -p : p) * sn[i]; v[i] = fq < 2 ? rv : v[i]; }
;                             }
;                             if (pn < 4) st_bf4(Q + (size_t)row * 512 + (pn - 2) * 256 + tc, v);
;                             else { st_bf4((bj == 0 ? KB : VB) + (size_t)row * 128 + (tc & 127), v);
;                                 bool w = false; size_t o = 0;
;                                 if (row < cfg::MP) { const int t = row & 2047; if (t >= 1920) { w = true; o = (bj == 0 ? cfg::OFF_KP : cfg::OFF_VP) + ((size_t)(layer * 8 + (row >> 11)) * 128 + (t - 1920)) * 128 + (tc & 127); } }
;                                 else { const int rs = row - cfg::MP; w = true; o = (bj == 0 ? cfg::OFF_KS : cfg::OFF_VS) + ((size_t)(layer * 128 + (rs >> 2)) * 128 + 124 + (rs & 3)) * 128 + (tc & 127); }
;                                 if (w) *(f32x4*)(out + o) = v; }
	v_readlane_b32 s86, v254, 63
	v_readlane_b32 s87, v255, 0
	s_or_b64 exec, exec, s[78:79]
	s_and_saveexec_b64 s[78:79], s[70:71]
	v_ashrrev_i32_e32 v187, 31, v186
	v_lshl_add_u64 v[146:147], v[188:189], 2, v[156:157]
	v_lshlrev_b64 v[148:149], 16, v[186:187]
	v_lshl_add_u64 v[146:147], v[146:147], 0, v[148:149]
	global_store_dwordx4 v[146:147], v[126:129], off offset:16
	s_or_b64 exec, exec, s[78:79]
	v_readlane_b32 s70, v254, 59
	v_readlane_b32 s71, v254, 60
	s_mov_b64 s[78:79], 0x1100000
	v_lshl_add_u64 v[126:127], v[182:183], 0, s[78:79]
	v_mov_b64_e32 v[124:125], v[120:121]
	v_mov_b64_e32 v[122:123], v[118:119]
	v_mov_b32_e32 v131, v118
	v_mov_b32_e32 v184, v119
	v_mov_b32_e32 v173, v120
	v_mov_b32_e32 v185, v121
	v_lshl_add_u64 v[128:129], v[158:159], 0, v[176:177]
	v_cvt_pk_bf16_f32 v146, v131, v184
	v_cvt_pk_bf16_f32 v147, v173, v185
	global_store_dwordx2 v[128:129], v[146:147], off
	s_and_saveexec_b64 s[78:79], s[20:21]
	s_xor_b64 s[78:79], exec, s[78:79]
	s_mov_b64 s[70:71], exec
	v_add_u32_e32 v128, s87, v202
	s_or_saveexec_b64 s[78:79], s[78:79]
	v_mov_b64_e32 v[182:183], v[162:163]
	s_xor_b64 exec, exec, s[78:79]
	s_and_saveexec_b64 vcc, s[18:19]
	v_readlane_b32 s80, v254, 37
	v_readlane_b32 s81, v254, 38
	s_add_i32 s46, s75, s80
	s_or_b64 s[80:81], s[70:71], exec
	s_or_b64 exec, exec, vcc
	s_andn2_b64 s[70:71], s[70:71], exec
	s_and_b64 s[80:81], s[80:81], exec
	v_mov_b32_e32 v128, s46
	s_or_b64 s[70:71], s[70:71], s[80:81]
	v_mov_b64_e32 v[182:183], v[126:127]
	v_readlane_b32 s86, v254, 63
	v_readlane_b32 s87, v255, 0
	s_or_b64 exec, exec, s[78:79]
	s_and_saveexec_b64 s[78:79], s[70:71]
	v_ashrrev_i32_e32 v129, 31, v128
	v_lshl_add_u64 v[146:147], v[182:183], 2, v[156:157]
	v_lshlrev_b64 v[128:129], 16, v[128:129]
	v_lshl_add_u64 v[128:129], v[146:147], 0, v[128:129]
	global_store_dwordx4 v[128:129], v[122:125], off
	s_or_b64 exec, exec, s[78:79]
	v_mov_b64_e32 v[120:121], v[116:117]
	v_mov_b64_e32 v[118:119], v[114:115]
	v_mov_b32_e32 v128, v114
	v_mov_b32_e32 v131, v115
	v_mov_b32_e32 v129, v116
	v_mov_b32_e32 v173, v117
	s_andn2_b64 vcc, exec, s[96:97]
	v_lshl_add_u64 v[122:123], v[166:167], 0, v[176:177]
	v_cvt_pk_bf16_f32 v124, v128, v131
	v_cvt_pk_bf16_f32 v125, v129, v173
	global_store_dwordx2 v[122:123], v[124:125], off
	s_and_saveexec_b64 s[78:79], s[20:21]
	s_xor_b64 s[20:21], exec, s[78:79]
	s_mov_b64 s[70:71], exec
	v_add_u32_e32 v122, s87, v202
	s_or_saveexec_b64 s[20:21], s[20:21]
	v_mov_b64_e32 v[124:125], v[162:163]
	s_xor_b64 exec, exec, s[20:21]
	s_and_saveexec_b64 s[80:81], s[18:19]
	v_readlane_b32 s18, v254, 37
	s_add_i32 s46, s75, s18
	s_or_b64 s[78:79], s[70:71], exec
	v_readlane_b32 s19, v254, 38
	s_or_b64 exec, exec, s[80:81]
	s_andn2_b64 s[18:19], s[70:71], exec
	s_and_b64 s[70:71], s[78:79], exec
	v_mov_b32_e32 v122, s46
	s_or_b64 s[70:71], s[18:19], s[70:71]
	v_mov_b64_e32 v[124:125], v[126:127]
	s_or_b64 exec, exec, s[20:21]
	s_and_saveexec_b64 s[18:19], s[70:71]
	v_ashrrev_i32_e32 v123, 31, v122
	v_lshl_add_u64 v[124:125], v[124:125], 2, v[156:157]
	v_lshlrev_b64 v[122:123], 16, v[122:123]
	v_lshl_add_u64 v[122:123], v[124:125], 0, v[122:123]
	global_store_dwordx4 v[122:123], v[118:121], off offset:16
	s_or_b64 exec, exec, s[18:19]
	v_or_b32_e32 v114, 16, v172
	v_mad_i64_i32 v[124:125], s[18:19], v114, s61, 0
	s_movk_i32 s18, 0x3fff
	s_nop 0
	v_cmp_lt_i32_e64 s[20:21], s18, v114
	s_movk_i32 s18, 0x7df
	v_bitop3_b32 v96, v172, s18, 16 bitop3:0xc8
	s_movk_i32 s18, 0x4000
	v_cmp_gt_i32_e32 vcc, s18, v114
	s_movk_i32 s18, 0x77f
	v_cmp_lt_u32_e64 s[18:19], s18, v96
	v_cndmask_b32_e32 v116, v151, v96, vcc
	v_add_u32_e32 v96, 0xfffff880, v96
	v_ashrrev_i32_e32 v115, 31, v114
	v_lshlrev_b32_e32 v176, 3, v116
	v_add_u32_e32 v116, 0xffffc010, v172
	v_lshlrev_b64 v[126:127], 7, v[96:97]
	s_mov_b64 s[70:71], 0x1080000
	v_lshlrev_b64 v[120:121], 8, v[114:115]
	v_lshrrev_b32_e32 v173, 2, v116
	v_lshl_add_u64 v[128:129], v[126:127], 0, s[70:71]
	v_lshlrev_b32_e32 v96, 2, v176
	global_load_dwordx4 v[208:211], v96, s[44:45]
	global_load_dwordx4 v[212:215], v96, s[4:5]
	global_load_dwordx4 v[216:219], v96, s[44:45] offset:16
	global_load_dwordx4 v[220:223], v96, s[4:5] offset:16
	v_mov_b32_e32 v96, v110
	v_mov_b32_e32 v131, v110
	s_nop 1
	v_permlane16_swap_b32_e32 v96, v131
	v_cndmask_b32_e64 v96, v96, v131, s[6:7]
	v_cndmask_b32_e64 v133, v96, -v96, s[10:11]
	v_mov_b32_e32 v146, v110
	v_mov_b32_e32 v131, v111
	s_waitcnt vmcnt(2)
; __device__ __forceinline__ float shx16(float v, int odd  ) { const unsigned x = __builtin_bit_cast(unsigned, v); auto r = __builtin_amdgcn_permlane16_swap(x, x, false, false); return __builtin_bit_cast(float, odd ? r[0] : r[1]); }
; __device__ __forceinline__ void st_bf4(bf16_t* p, const f32x4 v) { u32x2 w; w.x = cvt_pk_bf16(v[0], v[1]); w.y = cvt_pk_bf16(v[2], v[3]); *(u32x2*)p = w; }
;     __device__ __forceinline__ void operator()(const f32x4 (&acc)[2][2][4][2], const Unit& u, int wr, int wc, int fr, int fq) const {
;     ...
;             for (int m = 0; m < 4; ++m) { const int row = u.pm * 256 + ai * 128 + wr * 64 + m * 16 + fr;
; #pragma unroll
;                 for (int bj = 0; bj < 2; ++bj)
; #pragma unroll
;                     for (int n = 0; n < 2; ++n) { const int tc = bj * 128 + wc * 32 + 8 * fq + 4 * n; f32x4 v = acc[ai][bj][m][n];
;                         if (pn < 2) { *(f32x4*)(XA + (size_t)row * 512 + pn * 256 + tc) = v; }
;                         else if (pn <= 4) {
;                             const bool isv = (pn == 4 && bj == 1);
;                             if (!isv && (wc & 1) == 0) {
;                                 const int tix = row < cfg::MP ? (row & 2047) : 2048 + (row & 3);
;                                 const f32x4 cs = *(const f32x4*)(ropec + tix * 8 + 4 * n), sn = *(const f32x4*)(ropes + tix * 8 + 4 * n);
; #pragma unroll
;                                 for (int i = 0; i < 4; ++i) { const float p = shx16(v[i], fq & 1); const float rv = v[i] * cs[i] + (fq == 0 ? -p : p) * sn[i]; v[i] = fq < 2 ? rv : v[i]; }
;                             }
;                             if (pn < 4) st_bf4(Q + (size_t)row * 512 + (pn - 2) * 256 + tc, v);
;                             else { st_bf4((bj == 0 ? KB : VB) + (size_t)row * 128 + (tc & 127), v);
;                                 bool w = false; size_t o = 0;
;                                 if (row < cfg::MP) { const int t = row & 2047; if (t >= 1920) { w = true; o = (bj == 0 ? cfg::OFF_KP : cfg::OFF_VP) + ((size_t)(layer * 8 + (row >> 11)) * 128 + (t - 1920)) * 128 + (tc & 127); } }
;                                 else { const int rs = row - cfg::MP; w = true; o = (bj == 0 ? cfg::OFF_KS : cfg::OFF_VS) + ((size_t)(layer * 128 + (rs >> 2)) * 128 + 124 + (rs & 3)) * 128 + (tc & 127); }
;                                 if (w) *(f32x4*)(out + o) = v; }
	v_mov_b32_e32 v132, v208
	v_mov_b32_e32 v147, v212
	v_pk_mul_f32 v[132:133], v[146:147], v[132:133]
	v_mov_b32_e32 v178, v111
	v_add_f32_e32 v96, v132, v133
	v_cndmask_b32_e64 v114, v110, v96, s[8:9]
	v_mov_b32_e32 v96, v111
	s_nop 1
	v_permlane16_swap_b32_e32 v96, v131
	v_cndmask_b32_e64 v96, v96, v131, s[6:7]
	v_cndmask_b32_e64 v133, v96, -v96, s[10:11]
	v_mov_b32_e32 v132, v209
	v_mov_b32_e32 v179, v213
	v_pk_mul_f32 v[132:133], v[178:179], v[132:133]
	v_mov_b32_e32 v131, v112
	v_add_f32_e32 v96, v132, v133
	v_cndmask_b32_e64 v115, v111, v96, s[8:9]
	v_mov_b32_e32 v96, v112
	s_nop 1
	v_permlane16_swap_b32_e32 v96, v131
	v_cndmask_b32_e64 v96, v96, v131, s[6:7]
	v_cndmask_b32_e64 v133, v96, -v96, s[10:11]
	v_mov_b32_e32 v146, v112
	v_mov_b32_e32 v147, v214
	v_mov_b32_e32 v132, v210
	v_pk_mul_f32 v[132:133], v[146:147], v[132:133]
	v_mov_b32_e32 v131, v113
	v_add_f32_e32 v96, v132, v133
	v_cndmask_b32_e64 v116, v112, v96, s[8:9]
	v_mov_b32_e32 v96, v113
	s_nop 1
	v_permlane16_swap_b32_e32 v96, v131
	v_cndmask_b32_e64 v96, v96, v131, s[6:7]
	v_cndmask_b32_e64 v133, v96, -v96, s[10:11]
	v_mov_b32_e32 v180, v113
	v_mov_b32_e32 v132, v211
	v_mov_b32_e32 v181, v215
	v_pk_mul_f32 v[132:133], v[180:181], v[132:133]
	v_mov_b32_e32 v131, v114
	v_add_f32_e32 v96, v132, v133
	v_cndmask_b32_e64 v117, v113, v96, s[8:9]
	v_mov_b32_e32 v178, v115
	v_mov_b32_e32 v177, v116
	v_mov_b32_e32 v179, v117
	v_lshl_add_u64 v[132:133], v[154:155], 0, v[120:121]
	v_cvt_pk_bf16_f32 v146, v131, v178
	v_cvt_pk_bf16_f32 v147, v177, v179
	global_store_dwordx2 v[132:133], v[146:147], off
	s_and_saveexec_b64 s[78:79], s[20:21]
	s_xor_b64 s[78:79], exec, s[78:79]
	s_mov_b64 s[70:71], exec
	v_add_u32_e32 v132, s87, v173
	s_or_saveexec_b64 s[78:79], s[78:79]
	v_mov_b64_e32 v[174:175], v[160:161]
	s_xor_b64 exec, exec, s[78:79]
	s_and_saveexec_b64 vcc, s[18:19]
	v_readlane_b32 s80, v254, 37
	v_readlane_b32 s81, v254, 38
	s_add_i32 s46, s75, s80
	s_or_b64 s[80:81], s[70:71], exec
	s_or_b64 exec, exec, vcc
	s_andn2_b64 s[70:71], s[70:71], exec
	s_and_b64 s[80:81], s[80:81], exec
	v_mov_b32_e32 v132, s46
	s_or_b64 s[70:71], s[70:71], s[80:81]
	v_mov_b64_e32 v[174:175], v[128:129]
	v_readlane_b32 s86, v254, 63
	v_readlane_b32 s87, v255, 0
	s_or_b64 exec, exec, s[78:79]
	s_and_saveexec_b64 s[78:79], s[70:71]
	v_ashrrev_i32_e32 v133, 31, v132
	v_lshl_add_u64 v[146:147], v[174:175], 2, v[156:157]
	v_lshlrev_b64 v[132:133], 16, v[132:133]
	v_lshl_add_u64 v[132:133], v[146:147], 0, v[132:133]
	global_store_dwordx4 v[132:133], v[114:117], off
	s_or_b64 exec, exec, s[78:79]
	v_lshlrev_b32_e32 v96, 2, v176
	v_mov_b32_e32 v96, v106
	v_mov_b32_e32 v116, v106
	s_nop 1
	v_permlane16_swap_b32_e32 v96, v116
	v_cndmask_b32_e64 v96, v96, v116, s[6:7]
	v_cndmask_b32_e64 v117, v96, -v96, s[10:11]
	v_mov_b32_e32 v132, v106
	s_waitcnt vmcnt(1)
	v_mov_b32_e32 v116, v216
	v_mov_b32_e32 v133, v220
	v_pk_mul_f32 v[116:117], v[132:133], v[116:117]
	v_mov_b32_e32 v178, v107
	v_add_f32_e32 v96, v116, v117
	v_cndmask_b32_e64 v110, v106, v96, s[8:9]
	v_mov_b32_e32 v96, v107
	v_mov_b32_e32 v116, v107
	s_nop 1
	v_permlane16_swap_b32_e32 v96, v116
	v_cndmask_b32_e64 v96, v96, v116, s[6:7]
	v_cndmask_b32_e64 v117, v96, -v96, s[10:11]
	v_mov_b32_e32 v116, v217
	v_mov_b32_e32 v179, v221
	v_pk_mul_f32 v[116:117], v[178:179], v[116:117]
	v_mov_b32_e32 v132, v108
	v_add_f32_e32 v96, v116, v117
	v_cndmask_b32_e64 v111, v107, v96, s[8:9]
	v_mov_b32_e32 v96, v108
	v_mov_b32_e32 v116, v108
	s_nop 1
	v_permlane16_swap_b32_e32 v96, v116
	v_cndmask_b32_e64 v96, v96, v116, s[6:7]
	v_cndmask_b32_e64 v117, v96, -v96, s[10:11]
	v_mov_b32_e32 v133, v222
	v_mov_b32_e32 v116, v218
	v_pk_mul_f32 v[116:117], v[132:133], v[116:117]
	v_mov_b32_e32 v180, v109
	v_add_f32_e32 v96, v116, v117
	v_cndmask_b32_e64 v112, v108, v96, s[8:9]
	v_mov_b32_e32 v96, v109
	v_mov_b32_e32 v116, v109
	s_nop 1
	v_permlane16_swap_b32_e32 v96, v116
	v_cndmask_b32_e64 v96, v96, v116, s[6:7]
	v_cndmask_b32_e64 v117, v96, -v96, s[10:11]
	v_mov_b32_e32 v116, v219
	v_mov_b32_e32 v181, v223
	v_pk_mul_f32 v[116:117], v[180:181], v[116:117]
	v_mov_b32_e32 v131, v110
	v_add_f32_e32 v96, v116, v117
	v_cndmask_b32_e64 v113, v109, v96, s[8:9]
	v_mov_b32_e32 v175, v111
	v_mov_b32_e32 v174, v112
	v_mov_b32_e32 v177, v113
	v_lshl_add_u64 v[116:117], v[164:165], 0, v[120:121]
	v_cvt_pk_bf16_f32 v132, v131, v175
	v_cvt_pk_bf16_f32 v133, v174, v177
	global_store_dwordx2 v[116:117], v[132:133], off
	s_and_saveexec_b64 s[78:79], s[20:21]
	s_xor_b64 s[78:79], exec, s[78:79]
	s_mov_b64 s[70:71], exec
	v_add_u32_e32 v116, s87, v173
	s_or_saveexec_b64 s[78:79], s[78:79]
	v_mov_b64_e32 v[132:133], v[160:161]
	s_xor_b64 exec, exec, s[78:79]
	s_and_saveexec_b64 vcc, s[18:19]
	v_readlane_b32 s80, v254, 37
	v_readlane_b32 s81, v254, 38
	s_add_i32 s46, s75, s80
	s_or_b64 s[80:81], s[70:71], exec
	s_or_b64 exec, exec, vcc
	s_andn2_b64 s[70:71], s[70:71], exec
	s_and_b64 s[80:81], s[80:81], exec
	v_mov_b32_e32 v116, s46
	s_or_b64 s[70:71], s[70:71], s[80:81]
	v_mov_b64_e32 v[132:133], v[128:129]
	v_readlane_b32 s86, v254, 63
	v_readlane_b32 s87, v255, 0
	s_or_b64 exec, exec, s[78:79]
	s_and_saveexec_b64 s[78:79], s[70:71]
	v_ashrrev_i32_e32 v117, 31, v116
	v_lshl_add_u64 v[128:129], v[132:133], 2, v[156:157]
	v_lshlrev_b64 v[116:117], 16, v[116:117]
	v_lshl_add_u64 v[116:117], v[128:129], 0, v[116:117]
	global_store_dwordx4 v[116:117], v[110:113], off offset:16
	s_or_b64 exec, exec, s[78:79]
	s_mov_b64 s[70:71], 0x1100000
	v_lshl_add_u64 v[110:111], v[126:127], 0, s[70:71]
	v_mov_b64_e32 v[108:109], v[104:105]
	v_mov_b64_e32 v[106:107], v[102:103]
	v_mov_b32_e32 v126, v102
; __device__ __forceinline__ float shx16(float v, int odd  ) { const unsigned x = __builtin_bit_cast(unsigned, v); auto r = __builtin_amdgcn_permlane16_swap(x, x, false, false); return __builtin_bit_cast(float, odd ? r[0] : r[1]); }
; __device__ __forceinline__ void st_bf4(bf16_t* p, const f32x4 v) { u32x2 w; w.x = cvt_pk_bf16(v[0], v[1]); w.y = cvt_pk_bf16(v[2], v[3]); *(u32x2*)p = w; }
;     __device__ __forceinline__ void operator()(const f32x4 (&acc)[2][2][4][2], const Unit& u, int wr, int wc, int fr, int fq) const {
;     ...
;             for (int m = 0; m < 4; ++m) { const int row = u.pm * 256 + ai * 128 + wr * 64 + m * 16 + fr;
; #pragma unroll
;                 for (int bj = 0; bj < 2; ++bj)
; #pragma unroll
;                     for (int n = 0; n < 2; ++n) { const int tc = bj * 128 + wc * 32 + 8 * fq + 4 * n; f32x4 v = acc[ai][bj][m][n];
;                         if (pn < 2) { *(f32x4*)(XA + (size_t)row * 512 + pn * 256 + tc) = v; }
;                         else if (pn <= 4) {
;                             const bool isv = (pn == 4 && bj == 1);
;                             if (!isv && (wc & 1) == 0) {
;                                 const int tix = row < cfg::MP ? (row & 2047) : 2048 + (row & 3);
;                                 const f32x4 cs = *(const f32x4*)(ropec + tix * 8 + 4 * n), sn = *(const f32x4*)(ropes + tix * 8 + 4 * n);
; #pragma unroll
;                                 for (int i = 0; i < 4; ++i) { const float p = shx16(v[i], fq & 1); const float rv = v[i] * cs[i] + (fq == 0 ? -p : p) * sn[i]; v[i] = fq < 2 ? rv : v[i]; }
;                             }
;                             if (pn < 4) st_bf4(Q + (size_t)row * 512 + (pn - 2) * 256 + tc, v);
;                             else { st_bf4((bj == 0 ? KB : VB) + (size_t)row * 128 + (tc & 127), v);
;                                 bool w = false; size_t o = 0;
;                                 if (row < cfg::MP) { const int t = row & 2047; if (t >= 1920) { w = true; o = (bj == 0 ? cfg::OFF_KP : cfg::OFF_VP) + ((size_t)(layer * 8 + (row >> 11)) * 128 + (t - 1920)) * 128 + (tc & 127); } }
;                                 else { const int rs = row - cfg::MP; w = true; o = (bj == 0 ? cfg::OFF_KS : cfg::OFF_VS) + ((size_t)(layer * 128 + (rs >> 2)) * 128 + 124 + (rs & 3)) * 128 + (tc & 127); }
;                                 if (w) *(f32x4*)(out + o) = v; }
	v_mov_b32_e32 v128, v103
	v_mov_b32_e32 v127, v104
	v_mov_b32_e32 v129, v105
	v_lshl_add_u64 v[112:113], v[158:159], 0, v[120:121]
	v_cvt_pk_bf16_f32 v116, v126, v128
	v_cvt_pk_bf16_f32 v117, v127, v129
	global_store_dwordx2 v[112:113], v[116:117], off
	s_and_saveexec_b64 s[78:79], s[20:21]
	s_xor_b64 s[78:79], exec, s[78:79]
	s_mov_b64 s[70:71], exec
	v_add_u32_e32 v112, s87, v173
	s_or_saveexec_b64 s[78:79], s[78:79]
	v_mov_b64_e32 v[116:117], v[162:163]
	s_xor_b64 exec, exec, s[78:79]
	s_and_saveexec_b64 vcc, s[18:19]
	v_readlane_b32 s80, v254, 37
	v_readlane_b32 s81, v254, 38
	s_add_i32 s46, s75, s80
	s_or_b64 s[80:81], s[70:71], exec
	s_or_b64 exec, exec, vcc
	s_andn2_b64 s[70:71], s[70:71], exec
	s_and_b64 s[80:81], s[80:81], exec
	v_mov_b32_e32 v112, s46
	s_or_b64 s[70:71], s[70:71], s[80:81]
	v_mov_b64_e32 v[116:117], v[110:111]
	v_readlane_b32 s86, v254, 63
	v_readlane_b32 s87, v255, 0
	s_or_b64 exec, exec, s[78:79]
	s_and_saveexec_b64 s[78:79], s[70:71]
	v_ashrrev_i32_e32 v113, 31, v112
	v_lshl_add_u64 v[116:117], v[116:117], 2, v[156:157]
	v_lshlrev_b64 v[112:113], 16, v[112:113]
	v_lshl_add_u64 v[112:113], v[116:117], 0, v[112:113]
	global_store_dwordx4 v[112:113], v[106:109], off
	s_or_b64 exec, exec, s[78:79]
	v_mov_b64_e32 v[104:105], v[100:101]
	v_mov_b64_e32 v[102:103], v[98:99]
	v_mov_b32_e32 v112, v98
	v_mov_b32_e32 v116, v99
	v_mov_b32_e32 v113, v100
	v_mov_b32_e32 v117, v101
	s_andn2_b64 vcc, exec, s[96:97]
	v_lshl_add_u64 v[106:107], v[166:167], 0, v[120:121]
	v_cvt_pk_bf16_f32 v108, v112, v116
	v_cvt_pk_bf16_f32 v109, v113, v117
	global_store_dwordx2 v[106:107], v[108:109], off
	s_and_saveexec_b64 s[78:79], s[20:21]
	s_xor_b64 s[20:21], exec, s[78:79]
	s_mov_b64 s[70:71], exec
	v_add_u32_e32 v106, s87, v173
	s_or_saveexec_b64 s[20:21], s[20:21]
	v_mov_b64_e32 v[108:109], v[162:163]
	s_xor_b64 exec, exec, s[20:21]
	s_and_saveexec_b64 s[80:81], s[18:19]
	v_readlane_b32 s18, v254, 37
	s_add_i32 s46, s75, s18
	s_or_b64 s[78:79], s[70:71], exec
	v_readlane_b32 s19, v254, 38
	s_or_b64 exec, exec, s[80:81]
	s_andn2_b64 s[18:19], s[70:71], exec
	s_and_b64 s[70:71], s[78:79], exec
	v_mov_b32_e32 v106, s46
	s_or_b64 s[70:71], s[18:19], s[70:71]
	v_mov_b64_e32 v[108:109], v[110:111]
	s_or_b64 exec, exec, s[20:21]
	s_and_saveexec_b64 s[18:19], s[70:71]
	v_ashrrev_i32_e32 v107, 31, v106
	v_lshl_add_u64 v[108:109], v[108:109], 2, v[156:157]
	v_lshlrev_b64 v[106:107], 16, v[106:107]
	v_lshl_add_u64 v[106:107], v[108:109], 0, v[106:107]
	global_store_dwordx4 v[106:107], v[102:105], off offset:16
	s_or_b64 exec, exec, s[18:19]
	v_or_b32_e32 v98, 32, v172
	v_mad_i64_i32 v[108:109], s[18:19], v98, s61, 0
	s_movk_i32 s18, 0x3fff
	s_nop 0
	v_cmp_lt_i32_e64 s[20:21], s18, v98
	s_movk_i32 s18, 0x7ef
	v_bitop3_b32 v96, v172, s18, 32 bitop3:0xc8
	s_movk_i32 s18, 0x4000
	v_cmp_gt_i32_e32 vcc, s18, v98
	s_movk_i32 s18, 0x77f
	v_cmp_lt_u32_e64 s[18:19], s18, v96
	v_cndmask_b32_e32 v100, v151, v96, vcc
	v_add_u32_e32 v96, 0xfffff880, v96
	v_ashrrev_i32_e32 v99, 31, v98
	v_lshlrev_b32_e32 v119, 3, v100
	v_add_u32_e32 v100, 0xffffc020, v172
	v_lshlrev_b64 v[110:111], 7, v[96:97]
	s_mov_b64 s[70:71], 0x1080000
	v_lshlrev_b64 v[104:105], 8, v[98:99]
	v_lshrrev_b32_e32 v118, 2, v100
	v_lshl_add_u64 v[112:113], v[110:111], 0, s[70:71]
	v_lshlrev_b32_e32 v96, 2, v119
	global_load_dwordx4 v[208:211], v96, s[44:45]
	global_load_dwordx4 v[212:215], v96, s[4:5]
	global_load_dwordx4 v[216:219], v96, s[44:45] offset:16
	global_load_dwordx4 v[220:223], v96, s[4:5] offset:16
	v_mov_b32_e32 v96, v92
	v_mov_b32_e32 v120, v92
	s_nop 1
	v_permlane16_swap_b32_e32 v96, v120
	v_cndmask_b32_e64 v96, v96, v120, s[6:7]
	v_cndmask_b32_e64 v121, v96, -v96, s[10:11]
	v_mov_b32_e32 v122, v92
	s_waitcnt vmcnt(2)
	v_mov_b32_e32 v120, v208
	v_mov_b32_e32 v123, v212
	v_pk_mul_f32 v[120:121], v[122:123], v[120:121]
	v_mov_b32_e32 v114, v93
	v_add_f32_e32 v96, v120, v121
	v_cndmask_b32_e64 v98, v92, v96, s[8:9]
	v_mov_b32_e32 v96, v93
	s_nop 1
	v_permlane16_swap_b32_e32 v96, v114
	v_cndmask_b32_e64 v96, v96, v114, s[6:7]
	v_cndmask_b32_e64 v121, v96, -v96, s[10:11]
	v_mov_b32_e32 v114, v93
	v_mov_b32_e32 v120, v209
	v_mov_b32_e32 v115, v213
	v_pk_mul_f32 v[114:115], v[114:115], v[120:121]
	v_mov_b32_e32 v120, v94
	v_add_f32_e32 v96, v114, v115
	v_cndmask_b32_e64 v99, v93, v96, s[8:9]
	v_mov_b32_e32 v96, v94
	v_mov_b32_e32 v114, v94
	s_nop 1
	v_permlane16_swap_b32_e32 v96, v114
	v_cndmask_b32_e64 v96, v96, v114, s[6:7]
	v_cndmask_b32_e64 v115, v96, -v96, s[10:11]
	v_mov_b32_e32 v121, v214
	v_mov_b32_e32 v114, v210
	v_pk_mul_f32 v[114:115], v[120:121], v[114:115]
	v_mov_b32_e32 v116, v95
	v_add_f32_e32 v96, v114, v115
	v_cndmask_b32_e64 v100, v94, v96, s[8:9]
	v_mov_b32_e32 v96, v95
	v_mov_b32_e32 v114, v95
	s_nop 1
	v_permlane16_swap_b32_e32 v96, v114
	v_cndmask_b32_e64 v96, v96, v114, s[6:7]
	v_cndmask_b32_e64 v115, v96, -v96, s[10:11]
	v_mov_b32_e32 v114, v211
	v_mov_b32_e32 v117, v215
	v_pk_mul_f32 v[114:115], v[116:117], v[114:115]
	v_mov_b32_e32 v120, v98
	v_add_f32_e32 v96, v114, v115
	v_cndmask_b32_e64 v101, v95, v96, s[8:9]
	v_mov_b32_e32 v122, v99
	v_mov_b32_e32 v121, v100
	v_mov_b32_e32 v123, v101
	v_lshl_add_u64 v[114:115], v[154:155], 0, v[104:105]
	v_cvt_pk_bf16_f32 v116, v120, v122
	v_cvt_pk_bf16_f32 v117, v121, v123
	global_store_dwordx2 v[114:115], v[116:117], off
	s_and_saveexec_b64 s[78:79], s[20:21]
	s_xor_b64 s[78:79], exec, s[78:79]
	s_mov_b64 s[70:71], exec
	v_add_u32_e32 v114, s87, v118
	s_or_saveexec_b64 s[78:79], s[78:79]
	v_mov_b64_e32 v[116:117], v[160:161]
	s_xor_b64 exec, exec, s[78:79]
	s_and_saveexec_b64 vcc, s[18:19]
	v_readlane_b32 s80, v254, 37
	v_readlane_b32 s81, v254, 38
	s_add_i32 s46, s75, s80
	s_or_b64 s[80:81], s[70:71], exec
	s_or_b64 exec, exec, vcc
	s_andn2_b64 s[70:71], s[70:71], exec
	s_and_b64 s[80:81], s[80:81], exec
	v_mov_b32_e32 v114, s46
	s_or_b64 s[70:71], s[70:71], s[80:81]
	v_mov_b64_e32 v[116:117], v[112:113]
	v_readlane_b32 s86, v254, 63
	v_readlane_b32 s87, v255, 0
	s_or_b64 exec, exec, s[78:79]
	s_and_saveexec_b64 s[78:79], s[70:71]
	v_ashrrev_i32_e32 v115, 31, v114
	v_lshl_add_u64 v[116:117], v[116:117], 2, v[156:157]
	v_lshlrev_b64 v[114:115], 16, v[114:115]
	v_lshl_add_u64 v[114:115], v[116:117], 0, v[114:115]
	global_store_dwordx4 v[114:115], v[98:101], off
	s_or_b64 exec, exec, s[78:79]
	v_lshlrev_b32_e32 v96, 2, v119
	v_mov_b32_e32 v96, v88
	v_mov_b32_e32 v100, v88
	s_nop 1
	v_permlane16_swap_b32_e32 v96, v100
	v_cndmask_b32_e64 v96, v96, v100, s[6:7]
	v_cndmask_b32_e64 v101, v96, -v96, s[10:11]
	v_mov_b32_e32 v120, v88
	v_mov_b32_e32 v96, v89
	s_waitcnt vmcnt(1)
; __device__ __forceinline__ float shx16(float v, int odd  ) { const unsigned x = __builtin_bit_cast(unsigned, v); auto r = __builtin_amdgcn_permlane16_swap(x, x, false, false); return __builtin_bit_cast(float, odd ? r[0] : r[1]); }
; __device__ __forceinline__ void st_bf4(bf16_t* p, const f32x4 v) { u32x2 w; w.x = cvt_pk_bf16(v[0], v[1]); w.y = cvt_pk_bf16(v[2], v[3]); *(u32x2*)p = w; }
;     __device__ __forceinline__ void operator()(const f32x4 (&acc)[2][2][4][2], const Unit& u, int wr, int wc, int fr, int fq) const {
;     ...
;                     for (int n = 0; n < 2; ++n) { const int tc = bj * 128 + wc * 32 + 8 * fq + 4 * n; f32x4 v = acc[ai][bj][m][n];
;                         if (pn < 2) { *(f32x4*)(XA + (size_t)row * 512 + pn * 256 + tc) = v; }
;                         else if (pn <= 4) {
;                             const bool isv = (pn == 4 && bj == 1);
;                             if (!isv && (wc & 1) == 0) {
;                                 const int tix = row < cfg::MP ? (row & 2047) : 2048 + (row & 3);
;                                 const f32x4 cs = *(const f32x4*)(ropec + tix * 8 + 4 * n), sn = *(const f32x4*)(ropes + tix * 8 + 4 * n);
; #pragma unroll
;                                 for (int i = 0; i < 4; ++i) { const float p = shx16(v[i], fq & 1); const float rv = v[i] * cs[i] + (fq == 0 ? -p : p) * sn[i]; v[i] = fq < 2 ? rv : v[i]; }
;                             }
;                             if (pn < 4) st_bf4(Q + (size_t)row * 512 + (pn - 2) * 256 + tc, v);
;                             else { st_bf4((bj == 0 ? KB : VB) + (size_t)row * 128 + (tc & 127), v);
;                                 bool w = false; size_t o = 0;
;                                 if (row < cfg::MP) { const int t = row & 2047; if (t >= 1920) { w = true; o = (bj == 0 ? cfg::OFF_KP : cfg::OFF_VP) + ((size_t)(layer * 8 + (row >> 11)) * 128 + (t - 1920)) * 128 + (tc & 127); } }
;                                 else { const int rs = row - cfg::MP; w = true; o = (bj == 0 ? cfg::OFF_KS : cfg::OFF_VS) + ((size_t)(layer * 128 + (rs >> 2)) * 128 + 124 + (rs & 3)) * 128 + (tc & 127); }
;                                 if (w) *(f32x4*)(out + o) = v; }
	v_mov_b32_e32 v100, v216
	v_mov_b32_e32 v121, v220
	v_pk_mul_f32 v[100:101], v[120:121], v[100:101]
	v_mov_b32_e32 v114, v89
	v_add_f32_e32 v92, v100, v101
	v_mov_b32_e32 v100, v89
	s_nop 1
	v_permlane16_swap_b32_e32 v96, v100
	v_cndmask_b32_e64 v96, v96, v100, s[6:7]
	v_cndmask_b32_e64 v101, v96, -v96, s[10:11]
	v_mov_b32_e32 v100, v217
	v_mov_b32_e32 v115, v221
	v_pk_mul_f32 v[100:101], v[114:115], v[100:101]
	v_mov_b32_e32 v96, v90
	v_add_f32_e32 v93, v100, v101
	v_mov_b32_e32 v100, v90
	s_nop 1
	v_permlane16_swap_b32_e32 v96, v100
	v_cndmask_b32_e64 v96, v96, v100, s[6:7]
	v_cndmask_b32_e64 v101, v96, -v96, s[10:11]
	v_mov_b32_e32 v114, v90
	v_mov_b32_e32 v115, v222
	v_mov_b32_e32 v100, v218
	v_pk_mul_f32 v[100:101], v[114:115], v[100:101]
	v_mov_b32_e32 v96, v91
	v_add_f32_e32 v94, v100, v101
	v_mov_b32_e32 v100, v91
	s_nop 1
	v_permlane16_swap_b32_e32 v96, v100
	v_cndmask_b32_e64 v96, v96, v100, s[6:7]
	v_cndmask_b32_e64 v101, v96, -v96, s[10:11]
	v_mov_b32_e32 v116, v91
	v_mov_b32_e32 v100, v219
	v_mov_b32_e32 v117, v223
	v_pk_mul_f32 v[100:101], v[116:117], v[100:101]
	v_cndmask_b32_e64 v92, v88, v92, s[8:9]
	v_add_f32_e32 v95, v100, v101
	v_cndmask_b32_e64 v93, v89, v93, s[8:9]
	v_cndmask_b32_e64 v94, v90, v94, s[8:9]
	v_cndmask_b32_e64 v95, v91, v95, s[8:9]
	v_mov_b32_e32 v116, v92
	v_mov_b32_e32 v120, v93
	v_mov_b32_e32 v117, v94
	v_mov_b32_e32 v121, v95
	v_lshl_add_u64 v[100:101], v[164:165], 0, v[104:105]
	v_cvt_pk_bf16_f32 v114, v116, v120
	v_cvt_pk_bf16_f32 v115, v117, v121
	global_store_dwordx2 v[100:101], v[114:115], off
	s_and_saveexec_b64 s[78:79], s[20:21]
	s_xor_b64 s[78:79], exec, s[78:79]
	s_mov_b64 s[70:71], exec
	v_add_u32_e32 v100, s87, v118
	s_or_saveexec_b64 s[78:79], s[78:79]
	v_mov_b64_e32 v[114:115], v[160:161]
	s_xor_b64 exec, exec, s[78:79]
	s_and_saveexec_b64 vcc, s[18:19]
	v_readlane_b32 s80, v254, 37
	v_readlane_b32 s81, v254, 38
	s_add_i32 s46, s75, s80
	s_or_b64 s[80:81], s[70:71], exec
	s_or_b64 exec, exec, vcc
	s_andn2_b64 s[70:71], s[70:71], exec
	s_and_b64 s[80:81], s[80:81], exec
	v_mov_b32_e32 v100, s46
	s_or_b64 s[70:71], s[70:71], s[80:81]
	v_mov_b64_e32 v[114:115], v[112:113]
	v_readlane_b32 s86, v254, 63
	v_readlane_b32 s87, v255, 0
	s_or_b64 exec, exec, s[78:79]
	s_and_saveexec_b64 s[78:79], s[70:71]
	v_ashrrev_i32_e32 v101, 31, v100
	v_lshl_add_u64 v[112:113], v[114:115], 2, v[156:157]
	v_lshlrev_b64 v[100:101], 16, v[100:101]
	v_lshl_add_u64 v[100:101], v[112:113], 0, v[100:101]
	global_store_dwordx4 v[100:101], v[92:95], off offset:16
	s_or_b64 exec, exec, s[78:79]
	s_mov_b64 s[70:71], 0x1100000
	v_lshl_add_u64 v[92:93], v[110:111], 0, s[70:71]
	v_mov_b64_e32 v[90:91], v[86:87]
	v_mov_b64_e32 v[88:89], v[84:85]
	v_mov_b32_e32 v110, v84
	v_mov_b32_e32 v112, v85
	v_mov_b32_e32 v111, v86
	v_mov_b32_e32 v113, v87
	v_lshl_add_u64 v[94:95], v[158:159], 0, v[104:105]
	v_cvt_pk_bf16_f32 v100, v110, v112
	v_cvt_pk_bf16_f32 v101, v111, v113
	global_store_dwordx2 v[94:95], v[100:101], off
	s_and_saveexec_b64 s[78:79], s[20:21]
	s_xor_b64 s[78:79], exec, s[78:79]
	s_mov_b64 s[70:71], exec
	v_add_u32_e32 v94, s87, v118
	s_or_saveexec_b64 s[78:79], s[78:79]
	v_mov_b64_e32 v[100:101], v[162:163]
	s_xor_b64 exec, exec, s[78:79]
	s_and_saveexec_b64 vcc, s[18:19]
	v_readlane_b32 s80, v254, 37
	v_readlane_b32 s81, v254, 38
	s_add_i32 s46, s75, s80
	s_or_b64 s[80:81], s[70:71], exec
	s_or_b64 exec, exec, vcc
	s_andn2_b64 s[70:71], s[70:71], exec
	s_and_b64 s[80:81], s[80:81], exec
	v_mov_b32_e32 v94, s46
	s_or_b64 s[70:71], s[70:71], s[80:81]
	v_mov_b64_e32 v[100:101], v[92:93]
	v_readlane_b32 s86, v254, 63
	v_readlane_b32 s87, v255, 0
	s_or_b64 exec, exec, s[78:79]
	s_and_saveexec_b64 s[78:79], s[70:71]
	v_ashrrev_i32_e32 v95, 31, v94
	v_lshl_add_u64 v[100:101], v[100:101], 2, v[156:157]
	v_lshlrev_b64 v[94:95], 16, v[94:95]
	v_lshl_add_u64 v[94:95], v[100:101], 0, v[94:95]
	global_store_dwordx4 v[94:95], v[88:91], off
	s_or_b64 exec, exec, s[78:79]
	v_mov_b64_e32 v[86:87], v[82:83]
	v_mov_b64_e32 v[84:85], v[80:81]
	v_mov_b32_e32 v94, v80
	v_mov_b32_e32 v100, v81
	v_mov_b32_e32 v95, v82
	v_mov_b32_e32 v101, v83
	s_andn2_b64 vcc, exec, s[96:97]
	v_lshl_add_u64 v[88:89], v[166:167], 0, v[104:105]
	v_cvt_pk_bf16_f32 v90, v94, v100
	v_cvt_pk_bf16_f32 v91, v95, v101
	global_store_dwordx2 v[88:89], v[90:91], off
	s_and_saveexec_b64 s[78:79], s[20:21]
	s_xor_b64 s[20:21], exec, s[78:79]
	s_mov_b64 s[70:71], exec
	v_add_u32_e32 v88, s87, v118
	s_or_saveexec_b64 s[20:21], s[20:21]
	v_mov_b64_e32 v[90:91], v[162:163]
	s_xor_b64 exec, exec, s[20:21]
	s_and_saveexec_b64 s[80:81], s[18:19]
	v_readlane_b32 s18, v254, 37
	s_add_i32 s46, s75, s18
	s_or_b64 s[78:79], s[70:71], exec
	v_readlane_b32 s19, v254, 38
	s_or_b64 exec, exec, s[80:81]
	s_andn2_b64 s[18:19], s[70:71], exec
	s_and_b64 s[70:71], s[78:79], exec
	v_mov_b32_e32 v88, s46
	s_or_b64 s[70:71], s[18:19], s[70:71]
	v_mov_b64_e32 v[90:91], v[92:93]
	s_or_b64 exec, exec, s[20:21]
	s_and_saveexec_b64 s[18:19], s[70:71]
	v_ashrrev_i32_e32 v89, 31, v88
	v_lshl_add_u64 v[90:91], v[90:91], 2, v[156:157]
	v_lshlrev_b64 v[88:89], 16, v[88:89]
	v_lshl_add_u64 v[88:89], v[90:91], 0, v[88:89]
	global_store_dwordx4 v[88:89], v[84:87], off offset:16
	s_or_b64 exec, exec, s[18:19]
	v_or_b32_e32 v80, 48, v172
	s_movk_i32 s18, 0x3fff
	v_cmp_lt_i32_e64 s[20:21], s18, v80
	s_movk_i32 s18, 0x7ff
	v_bitop3_b32 v82, v172, s18, 48 bitop3:0xc8
	s_movk_i32 s18, 0x4000
	v_cmp_gt_i32_e32 vcc, s18, v80
	v_add_u32_e32 v96, 0xfffff880, v82
	v_ashrrev_i32_e32 v81, 31, v80
	v_cndmask_b32_e32 v83, v151, v82, vcc
	v_lshlrev_b32_e32 v103, 3, v83
	v_add_u32_e32 v83, 0xffffc030, v172
	s_movk_i32 s18, 0x77f
	v_lshlrev_b64 v[92:93], 7, v[96:97]
	s_mov_b64 s[70:71], 0x1080000
	v_lshlrev_b64 v[86:87], 8, v[80:81]
	v_lshrrev_b32_e32 v102, 2, v83
	v_cmp_lt_u32_e64 s[18:19], s18, v82
	v_lshl_add_u64 v[94:95], v[92:93], 0, s[70:71]
	v_lshlrev_b32_e32 v96, 2, v103
	global_load_dwordx4 v[208:211], v96, s[44:45]
	global_load_dwordx4 v[212:215], v96, s[4:5]
	global_load_dwordx4 v[216:219], v96, s[44:45] offset:16
	global_load_dwordx4 v[220:223], v96, s[4:5] offset:16
	v_mov_b32_e32 v96, v76
	v_mov_b32_e32 v104, v76
	s_nop 1
	v_permlane16_swap_b32_e32 v96, v104
	v_cndmask_b32_e64 v96, v96, v104, s[6:7]
	v_cndmask_b32_e64 v105, v96, -v96, s[10:11]
	v_mov_b32_e32 v96, v77
	v_mov_b32_e32 v106, v76
	s_waitcnt vmcnt(2)
; __device__ __forceinline__ float shx16(float v, int odd  ) { const unsigned x = __builtin_bit_cast(unsigned, v); auto r = __builtin_amdgcn_permlane16_swap(x, x, false, false); return __builtin_bit_cast(float, odd ? r[0] : r[1]); }
; __device__ __forceinline__ void st_bf4(bf16_t* p, const f32x4 v) { u32x2 w; w.x = cvt_pk_bf16(v[0], v[1]); w.y = cvt_pk_bf16(v[2], v[3]); *(u32x2*)p = w; }
;     __device__ __forceinline__ void operator()(const f32x4 (&acc)[2][2][4][2], const Unit& u, int wr, int wc, int fr, int fq) const {
;     ...
;                     for (int n = 0; n < 2; ++n) { const int tc = bj * 128 + wc * 32 + 8 * fq + 4 * n; f32x4 v = acc[ai][bj][m][n];
;                         if (pn < 2) { *(f32x4*)(XA + (size_t)row * 512 + pn * 256 + tc) = v; }
;                         else if (pn <= 4) {
;                             const bool isv = (pn == 4 && bj == 1);
;                             if (!isv && (wc & 1) == 0) {
;                                 const int tix = row < cfg::MP ? (row & 2047) : 2048 + (row & 3);
;                                 const f32x4 cs = *(const f32x4*)(ropec + tix * 8 + 4 * n), sn = *(const f32x4*)(ropes + tix * 8 + 4 * n);
; #pragma unroll
;                                 for (int i = 0; i < 4; ++i) { const float p = shx16(v[i], fq & 1); const float rv = v[i] * cs[i] + (fq == 0 ? -p : p) * sn[i]; v[i] = fq < 2 ? rv : v[i]; }
;                             }
;                             if (pn < 4) st_bf4(Q + (size_t)row * 512 + (pn - 2) * 256 + tc, v);
;                             else { st_bf4((bj == 0 ? KB : VB) + (size_t)row * 128 + (tc & 127), v);
;                                 bool w = false; size_t o = 0;
;                                 if (row < cfg::MP) { const int t = row & 2047; if (t >= 1920) { w = true; o = (bj == 0 ? cfg::OFF_KP : cfg::OFF_VP) + ((size_t)(layer * 8 + (row >> 11)) * 128 + (t - 1920)) * 128 + (tc & 127); } }
;                                 else { const int rs = row - cfg::MP; w = true; o = (bj == 0 ? cfg::OFF_KS : cfg::OFF_VS) + ((size_t)(layer * 128 + (rs >> 2)) * 128 + 124 + (rs & 3)) * 128 + (tc & 127); }
;                                 if (w) *(f32x4*)(out + o) = v; }
	v_mov_b32_e32 v104, v208
	v_mov_b32_e32 v107, v212
	v_mov_b32_e32 v98, v77
	s_nop 1
	v_permlane16_swap_b32_e32 v96, v98
	v_pk_mul_f32 v[104:105], v[106:107], v[104:105]
	v_cndmask_b32_e64 v96, v96, v98, s[6:7]
	v_add_f32_e32 v80, v104, v105
	v_cndmask_b32_e64 v105, v96, -v96, s[10:11]
	v_mov_b32_e32 v98, v77
	v_mov_b32_e32 v104, v209
	v_mov_b32_e32 v99, v213
	v_pk_mul_f32 v[98:99], v[98:99], v[104:105]
	v_mov_b32_e32 v96, v78
	v_add_f32_e32 v81, v98, v99
	v_mov_b32_e32 v98, v78
	s_nop 1
	v_permlane16_swap_b32_e32 v96, v98
	v_cndmask_b32_e64 v96, v96, v98, s[6:7]
	v_cndmask_b32_e64 v99, v96, -v96, s[10:11]
	v_mov_b32_e32 v104, v78
	v_mov_b32_e32 v105, v214
	v_mov_b32_e32 v98, v210
	v_pk_mul_f32 v[98:99], v[104:105], v[98:99]
	v_mov_b32_e32 v96, v79
	v_add_f32_e32 v82, v98, v99
	v_mov_b32_e32 v98, v79
	s_nop 1
	v_permlane16_swap_b32_e32 v96, v98
	v_cndmask_b32_e64 v96, v96, v98, s[6:7]
	v_cndmask_b32_e64 v99, v96, -v96, s[10:11]
	v_mov_b32_e32 v100, v79
	v_mov_b32_e32 v98, v211
	v_mov_b32_e32 v101, v215
	v_pk_mul_f32 v[98:99], v[100:101], v[98:99]
	v_cndmask_b32_e64 v80, v76, v80, s[8:9]
	v_add_f32_e32 v83, v98, v99
	v_cndmask_b32_e64 v81, v77, v81, s[8:9]
	v_cndmask_b32_e64 v82, v78, v82, s[8:9]
	v_cndmask_b32_e64 v83, v79, v83, s[8:9]
	v_mov_b32_e32 v104, v80
	v_mov_b32_e32 v106, v81
	v_mov_b32_e32 v105, v82
	v_mov_b32_e32 v107, v83
	v_lshl_add_u64 v[98:99], v[154:155], 0, v[86:87]
	v_cvt_pk_bf16_f32 v100, v104, v106
	v_cvt_pk_bf16_f32 v101, v105, v107
	global_store_dwordx2 v[98:99], v[100:101], off
	s_and_saveexec_b64 s[78:79], s[20:21]
	s_xor_b64 s[78:79], exec, s[78:79]
	s_mov_b64 s[70:71], exec
	v_add_u32_e32 v98, s87, v102
	s_or_saveexec_b64 s[78:79], s[78:79]
	v_mov_b64_e32 v[100:101], v[160:161]
	s_xor_b64 exec, exec, s[78:79]
	s_and_saveexec_b64 vcc, s[18:19]
	v_readlane_b32 s80, v254, 37
	v_readlane_b32 s81, v254, 38
	s_add_i32 s46, s75, s80
	s_or_b64 s[80:81], s[70:71], exec
	s_or_b64 exec, exec, vcc
	s_andn2_b64 s[70:71], s[70:71], exec
	s_and_b64 s[80:81], s[80:81], exec
	v_mov_b32_e32 v98, s46
	s_or_b64 s[70:71], s[70:71], s[80:81]
	v_mov_b64_e32 v[100:101], v[94:95]
	v_readlane_b32 s86, v254, 63
	v_readlane_b32 s87, v255, 0
	s_or_b64 exec, exec, s[78:79]
	s_and_saveexec_b64 s[78:79], s[70:71]
	v_ashrrev_i32_e32 v99, 31, v98
	v_lshl_add_u64 v[100:101], v[100:101], 2, v[156:157]
	v_lshlrev_b64 v[98:99], 16, v[98:99]
	v_lshl_add_u64 v[98:99], v[100:101], 0, v[98:99]
	global_store_dwordx4 v[98:99], v[80:83], off
	s_or_b64 exec, exec, s[78:79]
	s_nop 0
	v_lshlrev_b32_e32 v82, 2, v103
	v_mov_b32_e32 v82, v72
	v_mov_b32_e32 v83, v72
	s_nop 1
	v_permlane16_swap_b32_e32 v82, v83
	v_cndmask_b32_e64 v82, v82, v83, s[6:7]
	v_cndmask_b32_e64 v83, v82, -v82, s[10:11]
	v_mov_b32_e32 v104, v72
	s_waitcnt vmcnt(1)
	v_mov_b32_e32 v82, v216
	v_mov_b32_e32 v105, v220
	v_pk_mul_f32 v[82:83], v[104:105], v[82:83]
	v_mov_b32_e32 v98, v73
	v_add_f32_e32 v76, v82, v83
	v_mov_b32_e32 v82, v73
	v_mov_b32_e32 v83, v73
	s_nop 1
	v_permlane16_swap_b32_e32 v82, v83
	v_cndmask_b32_e64 v82, v82, v83, s[6:7]
	v_cndmask_b32_e64 v83, v82, -v82, s[10:11]
	v_mov_b32_e32 v82, v217
	v_mov_b32_e32 v99, v221
	v_pk_mul_f32 v[82:83], v[98:99], v[82:83]
	v_mov_b32_e32 v98, v74
	v_add_f32_e32 v77, v82, v83
	v_mov_b32_e32 v82, v74
	v_mov_b32_e32 v83, v74
	s_nop 1
	v_permlane16_swap_b32_e32 v82, v83
	v_cndmask_b32_e64 v82, v82, v83, s[6:7]
	v_cndmask_b32_e64 v83, v82, -v82, s[10:11]
	v_mov_b32_e32 v99, v222
	v_mov_b32_e32 v82, v218
	v_pk_mul_f32 v[82:83], v[98:99], v[82:83]
	v_mov_b32_e32 v100, v75
	v_add_f32_e32 v78, v82, v83
	v_mov_b32_e32 v82, v75
	v_mov_b32_e32 v83, v75
	s_nop 1
	v_permlane16_swap_b32_e32 v82, v83
	v_cndmask_b32_e64 v82, v82, v83, s[6:7]
	v_cndmask_b32_e64 v83, v82, -v82, s[10:11]
	v_mov_b32_e32 v82, v219
	v_mov_b32_e32 v101, v223
	v_pk_mul_f32 v[82:83], v[100:101], v[82:83]
	v_cndmask_b32_e64 v76, v72, v76, s[8:9]
	v_add_f32_e32 v79, v82, v83
	v_cndmask_b32_e64 v77, v73, v77, s[8:9]
	v_cndmask_b32_e64 v78, v74, v78, s[8:9]
	v_cndmask_b32_e64 v79, v75, v79, s[8:9]
	v_mov_b32_e32 v100, v76
	v_mov_b32_e32 v104, v77
	v_mov_b32_e32 v101, v78
	v_mov_b32_e32 v105, v79
	v_lshl_add_u64 v[82:83], v[164:165], 0, v[86:87]
	v_cvt_pk_bf16_f32 v98, v100, v104
	v_cvt_pk_bf16_f32 v99, v101, v105
	global_store_dwordx2 v[82:83], v[98:99], off
	s_and_saveexec_b64 s[78:79], s[20:21]
	s_xor_b64 s[78:79], exec, s[78:79]
	s_mov_b64 s[70:71], exec
	v_add_u32_e32 v82, s87, v102
	s_or_saveexec_b64 s[78:79], s[78:79]
	v_mov_b64_e32 v[98:99], v[160:161]
	s_xor_b64 exec, exec, s[78:79]
	s_and_saveexec_b64 vcc, s[18:19]
	v_readlane_b32 s80, v254, 37
	v_readlane_b32 s81, v254, 38
	s_add_i32 s46, s75, s80
	s_or_b64 s[80:81], s[70:71], exec
	s_or_b64 exec, exec, vcc
	s_andn2_b64 s[70:71], s[70:71], exec
	s_and_b64 s[80:81], s[80:81], exec
	v_mov_b32_e32 v82, s46
	s_or_b64 s[70:71], s[70:71], s[80:81]
	v_mov_b64_e32 v[98:99], v[94:95]
	v_readlane_b32 s86, v254, 63
	v_readlane_b32 s87, v255, 0
	s_or_b64 exec, exec, s[78:79]
	s_and_saveexec_b64 s[78:79], s[70:71]
	v_ashrrev_i32_e32 v83, 31, v82
	v_lshl_add_u64 v[94:95], v[98:99], 2, v[156:157]
	v_lshlrev_b64 v[82:83], 16, v[82:83]
	v_lshl_add_u64 v[82:83], v[94:95], 0, v[82:83]
	global_store_dwordx4 v[82:83], v[76:79], off offset:16
	s_or_b64 exec, exec, s[78:79]
	s_mov_b64 s[70:71], 0x1100000
	v_lshl_add_u64 v[76:77], v[92:93], 0, s[70:71]
	v_mov_b64_e32 v[74:75], v[70:71]
	v_mov_b64_e32 v[72:73], v[68:69]
	v_mov_b32_e32 v92, v68
	v_mov_b32_e32 v94, v69
	v_mov_b32_e32 v93, v70
	v_mov_b32_e32 v95, v71
	v_lshl_add_u64 v[78:79], v[158:159], 0, v[86:87]
	v_cvt_pk_bf16_f32 v82, v92, v94
	v_cvt_pk_bf16_f32 v83, v93, v95
; __device__ __forceinline__ float shx16(float v, int odd  ) { const unsigned x = __builtin_bit_cast(unsigned, v); auto r = __builtin_amdgcn_permlane16_swap(x, x, false, false); return __builtin_bit_cast(float, odd ? r[0] : r[1]); }
;     __device__ __forceinline__ void operator()(const f32x4 (&acc)[2][2][4][2], const Unit& u, int wr, int wc, int fr, int fq) const {
;     ...
;         for (int ai = 0; ai < 2; ++ai)
; #pragma unroll
;             for (int m = 0; m < 4; ++m) { const int row = u.pm * 256 + ai * 128 + wr * 64 + m * 16 + fr;
; #pragma unroll
;                 for (int bj = 0; bj < 2; ++bj)
; #pragma unroll
;                     for (int n = 0; n < 2; ++n) { const int tc = bj * 128 + wc * 32 + 8 * fq + 4 * n; f32x4 v = acc[ai][bj][m][n];
;                         if (pn < 2) { *(f32x4*)(XA + (size_t)row * 512 + pn * 256 + tc) = v; }
;                         else if (pn <= 4) {
;                             const bool isv = (pn == 4 && bj == 1);
;                             if (!isv && (wc & 1) == 0) {
;                                 const int tix = row < cfg::MP ? (row & 2047) : 2048 + (row & 3);
;                                 const f32x4 cs = *(const f32x4*)(ropec + tix * 8 + 4 * n), sn = *(const f32x4*)(ropes + tix * 8 + 4 * n);
; #pragma unroll
;                                 for (int i = 0; i < 4; ++i) { const float p = shx16(v[i], fq & 1); const float rv = v[i] * cs[i] + (fq == 0 ? -p : p) * sn[i]; v[i] = fq < 2 ? rv : v[i]; }
;                             }
;                             if (pn < 4) st_bf4(Q + (size_t)row * 512 + (pn - 2) * 256 + tc, v);
;                             else { st_bf4((bj == 0 ? KB : VB) + (size_t)row * 128 + (tc & 127), v);
;                                 bool w = false; size_t o = 0;
;                                 if (row < cfg::MP) { const int t = row & 2047; if (t >= 1920) { w = true; o = (bj == 0 ? cfg::OFF_KP : cfg::OFF_VP) + ((size_t)(layer * 8 + (row >> 11)) * 128 + (t - 1920)) * 128 + (tc & 127); } }
;                                 else { const int rs = row - cfg::MP; w = true; o = (bj == 0 ? cfg::OFF_KS : cfg::OFF_VS) + ((size_t)(layer * 128 + (rs >> 2)) * 128 + 124 + (rs & 3)) * 128 + (tc & 127); }
;                                 if (w) *(f32x4*)(out + o) = v; }
	global_store_dwordx2 v[78:79], v[82:83], off
	s_and_saveexec_b64 s[78:79], s[20:21]
	s_xor_b64 s[78:79], exec, s[78:79]
	s_mov_b64 s[70:71], exec
	v_add_u32_e32 v78, s87, v102
	s_or_saveexec_b64 s[78:79], s[78:79]
	v_mov_b64_e32 v[82:83], v[162:163]
	s_xor_b64 exec, exec, s[78:79]
	s_and_saveexec_b64 vcc, s[18:19]
	v_readlane_b32 s80, v254, 37
	v_readlane_b32 s81, v254, 38
	s_add_i32 s46, s75, s80
	s_or_b64 s[80:81], s[70:71], exec
	s_or_b64 exec, exec, vcc
	s_andn2_b64 s[70:71], s[70:71], exec
	s_and_b64 s[80:81], s[80:81], exec
	v_mov_b32_e32 v78, s46
	s_or_b64 s[70:71], s[70:71], s[80:81]
	v_mov_b64_e32 v[82:83], v[76:77]
	v_readlane_b32 s86, v254, 63
	v_readlane_b32 s87, v255, 0
	s_or_b64 exec, exec, s[78:79]
	s_and_saveexec_b64 s[78:79], s[70:71]
	v_ashrrev_i32_e32 v79, 31, v78
	v_lshl_add_u64 v[82:83], v[82:83], 2, v[156:157]
	v_lshlrev_b64 v[78:79], 16, v[78:79]
	v_lshl_add_u64 v[78:79], v[82:83], 0, v[78:79]
	global_store_dwordx4 v[78:79], v[72:75], off
	s_or_b64 exec, exec, s[78:79]
	v_mov_b64_e32 v[70:71], v[66:67]
	v_mov_b64_e32 v[68:69], v[64:65]
	v_mov_b32_e32 v78, v64
	v_mov_b32_e32 v82, v65
	v_mov_b32_e32 v79, v66
	v_mov_b32_e32 v83, v67
	s_andn2_b64 vcc, exec, s[96:97]
	v_lshl_add_u64 v[72:73], v[166:167], 0, v[86:87]
	v_cvt_pk_bf16_f32 v74, v78, v82
	v_cvt_pk_bf16_f32 v75, v79, v83
	global_store_dwordx2 v[72:73], v[74:75], off
	s_and_saveexec_b64 s[78:79], s[20:21]
	s_xor_b64 s[20:21], exec, s[78:79]
	s_mov_b64 s[70:71], exec
	v_add_u32_e32 v72, s87, v102
	s_or_saveexec_b64 s[20:21], s[20:21]
	v_mov_b64_e32 v[74:75], v[162:163]
	s_xor_b64 exec, exec, s[20:21]
	s_and_saveexec_b64 s[80:81], s[18:19]
	v_readlane_b32 s18, v254, 37
	s_add_i32 s46, s75, s18
	s_or_b64 s[78:79], s[70:71], exec
	v_readlane_b32 s19, v254, 38
	s_or_b64 exec, exec, s[80:81]
	s_andn2_b64 s[18:19], s[70:71], exec
	s_and_b64 s[70:71], s[78:79], exec
	v_mov_b32_e32 v72, s46
	s_or_b64 s[70:71], s[18:19], s[70:71]
	v_mov_b64_e32 v[74:75], v[76:77]
	s_or_b64 exec, exec, s[20:21]
	s_and_saveexec_b64 s[18:19], s[70:71]
	v_ashrrev_i32_e32 v73, 31, v72
	v_lshl_add_u64 v[74:75], v[74:75], 2, v[156:157]
	v_lshlrev_b64 v[72:73], 16, v[72:73]
	v_lshl_add_u64 v[72:73], v[74:75], 0, v[72:73]
	global_store_dwordx4 v[72:73], v[68:71], off offset:16
	s_or_b64 exec, exec, s[18:19]
	s_add_i32 s46, s53, 0x80
	v_or_b32_e32 v68, s46, v143
	v_mad_i64_i32 v[76:77], s[18:19], v68, s61, 0
	s_movk_i32 s18, 0x3fff
	s_nop 0
	v_cmp_lt_i32_e64 s[20:21], s18, v68
	v_mov_b32_e32 v64, 0x7cf
	s_movk_i32 s18, 0x4000
	v_bitop3_b32 v64, s46, v64, v143 bitop3:0xc8
	v_cmp_gt_i32_e32 vcc, s18, v68
	v_add_u32_e32 v96, 0xfffff880, v64
	v_ashrrev_i32_e32 v69, 31, v68
	v_cndmask_b32_e32 v65, v151, v64, vcc
	v_lshlrev_b32_e32 v87, 3, v65
	v_add_u32_e32 v65, 0xffffc000, v68
	s_movk_i32 s18, 0x77f
	v_lshlrev_b64 v[78:79], 7, v[96:97]
	s_mov_b64 s[70:71], 0x1080000
	s_ashr_i32 s53, s46, 11
	v_lshlrev_b64 v[72:73], 8, v[68:69]
	v_lshrrev_b32_e32 v86, 2, v65
	v_cmp_lt_u32_e64 s[18:19], s18, v64
	v_lshl_add_u64 v[80:81], v[78:79], 0, s[70:71]
	s_mov_b32 s75, 0x400000
	v_lshlrev_b32_e32 v69, 2, v87
	global_load_dwordx4 v[208:211], v69, s[44:45]
	global_load_dwordx4 v[212:215], v69, s[4:5]
	global_load_dwordx4 v[216:219], v69, s[44:45] offset:16
	global_load_dwordx4 v[220:223], v69, s[4:5] offset:16
	v_mov_b32_e32 v69, v60
	v_mov_b32_e32 v88, v60
	s_nop 1
	v_permlane16_swap_b32_e32 v69, v88
	v_cndmask_b32_e64 v69, v69, v88, s[6:7]
	v_cndmask_b32_e64 v89, v69, -v69, s[10:11]
	v_mov_b32_e32 v69, v61
	v_mov_b32_e32 v90, v60
	s_waitcnt vmcnt(2)
	v_mov_b32_e32 v88, v208
	v_mov_b32_e32 v91, v212
	v_mov_b32_e32 v82, v61
	s_nop 1
	v_permlane16_swap_b32_e32 v69, v82
	v_pk_mul_f32 v[88:89], v[90:91], v[88:89]
	v_cndmask_b32_e64 v69, v69, v82, s[6:7]
	v_add_f32_e32 v64, v88, v89
	v_cndmask_b32_e64 v89, v69, -v69, s[10:11]
	v_mov_b32_e32 v82, v61
	v_mov_b32_e32 v88, v209
	v_mov_b32_e32 v83, v213
	v_pk_mul_f32 v[82:83], v[82:83], v[88:89]
	v_mov_b32_e32 v69, v62
	v_add_f32_e32 v65, v82, v83
	v_mov_b32_e32 v82, v62
	s_nop 1
	v_permlane16_swap_b32_e32 v69, v82
	v_cndmask_b32_e64 v69, v69, v82, s[6:7]
	v_cndmask_b32_e64 v83, v69, -v69, s[10:11]
	v_mov_b32_e32 v88, v62
	v_mov_b32_e32 v89, v214
	v_mov_b32_e32 v82, v210
	v_pk_mul_f32 v[82:83], v[88:89], v[82:83]
	v_mov_b32_e32 v69, v63
	v_add_f32_e32 v66, v82, v83
	v_mov_b32_e32 v82, v63
	s_nop 1
	v_permlane16_swap_b32_e32 v69, v82
	v_cndmask_b32_e64 v69, v69, v82, s[6:7]
	v_cndmask_b32_e64 v83, v69, -v69, s[10:11]
	v_mov_b32_e32 v84, v63
	v_mov_b32_e32 v82, v211
	v_mov_b32_e32 v85, v215
	v_pk_mul_f32 v[82:83], v[84:85], v[82:83]
	v_cndmask_b32_e64 v64, v60, v64, s[8:9]
	v_add_f32_e32 v67, v82, v83
	v_cndmask_b32_e64 v65, v61, v65, s[8:9]
	v_cndmask_b32_e64 v66, v62, v66, s[8:9]
	v_cndmask_b32_e64 v67, v63, v67, s[8:9]
	v_mov_b32_e32 v69, v64
	v_mov_b32_e32 v89, v65
	v_mov_b32_e32 v88, v66
	v_mov_b32_e32 v90, v67
	v_lshl_add_u64 v[82:83], v[154:155], 0, v[72:73]
	v_cvt_pk_bf16_f32 v84, v69, v89
	v_cvt_pk_bf16_f32 v85, v88, v90
	global_store_dwordx2 v[82:83], v[84:85], off
	s_and_saveexec_b64 s[78:79], s[20:21]
	s_xor_b64 s[78:79], exec, s[78:79]
	s_mov_b64 s[70:71], exec
	v_add_u32_e32 v82, s87, v86
	s_or_saveexec_b64 s[78:79], s[78:79]
	v_mov_b64_e32 v[84:85], v[160:161]
	s_xor_b64 exec, exec, s[78:79]
	s_and_saveexec_b64 vcc, s[18:19]
	v_readlane_b32 s80, v254, 37
	v_readlane_b32 s81, v254, 38
	s_add_i32 s46, s53, s80
	s_or_b64 s[80:81], s[70:71], exec
	s_or_b64 exec, exec, vcc
	s_andn2_b64 s[70:71], s[70:71], exec
	s_and_b64 s[80:81], s[80:81], exec
	v_mov_b32_e32 v82, s46
	s_or_b64 s[70:71], s[70:71], s[80:81]
	v_mov_b64_e32 v[84:85], v[80:81]
	v_readlane_b32 s86, v254, 63
	v_readlane_b32 s87, v255, 0
	s_or_b64 exec, exec, s[78:79]
	s_and_saveexec_b64 s[78:79], s[70:71]
	v_ashrrev_i32_e32 v83, 31, v82
	v_lshl_add_u64 v[84:85], v[84:85], 2, v[156:157]
	v_lshlrev_b64 v[82:83], 16, v[82:83]
	v_lshl_add_u64 v[82:83], v[84:85], 0, v[82:83]
	global_store_dwordx4 v[82:83], v[64:67], off
	s_or_b64 exec, exec, s[78:79]
	s_nop 0
	v_lshlrev_b32_e32 v66, 2, v87
	v_mov_b32_e32 v66, v56
	v_mov_b32_e32 v67, v56
	s_nop 1
	v_permlane16_swap_b32_e32 v66, v67
	v_cndmask_b32_e64 v66, v66, v67, s[6:7]
	v_cndmask_b32_e64 v67, v66, -v66, s[10:11]
	v_mov_b32_e32 v88, v56
	s_waitcnt vmcnt(1)
; __device__ __forceinline__ float shx16(float v, int odd  ) { const unsigned x = __builtin_bit_cast(unsigned, v); auto r = __builtin_amdgcn_permlane16_swap(x, x, false, false); return __builtin_bit_cast(float, odd ? r[0] : r[1]); }
; __device__ __forceinline__ void st_bf4(bf16_t* p, const f32x4 v) { u32x2 w; w.x = cvt_pk_bf16(v[0], v[1]); w.y = cvt_pk_bf16(v[2], v[3]); *(u32x2*)p = w; }
;     __device__ __forceinline__ void operator()(const f32x4 (&acc)[2][2][4][2], const Unit& u, int wr, int wc, int fr, int fq) const {
;     ...
;                     for (int n = 0; n < 2; ++n) { const int tc = bj * 128 + wc * 32 + 8 * fq + 4 * n; f32x4 v = acc[ai][bj][m][n];
;                         if (pn < 2) { *(f32x4*)(XA + (size_t)row * 512 + pn * 256 + tc) = v; }
;                         else if (pn <= 4) {
;                             const bool isv = (pn == 4 && bj == 1);
;                             if (!isv && (wc & 1) == 0) {
;                                 const int tix = row < cfg::MP ? (row & 2047) : 2048 + (row & 3);
;                                 const f32x4 cs = *(const f32x4*)(ropec + tix * 8 + 4 * n), sn = *(const f32x4*)(ropes + tix * 8 + 4 * n);
; #pragma unroll
;                                 for (int i = 0; i < 4; ++i) { const float p = shx16(v[i], fq & 1); const float rv = v[i] * cs[i] + (fq == 0 ? -p : p) * sn[i]; v[i] = fq < 2 ? rv : v[i]; }
;                             }
;                             if (pn < 4) st_bf4(Q + (size_t)row * 512 + (pn - 2) * 256 + tc, v);
;                             else { st_bf4((bj == 0 ? KB : VB) + (size_t)row * 128 + (tc & 127), v);
;                                 bool w = false; size_t o = 0;
;                                 if (row < cfg::MP) { const int t = row & 2047; if (t >= 1920) { w = true; o = (bj == 0 ? cfg::OFF_KP : cfg::OFF_VP) + ((size_t)(layer * 8 + (row >> 11)) * 128 + (t - 1920)) * 128 + (tc & 127); } }
;                                 else { const int rs = row - cfg::MP; w = true; o = (bj == 0 ? cfg::OFF_KS : cfg::OFF_VS) + ((size_t)(layer * 128 + (rs >> 2)) * 128 + 124 + (rs & 3)) * 128 + (tc & 127); }
;                                 if (w) *(f32x4*)(out + o) = v; }
	v_mov_b32_e32 v66, v216
	v_mov_b32_e32 v89, v220
	v_pk_mul_f32 v[66:67], v[88:89], v[66:67]
	v_mov_b32_e32 v82, v57
	v_add_f32_e32 v60, v66, v67
	v_mov_b32_e32 v66, v57
	v_mov_b32_e32 v67, v57
	s_nop 1
	v_permlane16_swap_b32_e32 v66, v67
	v_cndmask_b32_e64 v66, v66, v67, s[6:7]
	v_cndmask_b32_e64 v67, v66, -v66, s[10:11]
	v_mov_b32_e32 v66, v217
	v_mov_b32_e32 v83, v221
	v_pk_mul_f32 v[66:67], v[82:83], v[66:67]
	v_mov_b32_e32 v82, v58
	v_add_f32_e32 v61, v66, v67
	v_mov_b32_e32 v66, v58
	v_mov_b32_e32 v67, v58
	s_nop 1
	v_permlane16_swap_b32_e32 v66, v67
	v_cndmask_b32_e64 v66, v66, v67, s[6:7]
	v_cndmask_b32_e64 v67, v66, -v66, s[10:11]
	v_mov_b32_e32 v83, v222
	v_mov_b32_e32 v66, v218
	v_pk_mul_f32 v[66:67], v[82:83], v[66:67]
	v_mov_b32_e32 v84, v59
	v_add_f32_e32 v62, v66, v67
	v_mov_b32_e32 v66, v59
	v_mov_b32_e32 v67, v59
	s_nop 1
	v_permlane16_swap_b32_e32 v66, v67
	v_cndmask_b32_e64 v66, v66, v67, s[6:7]
	v_cndmask_b32_e64 v67, v66, -v66, s[10:11]
	v_mov_b32_e32 v66, v219
	v_mov_b32_e32 v85, v223
	v_pk_mul_f32 v[66:67], v[84:85], v[66:67]
	v_cndmask_b32_e64 v60, v56, v60, s[8:9]
	v_add_f32_e32 v63, v66, v67
	v_cndmask_b32_e64 v61, v57, v61, s[8:9]
	v_cndmask_b32_e64 v62, v58, v62, s[8:9]
	v_cndmask_b32_e64 v63, v59, v63, s[8:9]
	v_mov_b32_e32 v69, v60
	v_mov_b32_e32 v85, v61
	v_mov_b32_e32 v84, v62
	v_mov_b32_e32 v88, v63
	v_lshl_add_u64 v[66:67], v[164:165], 0, v[72:73]
	v_cvt_pk_bf16_f32 v82, v69, v85
	v_cvt_pk_bf16_f32 v83, v84, v88
	global_store_dwordx2 v[66:67], v[82:83], off
	s_and_saveexec_b64 s[78:79], s[20:21]
	s_xor_b64 s[78:79], exec, s[78:79]
	s_mov_b64 s[70:71], exec
	v_add_u32_e32 v66, s87, v86
	s_or_saveexec_b64 s[78:79], s[78:79]
	v_mov_b64_e32 v[82:83], v[160:161]
	s_xor_b64 exec, exec, s[78:79]
	s_and_saveexec_b64 vcc, s[18:19]
	v_readlane_b32 s80, v254, 37
	v_readlane_b32 s81, v254, 38
	s_add_i32 s46, s53, s80
	s_or_b64 s[80:81], s[70:71], exec
	s_or_b64 exec, exec, vcc
	s_andn2_b64 s[70:71], s[70:71], exec
	s_and_b64 s[80:81], s[80:81], exec
	v_mov_b32_e32 v66, s46
	s_or_b64 s[70:71], s[70:71], s[80:81]
	v_mov_b64_e32 v[82:83], v[80:81]
	v_readlane_b32 s86, v254, 63
	v_readlane_b32 s87, v255, 0
	s_or_b64 exec, exec, s[78:79]
	s_and_saveexec_b64 s[78:79], s[70:71]
	v_ashrrev_i32_e32 v67, 31, v66
	v_lshl_add_u64 v[80:81], v[82:83], 2, v[156:157]
	v_lshlrev_b64 v[66:67], 16, v[66:67]
	v_lshl_add_u64 v[66:67], v[80:81], 0, v[66:67]
	global_store_dwordx4 v[66:67], v[60:63], off offset:16
	s_or_b64 exec, exec, s[78:79]
	s_mov_b64 s[70:71], 0x1100000
	v_lshl_add_u64 v[60:61], v[78:79], 0, s[70:71]
	v_mov_b64_e32 v[58:59], v[54:55]
	v_mov_b64_e32 v[56:57], v[52:53]
	v_mov_b32_e32 v69, v52
	v_mov_b32_e32 v79, v53
	v_mov_b32_e32 v78, v54
	v_mov_b32_e32 v80, v55
	v_lshl_add_u64 v[62:63], v[158:159], 0, v[72:73]
	v_cvt_pk_bf16_f32 v66, v69, v79
	v_cvt_pk_bf16_f32 v67, v78, v80
	global_store_dwordx2 v[62:63], v[66:67], off
	s_and_saveexec_b64 s[78:79], s[20:21]
	s_xor_b64 s[78:79], exec, s[78:79]
	s_mov_b64 s[70:71], exec
	v_add_u32_e32 v62, s87, v86
	s_or_saveexec_b64 s[78:79], s[78:79]
	v_mov_b64_e32 v[66:67], v[162:163]
	s_xor_b64 exec, exec, s[78:79]
	s_and_saveexec_b64 vcc, s[18:19]
	v_readlane_b32 s80, v254, 37
	v_readlane_b32 s81, v254, 38
	s_add_i32 s46, s53, s80
	s_or_b64 s[80:81], s[70:71], exec
	s_or_b64 exec, exec, vcc
	s_andn2_b64 s[70:71], s[70:71], exec
	s_and_b64 s[80:81], s[80:81], exec
	v_mov_b32_e32 v62, s46
	s_or_b64 s[70:71], s[70:71], s[80:81]
	v_mov_b64_e32 v[66:67], v[60:61]
	v_readlane_b32 s86, v254, 63
	v_readlane_b32 s87, v255, 0
	s_or_b64 exec, exec, s[78:79]
	s_and_saveexec_b64 s[78:79], s[70:71]
	v_ashrrev_i32_e32 v63, 31, v62
	v_lshl_add_u64 v[66:67], v[66:67], 2, v[156:157]
	v_lshlrev_b64 v[62:63], 16, v[62:63]
	v_lshl_add_u64 v[62:63], v[66:67], 0, v[62:63]
	global_store_dwordx4 v[62:63], v[56:59], off
	s_or_b64 exec, exec, s[78:79]
	v_mov_b64_e32 v[54:55], v[50:51]
	v_mov_b64_e32 v[52:53], v[48:49]
	v_mov_b32_e32 v62, v48
	v_mov_b32_e32 v66, v49
	v_mov_b32_e32 v63, v50
	v_mov_b32_e32 v67, v51
	s_andn2_b64 vcc, exec, s[96:97]
	v_lshl_add_u64 v[56:57], v[166:167], 0, v[72:73]
	v_cvt_pk_bf16_f32 v58, v62, v66
	v_cvt_pk_bf16_f32 v59, v63, v67
	global_store_dwordx2 v[56:57], v[58:59], off
	s_and_saveexec_b64 s[78:79], s[20:21]
	s_xor_b64 s[20:21], exec, s[78:79]
	s_mov_b64 s[70:71], exec
	v_add_u32_e32 v56, s87, v86
	s_or_saveexec_b64 s[20:21], s[20:21]
	v_mov_b64_e32 v[58:59], v[162:163]
	s_xor_b64 exec, exec, s[20:21]
	s_and_saveexec_b64 s[80:81], s[18:19]
	v_readlane_b32 s18, v254, 37
	s_add_i32 s46, s53, s18
	s_or_b64 s[78:79], s[70:71], exec
	v_readlane_b32 s19, v254, 38
	s_or_b64 exec, exec, s[80:81]
	s_andn2_b64 s[18:19], s[70:71], exec
	s_and_b64 s[70:71], s[78:79], exec
	v_mov_b32_e32 v56, s46
	s_or_b64 s[70:71], s[18:19], s[70:71]
	v_mov_b64_e32 v[58:59], v[60:61]
	s_or_b64 exec, exec, s[20:21]
	s_and_saveexec_b64 s[18:19], s[70:71]
	v_ashrrev_i32_e32 v57, 31, v56
	v_lshl_add_u64 v[58:59], v[58:59], 2, v[156:157]
	v_lshlrev_b64 v[56:57], 16, v[56:57]
	v_lshl_add_u64 v[56:57], v[58:59], 0, v[56:57]
	global_store_dwordx4 v[56:57], v[52:55], off offset:16
	s_or_b64 exec, exec, s[18:19]
	v_or_b32_e32 v48, 16, v68
	v_mad_i64_i32 v[58:59], s[18:19], v48, s61, 0
	s_movk_i32 s18, 0x3fff
	s_nop 0
	v_cmp_lt_i32_e64 s[20:21], s18, v48
	s_movk_i32 s18, 0x7df
	v_bitop3_b32 v50, v68, s18, 16 bitop3:0xc8
	s_movk_i32 s18, 0x4000
	v_cmp_gt_i32_e32 vcc, s18, v48
	v_add_u32_e32 v96, 0xfffff880, v50
	v_ashrrev_i32_e32 v49, 31, v48
	v_cndmask_b32_e32 v51, v151, v50, vcc
	v_lshlrev_b32_e32 v70, 3, v51
	v_add_u32_e32 v51, 0xffffc010, v68
	s_movk_i32 s18, 0x77f
	v_lshlrev_b64 v[60:61], 7, v[96:97]
	s_mov_b64 s[70:71], 0x1080000
	v_lshlrev_b64 v[54:55], 8, v[48:49]
	v_lshrrev_b32_e32 v69, 2, v51
	v_cmp_lt_u32_e64 s[18:19], s18, v50
	v_lshl_add_u64 v[62:63], v[60:61], 0, s[70:71]
	v_lshlrev_b32_e32 v64, 2, v70
	global_load_dwordx4 v[208:211], v64, s[44:45]
	global_load_dwordx4 v[212:215], v64, s[4:5]
	global_load_dwordx4 v[216:219], v64, s[44:45] offset:16
	global_load_dwordx4 v[220:223], v64, s[4:5] offset:16
	v_mov_b32_e32 v71, v44
	v_mov_b32_e32 v72, v44
	s_nop 1
	v_permlane16_swap_b32_e32 v71, v72
	v_cndmask_b32_e64 v71, v71, v72, s[6:7]
	v_cndmask_b32_e64 v73, v71, -v71, s[10:11]
	v_mov_b32_e32 v71, v45
	v_mov_b32_e32 v74, v44
	s_waitcnt vmcnt(2)
; __device__ __forceinline__ float shx16(float v, int odd  ) { const unsigned x = __builtin_bit_cast(unsigned, v); auto r = __builtin_amdgcn_permlane16_swap(x, x, false, false); return __builtin_bit_cast(float, odd ? r[0] : r[1]); }
; __device__ __forceinline__ void st_bf4(bf16_t* p, const f32x4 v) { u32x2 w; w.x = cvt_pk_bf16(v[0], v[1]); w.y = cvt_pk_bf16(v[2], v[3]); *(u32x2*)p = w; }
;     __device__ __forceinline__ void operator()(const f32x4 (&acc)[2][2][4][2], const Unit& u, int wr, int wc, int fr, int fq) const {
;     ...
;                     for (int n = 0; n < 2; ++n) { const int tc = bj * 128 + wc * 32 + 8 * fq + 4 * n; f32x4 v = acc[ai][bj][m][n];
;                         if (pn < 2) { *(f32x4*)(XA + (size_t)row * 512 + pn * 256 + tc) = v; }
;                         else if (pn <= 4) {
;                             const bool isv = (pn == 4 && bj == 1);
;                             if (!isv && (wc & 1) == 0) {
;                                 const int tix = row < cfg::MP ? (row & 2047) : 2048 + (row & 3);
;                                 const f32x4 cs = *(const f32x4*)(ropec + tix * 8 + 4 * n), sn = *(const f32x4*)(ropes + tix * 8 + 4 * n);
; #pragma unroll
;                                 for (int i = 0; i < 4; ++i) { const float p = shx16(v[i], fq & 1); const float rv = v[i] * cs[i] + (fq == 0 ? -p : p) * sn[i]; v[i] = fq < 2 ? rv : v[i]; }
;                             }
;                             if (pn < 4) st_bf4(Q + (size_t)row * 512 + (pn - 2) * 256 + tc, v);
;                             else { st_bf4((bj == 0 ? KB : VB) + (size_t)row * 128 + (tc & 127), v);
;                                 bool w = false; size_t o = 0;
;                                 if (row < cfg::MP) { const int t = row & 2047; if (t >= 1920) { w = true; o = (bj == 0 ? cfg::OFF_KP : cfg::OFF_VP) + ((size_t)(layer * 8 + (row >> 11)) * 128 + (t - 1920)) * 128 + (tc & 127); } }
;                                 else { const int rs = row - cfg::MP; w = true; o = (bj == 0 ? cfg::OFF_KS : cfg::OFF_VS) + ((size_t)(layer * 128 + (rs >> 2)) * 128 + 124 + (rs & 3)) * 128 + (tc & 127); }
;                                 if (w) *(f32x4*)(out + o) = v; }
	v_mov_b32_e32 v72, v208
	v_mov_b32_e32 v75, v212
	v_mov_b32_e32 v64, v45
	s_nop 1
	v_permlane16_swap_b32_e32 v64, v71
	v_pk_mul_f32 v[72:73], v[74:75], v[72:73]
	v_cndmask_b32_e64 v64, v64, v71, s[6:7]
	v_add_f32_e32 v48, v72, v73
	v_cndmask_b32_e64 v73, v64, -v64, s[10:11]
	v_mov_b32_e32 v64, v45
	v_mov_b32_e32 v72, v209
	v_mov_b32_e32 v65, v213
	v_pk_mul_f32 v[64:65], v[64:65], v[72:73]
	v_mov_b32_e32 v72, v46
	v_add_f32_e32 v49, v64, v65
	v_mov_b32_e32 v64, v46
	v_mov_b32_e32 v65, v46
	s_nop 1
	v_permlane16_swap_b32_e32 v64, v65
	v_cndmask_b32_e64 v64, v64, v65, s[6:7]
	v_cndmask_b32_e64 v65, v64, -v64, s[10:11]
	v_mov_b32_e32 v73, v214
	v_mov_b32_e32 v64, v210
	v_pk_mul_f32 v[64:65], v[72:73], v[64:65]
	v_mov_b32_e32 v66, v47
	v_add_f32_e32 v50, v64, v65
	v_mov_b32_e32 v64, v47
	v_mov_b32_e32 v65, v47
	s_nop 1
	v_permlane16_swap_b32_e32 v64, v65
	v_cndmask_b32_e64 v64, v64, v65, s[6:7]
	v_cndmask_b32_e64 v65, v64, -v64, s[10:11]
	v_mov_b32_e32 v64, v211
	v_mov_b32_e32 v67, v215
	v_pk_mul_f32 v[64:65], v[66:67], v[64:65]
	v_cndmask_b32_e64 v48, v44, v48, s[8:9]
	v_add_f32_e32 v51, v64, v65
	v_cndmask_b32_e64 v49, v45, v49, s[8:9]
	v_cndmask_b32_e64 v50, v46, v50, s[8:9]
	v_cndmask_b32_e64 v51, v47, v51, s[8:9]
	v_mov_b32_e32 v71, v48
	v_mov_b32_e32 v73, v49
	v_mov_b32_e32 v72, v50
	v_mov_b32_e32 v74, v51
	v_lshl_add_u64 v[64:65], v[154:155], 0, v[54:55]
	v_cvt_pk_bf16_f32 v66, v71, v73
	v_cvt_pk_bf16_f32 v67, v72, v74
	global_store_dwordx2 v[64:65], v[66:67], off
	s_and_saveexec_b64 s[78:79], s[20:21]
	s_xor_b64 s[78:79], exec, s[78:79]
	s_mov_b64 s[70:71], exec
	v_add_u32_e32 v64, s87, v69
	s_or_saveexec_b64 s[78:79], s[78:79]
	v_mov_b64_e32 v[66:67], v[160:161]
	s_xor_b64 exec, exec, s[78:79]
	s_and_saveexec_b64 vcc, s[18:19]
	v_readlane_b32 s80, v254, 37
	v_readlane_b32 s81, v254, 38
	s_add_i32 s46, s53, s80
	s_or_b64 s[80:81], s[70:71], exec
	s_or_b64 exec, exec, vcc
	s_andn2_b64 s[70:71], s[70:71], exec
	s_and_b64 s[80:81], s[80:81], exec
	v_mov_b32_e32 v64, s46
	s_or_b64 s[70:71], s[70:71], s[80:81]
	v_mov_b64_e32 v[66:67], v[62:63]
	v_readlane_b32 s86, v254, 63
	v_readlane_b32 s87, v255, 0
	s_or_b64 exec, exec, s[78:79]
	s_and_saveexec_b64 s[78:79], s[70:71]
	v_ashrrev_i32_e32 v65, 31, v64
	v_lshl_add_u64 v[66:67], v[66:67], 2, v[156:157]
	v_lshlrev_b64 v[64:65], 16, v[64:65]
	v_lshl_add_u64 v[64:65], v[66:67], 0, v[64:65]
	global_store_dwordx4 v[64:65], v[48:51], off
	s_or_b64 exec, exec, s[78:79]
	s_nop 0
	v_lshlrev_b32_e32 v50, 2, v70
	v_mov_b32_e32 v50, v40
	v_mov_b32_e32 v51, v40
	s_nop 1
	v_permlane16_swap_b32_e32 v50, v51
	v_cndmask_b32_e64 v50, v50, v51, s[6:7]
	v_cndmask_b32_e64 v51, v50, -v50, s[10:11]
	v_mov_b32_e32 v72, v40
	s_waitcnt vmcnt(1)
	v_mov_b32_e32 v50, v216
	v_mov_b32_e32 v73, v220
	v_pk_mul_f32 v[50:51], v[72:73], v[50:51]
	v_mov_b32_e32 v64, v41
	v_add_f32_e32 v44, v50, v51
	v_mov_b32_e32 v50, v41
	v_mov_b32_e32 v51, v41
	s_nop 1
	v_permlane16_swap_b32_e32 v50, v51
	v_cndmask_b32_e64 v50, v50, v51, s[6:7]
	v_cndmask_b32_e64 v51, v50, -v50, s[10:11]
	v_mov_b32_e32 v50, v217
	v_mov_b32_e32 v65, v221
	v_pk_mul_f32 v[50:51], v[64:65], v[50:51]
	v_mov_b32_e32 v64, v42
	v_add_f32_e32 v45, v50, v51
	v_mov_b32_e32 v50, v42
	v_mov_b32_e32 v51, v42
	s_nop 1
	v_permlane16_swap_b32_e32 v50, v51
	v_cndmask_b32_e64 v50, v50, v51, s[6:7]
	v_cndmask_b32_e64 v51, v50, -v50, s[10:11]
	v_mov_b32_e32 v65, v222
	v_mov_b32_e32 v50, v218
	v_pk_mul_f32 v[50:51], v[64:65], v[50:51]
	v_mov_b32_e32 v66, v43
	v_add_f32_e32 v46, v50, v51
	v_mov_b32_e32 v50, v43
	v_mov_b32_e32 v51, v43
	s_nop 1
	v_permlane16_swap_b32_e32 v50, v51
	v_cndmask_b32_e64 v50, v50, v51, s[6:7]
	v_cndmask_b32_e64 v51, v50, -v50, s[10:11]
	v_mov_b32_e32 v50, v219
	v_mov_b32_e32 v67, v223
	v_pk_mul_f32 v[50:51], v[66:67], v[50:51]
	v_cndmask_b32_e64 v44, v40, v44, s[8:9]
	v_add_f32_e32 v47, v50, v51
	v_cndmask_b32_e64 v45, v41, v45, s[8:9]
	v_cndmask_b32_e64 v46, v42, v46, s[8:9]
	v_cndmask_b32_e64 v47, v43, v47, s[8:9]
	v_mov_b32_e32 v66, v44
	v_mov_b32_e32 v71, v45
	v_mov_b32_e32 v67, v46
	v_mov_b32_e32 v72, v47
	v_lshl_add_u64 v[50:51], v[164:165], 0, v[54:55]
	v_cvt_pk_bf16_f32 v64, v66, v71
	v_cvt_pk_bf16_f32 v65, v67, v72
	global_store_dwordx2 v[50:51], v[64:65], off
	s_and_saveexec_b64 s[78:79], s[20:21]
	s_xor_b64 s[78:79], exec, s[78:79]
	s_mov_b64 s[70:71], exec
	v_add_u32_e32 v50, s87, v69
	s_or_saveexec_b64 s[78:79], s[78:79]
	v_mov_b64_e32 v[64:65], v[160:161]
	s_xor_b64 exec, exec, s[78:79]
	s_and_saveexec_b64 vcc, s[18:19]
	v_readlane_b32 s80, v254, 37
	v_readlane_b32 s81, v254, 38
	s_add_i32 s46, s53, s80
	s_or_b64 s[80:81], s[70:71], exec
	s_or_b64 exec, exec, vcc
	s_andn2_b64 s[70:71], s[70:71], exec
	s_and_b64 s[80:81], s[80:81], exec
	v_mov_b32_e32 v50, s46
	s_or_b64 s[70:71], s[70:71], s[80:81]
	v_mov_b64_e32 v[64:65], v[62:63]
	v_readlane_b32 s86, v254, 63
	v_readlane_b32 s87, v255, 0
	s_or_b64 exec, exec, s[78:79]
	s_and_saveexec_b64 s[78:79], s[70:71]
	v_ashrrev_i32_e32 v51, 31, v50
	v_lshl_add_u64 v[62:63], v[64:65], 2, v[156:157]
	v_lshlrev_b64 v[50:51], 16, v[50:51]
	v_lshl_add_u64 v[50:51], v[62:63], 0, v[50:51]
	global_store_dwordx4 v[50:51], v[44:47], off offset:16
	s_or_b64 exec, exec, s[78:79]
	s_mov_b64 s[70:71], 0x1100000
	v_lshl_add_u64 v[44:45], v[60:61], 0, s[70:71]
	v_mov_b64_e32 v[42:43], v[38:39]
	v_mov_b64_e32 v[40:41], v[36:37]
	v_mov_b32_e32 v60, v36
	v_mov_b32_e32 v62, v37
	v_mov_b32_e32 v61, v38
	v_mov_b32_e32 v63, v39
	v_lshl_add_u64 v[46:47], v[158:159], 0, v[54:55]
	v_cvt_pk_bf16_f32 v50, v60, v62
	v_cvt_pk_bf16_f32 v51, v61, v63
	global_store_dwordx2 v[46:47], v[50:51], off
	s_and_saveexec_b64 s[78:79], s[20:21]
; __device__ __forceinline__ float shx16(float v, int odd  ) { const unsigned x = __builtin_bit_cast(unsigned, v); auto r = __builtin_amdgcn_permlane16_swap(x, x, false, false); return __builtin_bit_cast(float, odd ? r[0] : r[1]); }
; __device__ __forceinline__ void st_bf4(bf16_t* p, const f32x4 v) { u32x2 w; w.x = cvt_pk_bf16(v[0], v[1]); w.y = cvt_pk_bf16(v[2], v[3]); *(u32x2*)p = w; }
;     __device__ __forceinline__ void operator()(const f32x4 (&acc)[2][2][4][2], const Unit& u, int wr, int wc, int fr, int fq) const {
;     ...
;                     for (int n = 0; n < 2; ++n) { const int tc = bj * 128 + wc * 32 + 8 * fq + 4 * n; f32x4 v = acc[ai][bj][m][n];
;                         if (pn < 2) { *(f32x4*)(XA + (size_t)row * 512 + pn * 256 + tc) = v; }
;                         else if (pn <= 4) {
;                             const bool isv = (pn == 4 && bj == 1);
;                             if (!isv && (wc & 1) == 0) {
;                                 const int tix = row < cfg::MP ? (row & 2047) : 2048 + (row & 3);
;                                 const f32x4 cs = *(const f32x4*)(ropec + tix * 8 + 4 * n), sn = *(const f32x4*)(ropes + tix * 8 + 4 * n);
; #pragma unroll
;                                 for (int i = 0; i < 4; ++i) { const float p = shx16(v[i], fq & 1); const float rv = v[i] * cs[i] + (fq == 0 ? -p : p) * sn[i]; v[i] = fq < 2 ? rv : v[i]; }
;                             }
;                             if (pn < 4) st_bf4(Q + (size_t)row * 512 + (pn - 2) * 256 + tc, v);
;                             else { st_bf4((bj == 0 ? KB : VB) + (size_t)row * 128 + (tc & 127), v);
;                                 bool w = false; size_t o = 0;
;                                 if (row < cfg::MP) { const int t = row & 2047; if (t >= 1920) { w = true; o = (bj == 0 ? cfg::OFF_KP : cfg::OFF_VP) + ((size_t)(layer * 8 + (row >> 11)) * 128 + (t - 1920)) * 128 + (tc & 127); } }
;                                 else { const int rs = row - cfg::MP; w = true; o = (bj == 0 ? cfg::OFF_KS : cfg::OFF_VS) + ((size_t)(layer * 128 + (rs >> 2)) * 128 + 124 + (rs & 3)) * 128 + (tc & 127); }
;                                 if (w) *(f32x4*)(out + o) = v; }
	s_xor_b64 s[78:79], exec, s[78:79]
	s_mov_b64 s[70:71], exec
	v_add_u32_e32 v46, s87, v69
	s_or_saveexec_b64 s[78:79], s[78:79]
	v_mov_b64_e32 v[50:51], v[162:163]
	s_xor_b64 exec, exec, s[78:79]
	s_and_saveexec_b64 vcc, s[18:19]
	v_readlane_b32 s80, v254, 37
	v_readlane_b32 s81, v254, 38
	s_add_i32 s46, s53, s80
	s_or_b64 s[80:81], s[70:71], exec
	s_or_b64 exec, exec, vcc
	s_andn2_b64 s[70:71], s[70:71], exec
	s_and_b64 s[80:81], s[80:81], exec
	v_mov_b32_e32 v46, s46
	s_or_b64 s[70:71], s[70:71], s[80:81]
	v_mov_b64_e32 v[50:51], v[44:45]
	v_readlane_b32 s86, v254, 63
	v_readlane_b32 s87, v255, 0
	s_or_b64 exec, exec, s[78:79]
	s_and_saveexec_b64 s[78:79], s[70:71]
	v_ashrrev_i32_e32 v47, 31, v46
	v_lshl_add_u64 v[50:51], v[50:51], 2, v[156:157]
	v_lshlrev_b64 v[46:47], 16, v[46:47]
	v_lshl_add_u64 v[46:47], v[50:51], 0, v[46:47]
	global_store_dwordx4 v[46:47], v[40:43], off
	s_or_b64 exec, exec, s[78:79]
	v_mov_b64_e32 v[38:39], v[34:35]
	v_mov_b64_e32 v[36:37], v[32:33]
	v_mov_b32_e32 v46, v32
	v_mov_b32_e32 v50, v33
	v_mov_b32_e32 v47, v34
	v_mov_b32_e32 v51, v35
	s_andn2_b64 vcc, exec, s[96:97]
	v_lshl_add_u64 v[40:41], v[166:167], 0, v[54:55]
	v_cvt_pk_bf16_f32 v42, v46, v50
	v_cvt_pk_bf16_f32 v43, v47, v51
	global_store_dwordx2 v[40:41], v[42:43], off
	s_and_saveexec_b64 s[78:79], s[20:21]
	s_xor_b64 s[20:21], exec, s[78:79]
	s_mov_b64 s[70:71], exec
	v_add_u32_e32 v40, s87, v69
	s_or_saveexec_b64 s[20:21], s[20:21]
	v_mov_b64_e32 v[42:43], v[162:163]
	s_xor_b64 exec, exec, s[20:21]
	s_and_saveexec_b64 s[80:81], s[18:19]
	v_readlane_b32 s18, v254, 37
	s_add_i32 s46, s53, s18
	s_or_b64 s[78:79], s[70:71], exec
	v_readlane_b32 s19, v254, 38
	s_or_b64 exec, exec, s[80:81]
	s_andn2_b64 s[18:19], s[70:71], exec
	s_and_b64 s[70:71], s[78:79], exec
	v_mov_b32_e32 v40, s46
	s_or_b64 s[70:71], s[18:19], s[70:71]
	v_mov_b64_e32 v[42:43], v[44:45]
	s_or_b64 exec, exec, s[20:21]
	s_and_saveexec_b64 s[18:19], s[70:71]
	v_ashrrev_i32_e32 v41, 31, v40
	v_lshl_add_u64 v[42:43], v[42:43], 2, v[156:157]
	v_lshlrev_b64 v[40:41], 16, v[40:41]
	v_lshl_add_u64 v[40:41], v[42:43], 0, v[40:41]
	global_store_dwordx4 v[40:41], v[36:39], off offset:16
	s_or_b64 exec, exec, s[18:19]
	v_or_b32_e32 v32, 32, v68
	v_mad_i64_i32 v[42:43], s[18:19], v32, s61, 0
	s_movk_i32 s18, 0x3fff
	s_nop 0
	v_cmp_lt_i32_e64 s[20:21], s18, v32
	s_movk_i32 s18, 0x7ef
	v_bitop3_b32 v34, v68, s18, 32 bitop3:0xc8
	s_movk_i32 s18, 0x4000
	v_cmp_gt_i32_e32 vcc, s18, v32
	v_add_u32_e32 v96, 0xfffff880, v34
	v_ashrrev_i32_e32 v33, 31, v32
	v_cndmask_b32_e32 v35, v151, v34, vcc
	v_lshlrev_b32_e32 v53, 3, v35
	v_add_u32_e32 v35, 0xffffc020, v68
	s_movk_i32 s18, 0x77f
	v_lshlrev_b64 v[44:45], 7, v[96:97]
	s_mov_b64 s[70:71], 0x1080000
	v_lshlrev_b64 v[38:39], 8, v[32:33]
	v_lshrrev_b32_e32 v52, 2, v35
	v_cmp_lt_u32_e64 s[18:19], s18, v34
	v_lshl_add_u64 v[46:47], v[44:45], 0, s[70:71]
	v_lshlrev_b32_e32 v48, 2, v53
	global_load_dwordx4 v[208:211], v48, s[44:45]
	global_load_dwordx4 v[212:215], v48, s[4:5]
	global_load_dwordx4 v[216:219], v48, s[44:45] offset:16
	global_load_dwordx4 v[220:223], v48, s[4:5] offset:16
	v_mov_b32_e32 v54, v28
	v_mov_b32_e32 v55, v28
	s_nop 1
	v_permlane16_swap_b32_e32 v54, v55
	v_cndmask_b32_e64 v54, v54, v55, s[6:7]
	v_cndmask_b32_e64 v55, v54, -v54, s[10:11]
	v_mov_b32_e32 v56, v28
	s_waitcnt vmcnt(2)
	v_mov_b32_e32 v54, v208
	v_mov_b32_e32 v57, v212
	v_pk_mul_f32 v[54:55], v[56:57], v[54:55]
	v_mov_b32_e32 v48, v29
	v_add_f32_e32 v32, v54, v55
	v_mov_b32_e32 v54, v29
	s_nop 1
	v_permlane16_swap_b32_e32 v48, v54
	v_cndmask_b32_e64 v48, v48, v54, s[6:7]
	v_cndmask_b32_e64 v55, v48, -v48, s[10:11]
	v_mov_b32_e32 v48, v29
	v_mov_b32_e32 v54, v209
	v_mov_b32_e32 v49, v213
	v_pk_mul_f32 v[48:49], v[48:49], v[54:55]
	v_mov_b32_e32 v54, v30
	v_add_f32_e32 v33, v48, v49
	v_mov_b32_e32 v48, v30
	v_mov_b32_e32 v49, v30
	s_nop 1
	v_permlane16_swap_b32_e32 v48, v49
	v_cndmask_b32_e64 v48, v48, v49, s[6:7]
	v_cndmask_b32_e64 v49, v48, -v48, s[10:11]
	v_mov_b32_e32 v55, v214
	v_mov_b32_e32 v48, v210
	v_pk_mul_f32 v[48:49], v[54:55], v[48:49]
	v_mov_b32_e32 v50, v31
	v_add_f32_e32 v34, v48, v49
	v_mov_b32_e32 v48, v31
	v_mov_b32_e32 v49, v31
	s_nop 1
	v_permlane16_swap_b32_e32 v48, v49
	v_cndmask_b32_e64 v48, v48, v49, s[6:7]
	v_cndmask_b32_e64 v49, v48, -v48, s[10:11]
	v_mov_b32_e32 v48, v211
	v_mov_b32_e32 v51, v215
	v_pk_mul_f32 v[48:49], v[50:51], v[48:49]
	v_cndmask_b32_e64 v32, v28, v32, s[8:9]
	v_add_f32_e32 v35, v48, v49
	v_cndmask_b32_e64 v33, v29, v33, s[8:9]
	v_cndmask_b32_e64 v34, v30, v34, s[8:9]
	v_cndmask_b32_e64 v35, v31, v35, s[8:9]
	v_mov_b32_e32 v54, v32
	v_mov_b32_e32 v56, v33
	v_mov_b32_e32 v55, v34
	v_mov_b32_e32 v57, v35
	v_lshl_add_u64 v[48:49], v[154:155], 0, v[38:39]
	v_cvt_pk_bf16_f32 v50, v54, v56
	v_cvt_pk_bf16_f32 v51, v55, v57
	global_store_dwordx2 v[48:49], v[50:51], off
	s_and_saveexec_b64 s[78:79], s[20:21]
	s_xor_b64 s[78:79], exec, s[78:79]
	s_mov_b64 s[70:71], exec
	v_add_u32_e32 v48, s87, v52
	s_or_saveexec_b64 s[78:79], s[78:79]
	v_mov_b64_e32 v[50:51], v[160:161]
	s_xor_b64 exec, exec, s[78:79]
	s_and_saveexec_b64 vcc, s[18:19]
	v_readlane_b32 s80, v254, 37
	v_readlane_b32 s81, v254, 38
	s_add_i32 s46, s53, s80
	s_or_b64 s[80:81], s[70:71], exec
	s_or_b64 exec, exec, vcc
	s_andn2_b64 s[70:71], s[70:71], exec
	s_and_b64 s[80:81], s[80:81], exec
	v_mov_b32_e32 v48, s46
	s_or_b64 s[70:71], s[70:71], s[80:81]
	v_mov_b64_e32 v[50:51], v[46:47]
	v_readlane_b32 s86, v254, 63
	v_readlane_b32 s87, v255, 0
	s_or_b64 exec, exec, s[78:79]
	s_and_saveexec_b64 s[78:79], s[70:71]
	v_ashrrev_i32_e32 v49, 31, v48
	v_lshl_add_u64 v[50:51], v[50:51], 2, v[156:157]
	v_lshlrev_b64 v[48:49], 16, v[48:49]
	v_lshl_add_u64 v[48:49], v[50:51], 0, v[48:49]
	global_store_dwordx4 v[48:49], v[32:35], off
	s_or_b64 exec, exec, s[78:79]
	s_nop 0
	v_lshlrev_b32_e32 v34, 2, v53
	v_mov_b32_e32 v34, v24
	v_mov_b32_e32 v35, v24
	s_nop 1
	v_permlane16_swap_b32_e32 v34, v35
	v_cndmask_b32_e64 v34, v34, v35, s[6:7]
	v_cndmask_b32_e64 v35, v34, -v34, s[10:11]
	v_mov_b32_e32 v54, v24
	s_waitcnt vmcnt(1)
; __device__ __forceinline__ float shx16(float v, int odd  ) { const unsigned x = __builtin_bit_cast(unsigned, v); auto r = __builtin_amdgcn_permlane16_swap(x, x, false, false); return __builtin_bit_cast(float, odd ? r[0] : r[1]); }
; __device__ __forceinline__ void st_bf4(bf16_t* p, const f32x4 v) { u32x2 w; w.x = cvt_pk_bf16(v[0], v[1]); w.y = cvt_pk_bf16(v[2], v[3]); *(u32x2*)p = w; }
;     __device__ __forceinline__ void operator()(const f32x4 (&acc)[2][2][4][2], const Unit& u, int wr, int wc, int fr, int fq) const {
;     ...
;                     for (int n = 0; n < 2; ++n) { const int tc = bj * 128 + wc * 32 + 8 * fq + 4 * n; f32x4 v = acc[ai][bj][m][n];
;                         if (pn < 2) { *(f32x4*)(XA + (size_t)row * 512 + pn * 256 + tc) = v; }
;                         else if (pn <= 4) {
;                             const bool isv = (pn == 4 && bj == 1);
;                             if (!isv && (wc & 1) == 0) {
;                                 const int tix = row < cfg::MP ? (row & 2047) : 2048 + (row & 3);
;                                 const f32x4 cs = *(const f32x4*)(ropec + tix * 8 + 4 * n), sn = *(const f32x4*)(ropes + tix * 8 + 4 * n);
; #pragma unroll
;                                 for (int i = 0; i < 4; ++i) { const float p = shx16(v[i], fq & 1); const float rv = v[i] * cs[i] + (fq == 0 ? -p : p) * sn[i]; v[i] = fq < 2 ? rv : v[i]; }
;                             }
;                             if (pn < 4) st_bf4(Q + (size_t)row * 512 + (pn - 2) * 256 + tc, v);
;                             else { st_bf4((bj == 0 ? KB : VB) + (size_t)row * 128 + (tc & 127), v);
;                                 bool w = false; size_t o = 0;
;                                 if (row < cfg::MP) { const int t = row & 2047; if (t >= 1920) { w = true; o = (bj == 0 ? cfg::OFF_KP : cfg::OFF_VP) + ((size_t)(layer * 8 + (row >> 11)) * 128 + (t - 1920)) * 128 + (tc & 127); } }
;                                 else { const int rs = row - cfg::MP; w = true; o = (bj == 0 ? cfg::OFF_KS : cfg::OFF_VS) + ((size_t)(layer * 128 + (rs >> 2)) * 128 + 124 + (rs & 3)) * 128 + (tc & 127); }
;                                 if (w) *(f32x4*)(out + o) = v; }
	v_mov_b32_e32 v34, v216
	v_mov_b32_e32 v55, v220
	v_pk_mul_f32 v[34:35], v[54:55], v[34:35]
	v_mov_b32_e32 v48, v25
	v_add_f32_e32 v28, v34, v35
	v_mov_b32_e32 v34, v25
	v_mov_b32_e32 v35, v25
	s_nop 1
	v_permlane16_swap_b32_e32 v34, v35
	v_cndmask_b32_e64 v34, v34, v35, s[6:7]
	v_cndmask_b32_e64 v35, v34, -v34, s[10:11]
	v_mov_b32_e32 v34, v217
	v_mov_b32_e32 v49, v221
	v_pk_mul_f32 v[34:35], v[48:49], v[34:35]
	v_mov_b32_e32 v48, v26
	v_add_f32_e32 v29, v34, v35
	v_mov_b32_e32 v34, v26
	v_mov_b32_e32 v35, v26
	s_nop 1
	v_permlane16_swap_b32_e32 v34, v35
	v_cndmask_b32_e64 v34, v34, v35, s[6:7]
	v_cndmask_b32_e64 v35, v34, -v34, s[10:11]
	v_mov_b32_e32 v49, v222
	v_mov_b32_e32 v34, v218
	v_pk_mul_f32 v[34:35], v[48:49], v[34:35]
	v_mov_b32_e32 v50, v27
	v_add_f32_e32 v30, v34, v35
	v_mov_b32_e32 v34, v27
	v_mov_b32_e32 v35, v27
	s_nop 1
	v_permlane16_swap_b32_e32 v34, v35
	v_cndmask_b32_e64 v34, v34, v35, s[6:7]
	v_cndmask_b32_e64 v35, v34, -v34, s[10:11]
	v_mov_b32_e32 v34, v219
	v_mov_b32_e32 v51, v223
	v_pk_mul_f32 v[34:35], v[50:51], v[34:35]
	v_cndmask_b32_e64 v28, v24, v28, s[8:9]
	v_add_f32_e32 v31, v34, v35
	v_cndmask_b32_e64 v29, v25, v29, s[8:9]
	v_cndmask_b32_e64 v30, v26, v30, s[8:9]
	v_cndmask_b32_e64 v31, v27, v31, s[8:9]
	v_mov_b32_e32 v50, v28
	v_mov_b32_e32 v54, v29
	v_mov_b32_e32 v51, v30
	v_mov_b32_e32 v55, v31
	v_lshl_add_u64 v[34:35], v[164:165], 0, v[38:39]
	v_cvt_pk_bf16_f32 v48, v50, v54
	v_cvt_pk_bf16_f32 v49, v51, v55
	global_store_dwordx2 v[34:35], v[48:49], off
	s_and_saveexec_b64 s[78:79], s[20:21]
	s_xor_b64 s[78:79], exec, s[78:79]
	s_mov_b64 s[70:71], exec
	v_add_u32_e32 v34, s87, v52
	s_or_saveexec_b64 s[78:79], s[78:79]
	v_mov_b64_e32 v[48:49], v[160:161]
	s_xor_b64 exec, exec, s[78:79]
	s_and_saveexec_b64 vcc, s[18:19]
	v_readlane_b32 s80, v254, 37
	v_readlane_b32 s81, v254, 38
	s_add_i32 s46, s53, s80
	s_or_b64 s[80:81], s[70:71], exec
	s_or_b64 exec, exec, vcc
	s_andn2_b64 s[70:71], s[70:71], exec
	s_and_b64 s[80:81], s[80:81], exec
	v_mov_b32_e32 v34, s46
	s_or_b64 s[70:71], s[70:71], s[80:81]
	v_mov_b64_e32 v[48:49], v[46:47]
	v_readlane_b32 s86, v254, 63
	v_readlane_b32 s87, v255, 0
	s_or_b64 exec, exec, s[78:79]
	s_and_saveexec_b64 s[78:79], s[70:71]
	v_ashrrev_i32_e32 v35, 31, v34
	v_lshl_add_u64 v[46:47], v[48:49], 2, v[156:157]
	v_lshlrev_b64 v[34:35], 16, v[34:35]
	v_lshl_add_u64 v[34:35], v[46:47], 0, v[34:35]
	global_store_dwordx4 v[34:35], v[28:31], off offset:16
	s_or_b64 exec, exec, s[78:79]
	s_mov_b64 s[70:71], 0x1100000
	v_lshl_add_u64 v[28:29], v[44:45], 0, s[70:71]
	v_mov_b64_e32 v[26:27], v[22:23]
	v_mov_b64_e32 v[24:25], v[20:21]
	v_mov_b32_e32 v44, v20
	v_mov_b32_e32 v46, v21
	v_mov_b32_e32 v45, v22
	v_mov_b32_e32 v47, v23
	v_lshl_add_u64 v[30:31], v[158:159], 0, v[38:39]
	v_cvt_pk_bf16_f32 v34, v44, v46
	v_cvt_pk_bf16_f32 v35, v45, v47
	global_store_dwordx2 v[30:31], v[34:35], off
	s_and_saveexec_b64 s[78:79], s[20:21]
	s_xor_b64 s[78:79], exec, s[78:79]
	s_mov_b64 s[70:71], exec
	v_add_u32_e32 v30, s87, v52
	s_or_saveexec_b64 s[78:79], s[78:79]
	v_mov_b64_e32 v[34:35], v[162:163]
	s_xor_b64 exec, exec, s[78:79]
	s_and_saveexec_b64 vcc, s[18:19]
	v_readlane_b32 s80, v254, 37
	v_readlane_b32 s81, v254, 38
	s_add_i32 s46, s53, s80
	s_or_b64 s[80:81], s[70:71], exec
	s_or_b64 exec, exec, vcc
	s_andn2_b64 s[70:71], s[70:71], exec
	s_and_b64 s[80:81], s[80:81], exec
	v_mov_b32_e32 v30, s46
	s_or_b64 s[70:71], s[70:71], s[80:81]
	v_mov_b64_e32 v[34:35], v[28:29]
	v_readlane_b32 s86, v254, 63
	v_readlane_b32 s87, v255, 0
	s_or_b64 exec, exec, s[78:79]
	s_and_saveexec_b64 s[78:79], s[70:71]
	v_ashrrev_i32_e32 v31, 31, v30
	v_lshl_add_u64 v[34:35], v[34:35], 2, v[156:157]
	v_lshlrev_b64 v[30:31], 16, v[30:31]
	v_lshl_add_u64 v[30:31], v[34:35], 0, v[30:31]
	global_store_dwordx4 v[30:31], v[24:27], off
	s_or_b64 exec, exec, s[78:79]
	v_mov_b64_e32 v[22:23], v[18:19]
	v_mov_b64_e32 v[20:21], v[16:17]
	v_mov_b32_e32 v30, v16
	v_mov_b32_e32 v34, v17
	v_mov_b32_e32 v31, v18
	v_mov_b32_e32 v35, v19
	s_andn2_b64 vcc, exec, s[96:97]
	v_lshl_add_u64 v[24:25], v[166:167], 0, v[38:39]
	v_cvt_pk_bf16_f32 v26, v30, v34
	v_cvt_pk_bf16_f32 v27, v31, v35
	global_store_dwordx2 v[24:25], v[26:27], off
	s_and_saveexec_b64 s[78:79], s[20:21]
	s_xor_b64 s[20:21], exec, s[78:79]
	s_mov_b64 s[70:71], exec
	v_add_u32_e32 v24, s87, v52
	s_or_saveexec_b64 s[20:21], s[20:21]
	v_mov_b64_e32 v[26:27], v[162:163]
	s_xor_b64 exec, exec, s[20:21]
	s_and_saveexec_b64 s[80:81], s[18:19]
	v_readlane_b32 s18, v254, 37
	s_add_i32 s46, s53, s18
	s_or_b64 s[78:79], s[70:71], exec
	v_readlane_b32 s19, v254, 38
	s_or_b64 exec, exec, s[80:81]
	s_andn2_b64 s[18:19], s[70:71], exec
	s_and_b64 s[70:71], s[78:79], exec
	v_mov_b32_e32 v24, s46
	s_or_b64 s[70:71], s[18:19], s[70:71]
	v_mov_b64_e32 v[26:27], v[28:29]
	s_or_b64 exec, exec, s[20:21]
	s_and_saveexec_b64 s[18:19], s[70:71]
	v_ashrrev_i32_e32 v25, 31, v24
	v_lshl_add_u64 v[26:27], v[26:27], 2, v[156:157]
	v_lshlrev_b64 v[24:25], 16, v[24:25]
	v_lshl_add_u64 v[24:25], v[26:27], 0, v[24:25]
	global_store_dwordx4 v[24:25], v[20:23], off offset:16
	s_or_b64 exec, exec, s[18:19]
	v_or_b32_e32 v16, 48, v68
	v_mad_i64_i32 v[26:27], s[18:19], v16, s61, 0
	s_movk_i32 s18, 0x3fff
	s_nop 0
	v_cmp_lt_i32_e64 s[20:21], s18, v16
	s_movk_i32 s18, 0x7ff
	v_bitop3_b32 v18, v68, s18, 48 bitop3:0xc8
	s_movk_i32 s18, 0x4000
	v_cmp_gt_i32_e32 vcc, s18, v16
	v_add_u32_e32 v96, 0xfffff880, v18
	v_ashrrev_i32_e32 v17, 31, v16
	v_cndmask_b32_e32 v19, v151, v18, vcc
	v_lshlrev_b32_e32 v37, 3, v19
	v_add_u32_e32 v19, 0xffffc030, v68
	s_movk_i32 s18, 0x77f
	v_lshlrev_b64 v[28:29], 7, v[96:97]
	s_mov_b64 s[70:71], 0x1080000
	v_lshlrev_b64 v[24:25], 11, v[16:17]
	v_lshlrev_b64 v[22:23], 8, v[16:17]
	v_lshrrev_b32_e32 v36, 2, v19
	v_cmp_lt_u32_e64 s[18:19], s18, v18
	v_lshlrev_b64 v[20:21], 10, v[16:17]
	v_lshl_add_u64 v[30:31], v[28:29], 0, s[70:71]
	v_lshlrev_b32_e32 v32, 2, v37
	global_load_dwordx4 v[208:211], v32, s[44:45]
	global_load_dwordx4 v[212:215], v32, s[4:5]
	global_load_dwordx4 v[216:219], v32, s[44:45] offset:16
	global_load_dwordx4 v[220:223], v32, s[4:5] offset:16
	v_mov_b32_e32 v38, v12
	v_mov_b32_e32 v39, v12
	s_nop 1
	v_permlane16_swap_b32_e32 v38, v39
	v_cndmask_b32_e64 v38, v38, v39, s[6:7]
	v_cndmask_b32_e64 v39, v38, -v38, s[10:11]
	v_mov_b32_e32 v40, v12
	s_waitcnt vmcnt(2)
; __device__ __forceinline__ float shx16(float v, int odd  ) { const unsigned x = __builtin_bit_cast(unsigned, v); auto r = __builtin_amdgcn_permlane16_swap(x, x, false, false); return __builtin_bit_cast(float, odd ? r[0] : r[1]); }
; __device__ __forceinline__ void st_bf4(bf16_t* p, const f32x4 v) { u32x2 w; w.x = cvt_pk_bf16(v[0], v[1]); w.y = cvt_pk_bf16(v[2], v[3]); *(u32x2*)p = w; }
;     __device__ __forceinline__ void operator()(const f32x4 (&acc)[2][2][4][2], const Unit& u, int wr, int wc, int fr, int fq) const {
;     ...
;                     for (int n = 0; n < 2; ++n) { const int tc = bj * 128 + wc * 32 + 8 * fq + 4 * n; f32x4 v = acc[ai][bj][m][n];
;                         if (pn < 2) { *(f32x4*)(XA + (size_t)row * 512 + pn * 256 + tc) = v; }
;                         else if (pn <= 4) {
;                             const bool isv = (pn == 4 && bj == 1);
;                             if (!isv && (wc & 1) == 0) {
;                                 const int tix = row < cfg::MP ? (row & 2047) : 2048 + (row & 3);
;                                 const f32x4 cs = *(const f32x4*)(ropec + tix * 8 + 4 * n), sn = *(const f32x4*)(ropes + tix * 8 + 4 * n);
; #pragma unroll
;                                 for (int i = 0; i < 4; ++i) { const float p = shx16(v[i], fq & 1); const float rv = v[i] * cs[i] + (fq == 0 ? -p : p) * sn[i]; v[i] = fq < 2 ? rv : v[i]; }
;                             }
;                             if (pn < 4) st_bf4(Q + (size_t)row * 512 + (pn - 2) * 256 + tc, v);
;                             else { st_bf4((bj == 0 ? KB : VB) + (size_t)row * 128 + (tc & 127), v);
;                                 bool w = false; size_t o = 0;
;                                 if (row < cfg::MP) { const int t = row & 2047; if (t >= 1920) { w = true; o = (bj == 0 ? cfg::OFF_KP : cfg::OFF_VP) + ((size_t)(layer * 8 + (row >> 11)) * 128 + (t - 1920)) * 128 + (tc & 127); } }
;                                 else { const int rs = row - cfg::MP; w = true; o = (bj == 0 ? cfg::OFF_KS : cfg::OFF_VS) + ((size_t)(layer * 128 + (rs >> 2)) * 128 + 124 + (rs & 3)) * 128 + (tc & 127); }
;                                 if (w) *(f32x4*)(out + o) = v; }
	v_mov_b32_e32 v38, v208
	v_mov_b32_e32 v41, v212
	v_pk_mul_f32 v[38:39], v[40:41], v[38:39]
	v_mov_b32_e32 v32, v13
	v_add_f32_e32 v16, v38, v39
	v_mov_b32_e32 v38, v13
	s_nop 1
	v_permlane16_swap_b32_e32 v32, v38
	v_cndmask_b32_e64 v32, v32, v38, s[6:7]
	v_cndmask_b32_e64 v39, v32, -v32, s[10:11]
	v_mov_b32_e32 v32, v13
	v_mov_b32_e32 v38, v209
	v_mov_b32_e32 v33, v213
	v_pk_mul_f32 v[32:33], v[32:33], v[38:39]
	v_mov_b32_e32 v38, v14
	v_add_f32_e32 v17, v32, v33
	v_mov_b32_e32 v32, v14
	v_mov_b32_e32 v33, v14
	s_nop 1
	v_permlane16_swap_b32_e32 v32, v33
	v_cndmask_b32_e64 v32, v32, v33, s[6:7]
	v_cndmask_b32_e64 v33, v32, -v32, s[10:11]
	v_mov_b32_e32 v39, v214
	v_mov_b32_e32 v32, v210
	v_pk_mul_f32 v[32:33], v[38:39], v[32:33]
	v_mov_b32_e32 v34, v15
	v_add_f32_e32 v18, v32, v33
	v_mov_b32_e32 v32, v15
	v_mov_b32_e32 v33, v15
	s_nop 1
	v_permlane16_swap_b32_e32 v32, v33
	v_cndmask_b32_e64 v32, v32, v33, s[6:7]
	v_cndmask_b32_e64 v33, v32, -v32, s[10:11]
	v_mov_b32_e32 v32, v211
	v_mov_b32_e32 v35, v215
	v_pk_mul_f32 v[32:33], v[34:35], v[32:33]
	v_cndmask_b32_e64 v16, v12, v16, s[8:9]
	v_add_f32_e32 v19, v32, v33
	v_cndmask_b32_e64 v17, v13, v17, s[8:9]
	v_cndmask_b32_e64 v18, v14, v18, s[8:9]
	v_cndmask_b32_e64 v19, v15, v19, s[8:9]
	v_mov_b32_e32 v38, v16
	v_mov_b32_e32 v40, v17
	v_mov_b32_e32 v39, v18
	v_mov_b32_e32 v41, v19
	v_lshl_add_u64 v[32:33], v[154:155], 0, v[22:23]
	v_cvt_pk_bf16_f32 v34, v38, v40
	v_cvt_pk_bf16_f32 v35, v39, v41
	global_store_dwordx2 v[32:33], v[34:35], off
	s_and_saveexec_b64 s[78:79], s[20:21]
	s_xor_b64 s[78:79], exec, s[78:79]
	s_mov_b64 s[70:71], exec
	v_add_u32_e32 v32, s87, v36
	s_or_saveexec_b64 s[78:79], s[78:79]
	v_mov_b64_e32 v[34:35], v[160:161]
	s_xor_b64 exec, exec, s[78:79]
	s_and_saveexec_b64 vcc, s[18:19]
	v_readlane_b32 s80, v254, 37
	v_readlane_b32 s81, v254, 38
	s_add_i32 s46, s53, s80
	s_or_b64 s[80:81], s[70:71], exec
	s_or_b64 exec, exec, vcc
	s_andn2_b64 s[70:71], s[70:71], exec
	s_and_b64 s[80:81], s[80:81], exec
	v_mov_b32_e32 v32, s46
	s_or_b64 s[70:71], s[70:71], s[80:81]
	v_mov_b64_e32 v[34:35], v[30:31]
	v_readlane_b32 s86, v254, 63
	v_readlane_b32 s87, v255, 0
	s_or_b64 exec, exec, s[78:79]
	s_and_saveexec_b64 s[78:79], s[70:71]
	v_ashrrev_i32_e32 v33, 31, v32
	v_lshl_add_u64 v[34:35], v[34:35], 2, v[156:157]
	v_lshlrev_b64 v[32:33], 16, v[32:33]
	v_lshl_add_u64 v[32:33], v[34:35], 0, v[32:33]
	global_store_dwordx4 v[32:33], v[16:19], off
	s_or_b64 exec, exec, s[78:79]
	s_nop 0
	v_lshl_add_u64 v[16:17], s[30:31], 0, v[24:25]
	v_lshl_add_u64 v[16:17], s[92:93], 2, v[16:17]
	v_lshlrev_b32_e32 v18, 2, v37
	v_mov_b32_e32 v18, v8
	v_mov_b32_e32 v19, v8
	s_nop 1
	v_permlane16_swap_b32_e32 v18, v19
	v_cndmask_b32_e64 v18, v18, v19, s[6:7]
	v_cndmask_b32_e64 v19, v18, -v18, s[10:11]
	v_mov_b32_e32 v38, v8
	s_waitcnt vmcnt(1)
	v_mov_b32_e32 v18, v216
	v_mov_b32_e32 v39, v220
	v_pk_mul_f32 v[18:19], v[38:39], v[18:19]
	v_mov_b32_e32 v32, v9
	v_add_f32_e32 v12, v18, v19
	v_mov_b32_e32 v18, v9
	v_mov_b32_e32 v19, v9
	s_nop 1
	v_permlane16_swap_b32_e32 v18, v19
	v_cndmask_b32_e64 v18, v18, v19, s[6:7]
	v_cndmask_b32_e64 v19, v18, -v18, s[10:11]
	v_mov_b32_e32 v18, v217
	v_mov_b32_e32 v33, v221
	v_pk_mul_f32 v[18:19], v[32:33], v[18:19]
	v_mov_b32_e32 v32, v10
	v_add_f32_e32 v13, v18, v19
	v_mov_b32_e32 v18, v10
	v_mov_b32_e32 v19, v10
	s_nop 1
	v_permlane16_swap_b32_e32 v18, v19
	v_cndmask_b32_e64 v18, v18, v19, s[6:7]
	v_cndmask_b32_e64 v19, v18, -v18, s[10:11]
	v_mov_b32_e32 v33, v222
	v_mov_b32_e32 v18, v218
	v_pk_mul_f32 v[18:19], v[32:33], v[18:19]
	v_mov_b32_e32 v34, v11
	v_add_f32_e32 v14, v18, v19
	v_mov_b32_e32 v18, v11
	v_mov_b32_e32 v19, v11
	s_nop 1
	v_permlane16_swap_b32_e32 v18, v19
	v_cndmask_b32_e64 v18, v18, v19, s[6:7]
	v_cndmask_b32_e64 v19, v18, -v18, s[10:11]
	v_mov_b32_e32 v18, v219
	v_mov_b32_e32 v35, v223
	v_pk_mul_f32 v[18:19], v[34:35], v[18:19]
	v_cndmask_b32_e64 v12, v8, v12, s[8:9]
	v_add_f32_e32 v15, v18, v19
	v_cndmask_b32_e64 v13, v9, v13, s[8:9]
	v_cndmask_b32_e64 v14, v10, v14, s[8:9]
	v_cndmask_b32_e64 v15, v11, v15, s[8:9]
	v_mov_b32_e32 v34, v12
	v_mov_b32_e32 v38, v13
	v_mov_b32_e32 v35, v14
	v_mov_b32_e32 v39, v15
	v_lshl_add_u64 v[18:19], v[164:165], 0, v[22:23]
	v_cvt_pk_bf16_f32 v32, v34, v38
	v_cvt_pk_bf16_f32 v33, v35, v39
	global_store_dwordx2 v[18:19], v[32:33], off
	s_and_saveexec_b64 s[78:79], s[20:21]
	s_xor_b64 s[78:79], exec, s[78:79]
	s_mov_b64 s[70:71], exec
	v_add_u32_e32 v18, s87, v36
	s_or_saveexec_b64 s[78:79], s[78:79]
	v_mov_b64_e32 v[32:33], v[160:161]
	s_xor_b64 exec, exec, s[78:79]
	s_and_saveexec_b64 s[92:93], s[18:19]
	v_readlane_b32 s80, v254, 37
	v_readlane_b32 s81, v254, 38
	s_add_i32 s46, s53, s80
	s_or_b64 s[80:81], s[70:71], exec
	s_or_b64 exec, exec, s[92:93]
	s_andn2_b64 s[70:71], s[70:71], exec
	s_and_b64 s[80:81], s[80:81], exec
	v_mov_b32_e32 v18, s46
	s_or_b64 s[70:71], s[70:71], s[80:81]
	v_mov_b64_e32 v[32:33], v[30:31]
	v_readlane_b32 s86, v254, 63
	v_readlane_b32 s87, v255, 0
	s_or_b64 exec, exec, s[78:79]
	s_and_saveexec_b64 s[78:79], s[70:71]
	v_ashrrev_i32_e32 v19, 31, v18
	v_lshl_add_u64 v[30:31], v[32:33], 2, v[156:157]
	v_lshlrev_b64 v[18:19], 16, v[18:19]
	v_lshl_add_u64 v[18:19], v[30:31], 0, v[18:19]
	global_store_dwordx4 v[18:19], v[12:15], off offset:16
	s_or_b64 exec, exec, s[78:79]
	s_mov_b64 s[70:71], 0x1100000
	v_lshl_add_u64 v[12:13], v[28:29], 0, s[70:71]
	v_mov_b64_e32 v[10:11], v[6:7]
	v_mov_b64_e32 v[8:9], v[4:5]
	v_mov_b32_e32 v28, v4
	v_mov_b32_e32 v30, v5
	v_mov_b32_e32 v29, v6
	v_mov_b32_e32 v31, v7
	v_lshl_add_u64 v[14:15], v[158:159], 0, v[22:23]
	v_cvt_pk_bf16_f32 v18, v28, v30
; __device__ __forceinline__ float shx16(float v, int odd  ) { const unsigned x = __builtin_bit_cast(unsigned, v); auto r = __builtin_amdgcn_permlane16_swap(x, x, false, false); return __builtin_bit_cast(float, odd ? r[0] : r[1]); }
; __device__ __forceinline__ void st_bf4(bf16_t* p, const f32x4 v) { u32x2 w; w.x = cvt_pk_bf16(v[0], v[1]); w.y = cvt_pk_bf16(v[2], v[3]); *(u32x2*)p = w; }
;     __device__ __forceinline__ void operator()(const f32x4 (&acc)[2][2][4][2], const Unit& u, int wr, int wc, int fr, int fq) const {
;     ...
;                     for (int n = 0; n < 2; ++n) { const int tc = bj * 128 + wc * 32 + 8 * fq + 4 * n; f32x4 v = acc[ai][bj][m][n];
;                         if (pn < 2) { *(f32x4*)(XA + (size_t)row * 512 + pn * 256 + tc) = v; }
;                         else if (pn <= 4) {
;                             const bool isv = (pn == 4 && bj == 1);
;                             if (!isv && (wc & 1) == 0) {
;                                 const int tix = row < cfg::MP ? (row & 2047) : 2048 + (row & 3);
;                                 const f32x4 cs = *(const f32x4*)(ropec + tix * 8 + 4 * n), sn = *(const f32x4*)(ropes + tix * 8 + 4 * n);
; #pragma unroll
;                                 for (int i = 0; i < 4; ++i) { const float p = shx16(v[i], fq & 1); const float rv = v[i] * cs[i] + (fq == 0 ? -p : p) * sn[i]; v[i] = fq < 2 ? rv : v[i]; }
;                             }
;                             if (pn < 4) st_bf4(Q + (size_t)row * 512 + (pn - 2) * 256 + tc, v);
;                             else { st_bf4((bj == 0 ? KB : VB) + (size_t)row * 128 + (tc & 127), v);
;                                 bool w = false; size_t o = 0;
;                                 if (row < cfg::MP) { const int t = row & 2047; if (t >= 1920) { w = true; o = (bj == 0 ? cfg::OFF_KP : cfg::OFF_VP) + ((size_t)(layer * 8 + (row >> 11)) * 128 + (t - 1920)) * 128 + (tc & 127); } }
;                                 else { const int rs = row - cfg::MP; w = true; o = (bj == 0 ? cfg::OFF_KS : cfg::OFF_VS) + ((size_t)(layer * 128 + (rs >> 2)) * 128 + 124 + (rs & 3)) * 128 + (tc & 127); }
;                                 if (w) *(f32x4*)(out + o) = v; }
	v_cvt_pk_bf16_f32 v19, v29, v31
	global_store_dwordx2 v[14:15], v[18:19], off
	s_and_saveexec_b64 s[78:79], s[20:21]
	s_xor_b64 s[78:79], exec, s[78:79]
	s_mov_b64 s[70:71], exec
	v_add_u32_e32 v14, s87, v36
	s_or_saveexec_b64 s[78:79], s[78:79]
	v_mov_b64_e32 v[18:19], v[162:163]
	s_xor_b64 exec, exec, s[78:79]
	s_and_saveexec_b64 s[92:93], s[18:19]
	v_readlane_b32 s80, v254, 37
	v_readlane_b32 s81, v254, 38
	s_add_i32 s46, s53, s80
	s_or_b64 s[80:81], s[70:71], exec
	s_or_b64 exec, exec, s[92:93]
	s_andn2_b64 s[70:71], s[70:71], exec
	s_and_b64 s[80:81], s[80:81], exec
	v_mov_b32_e32 v14, s46
	s_or_b64 s[70:71], s[70:71], s[80:81]
	v_mov_b64_e32 v[18:19], v[12:13]
	v_readlane_b32 s86, v254, 63
	v_readlane_b32 s87, v255, 0
	s_or_b64 exec, exec, s[78:79]
	s_and_saveexec_b64 s[78:79], s[70:71]
	v_ashrrev_i32_e32 v15, 31, v14
	v_lshl_add_u64 v[18:19], v[18:19], 2, v[156:157]
	v_lshlrev_b64 v[14:15], 16, v[14:15]
	v_lshl_add_u64 v[14:15], v[18:19], 0, v[14:15]
	global_store_dwordx4 v[14:15], v[8:11], off
	s_or_b64 exec, exec, s[78:79]
	s_mov_b32 s70, 0x1200000
	s_mov_b32 s71, 0x1400000
	v_mov_b64_e32 v[6:7], v[2:3]
	v_mov_b64_e32 v[4:5], v[0:1]
	v_mov_b32_e32 v14, v0
	v_mov_b32_e32 v18, v1
	v_mov_b32_e32 v15, v2
	v_mov_b32_e32 v19, v3
	v_lshl_add_u64 v[8:9], v[166:167], 0, v[22:23]
	v_cvt_pk_bf16_f32 v10, v14, v18
	v_cvt_pk_bf16_f32 v11, v15, v19
	global_store_dwordx2 v[8:9], v[10:11], off
	s_and_saveexec_b64 s[16:17], s[20:21]
	s_xor_b64 s[16:17], exec, s[16:17]
	s_mov_b64 s[14:15], exec
	v_add_u32_e32 v8, s87, v36
	s_or_saveexec_b64 s[16:17], s[16:17]
	v_mov_b64_e32 v[10:11], v[162:163]
	s_xor_b64 exec, exec, s[16:17]
	s_and_saveexec_b64 s[28:29], s[18:19]
	v_readlane_b32 s18, v254, 37
	s_add_i32 s46, s53, s18
	s_or_b64 s[20:21], s[14:15], exec
	v_readlane_b32 s19, v254, 38
	s_or_b64 exec, exec, s[28:29]
	s_andn2_b64 s[14:15], s[14:15], exec
	s_and_b64 s[18:19], s[20:21], exec
	v_mov_b32_e32 v8, s46
	s_or_b64 s[14:15], s[14:15], s[18:19]
	v_mov_b64_e32 v[10:11], v[12:13]
	s_or_b64 exec, exec, s[16:17]
	s_and_saveexec_b64 s[16:17], s[14:15]
	v_ashrrev_i32_e32 v9, 31, v8
	v_lshl_add_u64 v[10:11], v[10:11], 2, v[156:157]
	v_lshlrev_b64 v[8:9], 16, v[8:9]
	v_lshl_add_u64 v[8:9], v[10:11], 0, v[8:9]
	global_store_dwordx4 v[8:9], v[4:7], off offset:16
	s_or_b64 exec, exec, s[16:17]
	s_branch .LBB0_1574
.Lsp_kv1:
	s_nop 7
	v_mov_b64_e32 v[132:133], v[128:129]
	v_mov_b64_e32 v[130:131], v[126:127]
	v_mov_b32_e32 v173, v126
	v_mov_b32_e32 v205, v127
	v_mov_b32_e32 v204, v128
	v_mov_b32_e32 v206, v129
	v_lshl_add_u64 v[146:147], v[154:155], 0, v[176:177]
	v_cvt_pk_bf16_f32 v148, v173, v205
	v_cvt_pk_bf16_f32 v149, v204, v206
	global_store_dwordx2 v[146:147], v[148:149], off
	s_and_saveexec_b64 s[16:17], s[20:21]
	s_xor_b64 s[16:17], exec, s[16:17]
	s_mov_b64 s[14:15], exec
	v_add_u32_e32 v186, s87, v202
	s_or_saveexec_b64 s[16:17], s[16:17]
	v_mov_b64_e32 v[188:189], v[160:161]
	s_xor_b64 exec, exec, s[16:17]
	s_and_saveexec_b64 s[80:81], s[18:19]
	v_readlane_b32 s86, v254, 37
	s_add_i32 vcc_lo, s75, s86
	s_or_b64 s[92:93], s[14:15], exec
	v_readlane_b32 s87, v254, 38
	s_or_b64 exec, exec, s[80:81]
	s_andn2_b64 s[14:15], s[14:15], exec
	s_and_b64 s[80:81], s[92:93], exec
	v_mov_b32_e32 v186, vcc_lo
	s_or_b64 s[14:15], s[14:15], s[80:81]
	v_mov_b64_e32 v[188:189], v[184:185]
	v_readlane_b32 s86, v254, 63
	v_readlane_b32 s87, v255, 0
	s_or_b64 exec, exec, s[16:17]
	s_and_saveexec_b64 s[16:17], s[14:15]
	v_ashrrev_i32_e32 v187, 31, v186
	v_lshl_add_u64 v[146:147], v[188:189], 2, v[156:157]
	v_lshlrev_b64 v[148:149], 16, v[186:187]
	v_lshl_add_u64 v[146:147], v[146:147], 0, v[148:149]
	global_store_dwordx4 v[146:147], v[130:133], off
	s_or_b64 exec, exec, s[16:17]
	s_ashr_i32 s93, s0, 31
	s_mov_b32 s92, s0
	v_lshlrev_b32_e32 v130, 2, v142
	v_mov_b64_e32 v[128:129], v[124:125]
	v_mov_b64_e32 v[126:127], v[122:123]
	v_mov_b32_e32 v131, v122
	v_mov_b32_e32 v204, v123
	v_mov_b32_e32 v173, v124
	v_mov_b32_e32 v205, v125
	v_lshl_add_u64 v[146:147], v[164:165], 0, v[176:177]
	v_cvt_pk_bf16_f32 v148, v131, v204
	v_cvt_pk_bf16_f32 v149, v173, v205
	global_store_dwordx2 v[146:147], v[148:149], off
	s_and_saveexec_b64 s[78:79], s[20:21]
	s_xor_b64 s[78:79], exec, s[78:79]
	s_mov_b64 s[70:71], exec
	v_add_u32_e32 v186, s87, v202
	s_or_saveexec_b64 s[78:79], s[78:79]
	v_mov_b64_e32 v[188:189], v[160:161]
	s_xor_b64 exec, exec, s[78:79]
	s_and_saveexec_b64 s[80:81], s[18:19]
	v_readlane_b32 s86, v254, 37
	s_add_i32 s46, s75, s86
	s_or_b64 vcc, s[70:71], exec
	v_readlane_b32 s87, v254, 38
	s_or_b64 exec, exec, s[80:81]
	s_andn2_b64 s[70:71], s[70:71], exec
	s_and_b64 s[80:81], vcc, exec
	v_mov_b32_e32 v186, s46
	s_or_b64 s[70:71], s[70:71], s[80:81]
	v_mov_b64_e32 v[188:189], v[184:185]
	v_readlane_b32 s86, v254, 63
	v_readlane_b32 s87, v255, 0
	s_or_b64 exec, exec, s[78:79]
	s_and_saveexec_b64 s[78:79], s[70:71]
	v_ashrrev_i32_e32 v187, 31, v186
	v_lshl_add_u64 v[146:147], v[188:189], 2, v[156:157]
	v_lshlrev_b64 v[148:149], 16, v[186:187]
	v_lshl_add_u64 v[146:147], v[146:147], 0, v[148:149]
	global_store_dwordx4 v[146:147], v[126:129], off offset:16
	s_or_b64 exec, exec, s[78:79]
	v_readlane_b32 s70, v254, 59
	v_readlane_b32 s71, v254, 60
	s_mov_b64 s[78:79], 0x1100000
	v_lshl_add_u64 v[126:127], v[182:183], 0, s[78:79]
	v_mov_b64_e32 v[124:125], v[120:121]
	v_mov_b64_e32 v[122:123], v[118:119]
	v_mov_b32_e32 v131, v118
	v_mov_b32_e32 v184, v119
	v_mov_b32_e32 v173, v120
	v_mov_b32_e32 v185, v121
	v_lshl_add_u64 v[128:129], v[158:159], 0, v[176:177]
	v_cvt_pk_bf16_f32 v146, v131, v184
	v_cvt_pk_bf16_f32 v147, v173, v185
	global_store_dwordx2 v[128:129], v[146:147], off
; __device__ __forceinline__ float shx16(float v, int odd  ) { const unsigned x = __builtin_bit_cast(unsigned, v); auto r = __builtin_amdgcn_permlane16_swap(x, x, false, false); return __builtin_bit_cast(float, odd ? r[0] : r[1]); }
; __device__ __forceinline__ void st_bf4(bf16_t* p, const f32x4 v) { u32x2 w; w.x = cvt_pk_bf16(v[0], v[1]); w.y = cvt_pk_bf16(v[2], v[3]); *(u32x2*)p = w; }
;     __device__ __forceinline__ void operator()(const f32x4 (&acc)[2][2][4][2], const Unit& u, int wr, int wc, int fr, int fq) const {
;     ...
;                     for (int n = 0; n < 2; ++n) { const int tc = bj * 128 + wc * 32 + 8 * fq + 4 * n; f32x4 v = acc[ai][bj][m][n];
;                         if (pn < 2) { *(f32x4*)(XA + (size_t)row * 512 + pn * 256 + tc) = v; }
;                         else if (pn <= 4) {
;                             const bool isv = (pn == 4 && bj == 1);
;                             if (!isv && (wc & 1) == 0) {
;                                 const int tix = row < cfg::MP ? (row & 2047) : 2048 + (row & 3);
;                                 const f32x4 cs = *(const f32x4*)(ropec + tix * 8 + 4 * n), sn = *(const f32x4*)(ropes + tix * 8 + 4 * n);
; #pragma unroll
;                                 for (int i = 0; i < 4; ++i) { const float p = shx16(v[i], fq & 1); const float rv = v[i] * cs[i] + (fq == 0 ? -p : p) * sn[i]; v[i] = fq < 2 ? rv : v[i]; }
;                             }
;                             if (pn < 4) st_bf4(Q + (size_t)row * 512 + (pn - 2) * 256 + tc, v);
;                             else { st_bf4((bj == 0 ? KB : VB) + (size_t)row * 128 + (tc & 127), v);
;                                 bool w = false; size_t o = 0;
;                                 if (row < cfg::MP) { const int t = row & 2047; if (t >= 1920) { w = true; o = (bj == 0 ? cfg::OFF_KP : cfg::OFF_VP) + ((size_t)(layer * 8 + (row >> 11)) * 128 + (t - 1920)) * 128 + (tc & 127); } }
;                                 else { const int rs = row - cfg::MP; w = true; o = (bj == 0 ? cfg::OFF_KS : cfg::OFF_VS) + ((size_t)(layer * 128 + (rs >> 2)) * 128 + 124 + (rs & 3)) * 128 + (tc & 127); }
;                                 if (w) *(f32x4*)(out + o) = v; }
	s_and_saveexec_b64 s[78:79], s[20:21]
	s_xor_b64 s[78:79], exec, s[78:79]
	s_mov_b64 s[70:71], exec
	v_add_u32_e32 v128, s87, v202
	s_or_saveexec_b64 s[78:79], s[78:79]
	v_mov_b64_e32 v[182:183], v[162:163]
	s_xor_b64 exec, exec, s[78:79]
	s_and_saveexec_b64 vcc, s[18:19]
	v_readlane_b32 s80, v254, 37
	v_readlane_b32 s81, v254, 38
	s_add_i32 s46, s75, s80
	s_or_b64 s[80:81], s[70:71], exec
	s_or_b64 exec, exec, vcc
	s_andn2_b64 s[70:71], s[70:71], exec
	s_and_b64 s[80:81], s[80:81], exec
	v_mov_b32_e32 v128, s46
	s_or_b64 s[70:71], s[70:71], s[80:81]
	v_mov_b64_e32 v[182:183], v[126:127]
	v_readlane_b32 s86, v254, 63
	v_readlane_b32 s87, v255, 0
	s_or_b64 exec, exec, s[78:79]
	s_and_saveexec_b64 s[78:79], s[70:71]
	v_ashrrev_i32_e32 v129, 31, v128
	v_lshl_add_u64 v[146:147], v[182:183], 2, v[156:157]
	v_lshlrev_b64 v[128:129], 16, v[128:129]
	v_lshl_add_u64 v[128:129], v[146:147], 0, v[128:129]
	global_store_dwordx4 v[128:129], v[122:125], off
	s_or_b64 exec, exec, s[78:79]
	v_mov_b64_e32 v[120:121], v[116:117]
	v_mov_b64_e32 v[118:119], v[114:115]
	v_mov_b32_e32 v128, v114
	v_mov_b32_e32 v131, v115
	v_mov_b32_e32 v129, v116
	v_mov_b32_e32 v173, v117
	s_andn2_b64 vcc, exec, s[96:97]
	v_lshl_add_u64 v[122:123], v[166:167], 0, v[176:177]
	v_cvt_pk_bf16_f32 v124, v128, v131
	v_cvt_pk_bf16_f32 v125, v129, v173
	global_store_dwordx2 v[122:123], v[124:125], off
	s_and_saveexec_b64 s[78:79], s[20:21]
	s_xor_b64 s[20:21], exec, s[78:79]
	s_mov_b64 s[70:71], exec
	v_add_u32_e32 v122, s87, v202
	s_or_saveexec_b64 s[20:21], s[20:21]
	v_mov_b64_e32 v[124:125], v[162:163]
	s_xor_b64 exec, exec, s[20:21]
	s_and_saveexec_b64 s[80:81], s[18:19]
	v_readlane_b32 s18, v254, 37
	s_add_i32 s46, s75, s18
	s_or_b64 s[78:79], s[70:71], exec
	v_readlane_b32 s19, v254, 38
	s_or_b64 exec, exec, s[80:81]
	s_andn2_b64 s[18:19], s[70:71], exec
	s_and_b64 s[70:71], s[78:79], exec
	v_mov_b32_e32 v122, s46
	s_or_b64 s[70:71], s[18:19], s[70:71]
	v_mov_b64_e32 v[124:125], v[126:127]
	s_or_b64 exec, exec, s[20:21]
	s_and_saveexec_b64 s[18:19], s[70:71]
	v_ashrrev_i32_e32 v123, 31, v122
	v_lshl_add_u64 v[124:125], v[124:125], 2, v[156:157]
	v_lshlrev_b64 v[122:123], 16, v[122:123]
	v_lshl_add_u64 v[122:123], v[124:125], 0, v[122:123]
	global_store_dwordx4 v[122:123], v[118:121], off offset:16
	s_or_b64 exec, exec, s[18:19]
	v_or_b32_e32 v114, 16, v172
	v_mad_i64_i32 v[124:125], s[18:19], v114, s61, 0
	s_movk_i32 s18, 0x3fff
	s_nop 0
	v_cmp_lt_i32_e64 s[20:21], s18, v114
	s_movk_i32 s18, 0x7df
	v_bitop3_b32 v96, v172, s18, 16 bitop3:0xc8
	s_movk_i32 s18, 0x4000
	v_cmp_gt_i32_e32 vcc, s18, v114
	s_movk_i32 s18, 0x77f
	v_cmp_lt_u32_e64 s[18:19], s18, v96
	v_cndmask_b32_e32 v116, v151, v96, vcc
	v_add_u32_e32 v96, 0xfffff880, v96
	v_ashrrev_i32_e32 v115, 31, v114
	v_lshlrev_b32_e32 v176, 3, v116
	v_add_u32_e32 v116, 0xffffc010, v172
	v_lshlrev_b64 v[126:127], 7, v[96:97]
	s_mov_b64 s[70:71], 0x1080000
	v_lshlrev_b64 v[120:121], 8, v[114:115]
	v_lshrrev_b32_e32 v173, 2, v116
	v_lshl_add_u64 v[128:129], v[126:127], 0, s[70:71]
	v_mov_b64_e32 v[116:117], v[112:113]
	v_mov_b64_e32 v[114:115], v[110:111]
	v_mov_b32_e32 v131, v110
	v_mov_b32_e32 v178, v111
	v_mov_b32_e32 v177, v112
	v_mov_b32_e32 v179, v113
	v_lshl_add_u64 v[132:133], v[154:155], 0, v[120:121]
	v_cvt_pk_bf16_f32 v146, v131, v178
	v_cvt_pk_bf16_f32 v147, v177, v179
	global_store_dwordx2 v[132:133], v[146:147], off
	s_and_saveexec_b64 s[78:79], s[20:21]
	s_xor_b64 s[78:79], exec, s[78:79]
	s_mov_b64 s[70:71], exec
	v_add_u32_e32 v132, s87, v173
	s_or_saveexec_b64 s[78:79], s[78:79]
	v_mov_b64_e32 v[174:175], v[160:161]
	s_xor_b64 exec, exec, s[78:79]
	s_and_saveexec_b64 vcc, s[18:19]
	v_readlane_b32 s80, v254, 37
	v_readlane_b32 s81, v254, 38
	s_add_i32 s46, s75, s80
	s_or_b64 s[80:81], s[70:71], exec
	s_or_b64 exec, exec, vcc
	s_andn2_b64 s[70:71], s[70:71], exec
	s_and_b64 s[80:81], s[80:81], exec
	v_mov_b32_e32 v132, s46
	s_or_b64 s[70:71], s[70:71], s[80:81]
	v_mov_b64_e32 v[174:175], v[128:129]
	v_readlane_b32 s86, v254, 63
	v_readlane_b32 s87, v255, 0
	s_or_b64 exec, exec, s[78:79]
	s_and_saveexec_b64 s[78:79], s[70:71]
	v_ashrrev_i32_e32 v133, 31, v132
	v_lshl_add_u64 v[146:147], v[174:175], 2, v[156:157]
	v_lshlrev_b64 v[132:133], 16, v[132:133]
	v_lshl_add_u64 v[132:133], v[146:147], 0, v[132:133]
	global_store_dwordx4 v[132:133], v[114:117], off
	s_or_b64 exec, exec, s[78:79]
	v_mov_b64_e32 v[112:113], v[108:109]
	v_mov_b64_e32 v[110:111], v[106:107]
	v_mov_b32_e32 v131, v106
	v_mov_b32_e32 v175, v107
	v_mov_b32_e32 v174, v108
	v_mov_b32_e32 v177, v109
	v_lshl_add_u64 v[116:117], v[164:165], 0, v[120:121]
	v_cvt_pk_bf16_f32 v132, v131, v175
	v_cvt_pk_bf16_f32 v133, v174, v177
	global_store_dwordx2 v[116:117], v[132:133], off
	s_and_saveexec_b64 s[78:79], s[20:21]
	s_xor_b64 s[78:79], exec, s[78:79]
	s_mov_b64 s[70:71], exec
	v_add_u32_e32 v116, s87, v173
	s_or_saveexec_b64 s[78:79], s[78:79]
	v_mov_b64_e32 v[132:133], v[160:161]
	s_xor_b64 exec, exec, s[78:79]
	s_and_saveexec_b64 vcc, s[18:19]
	v_readlane_b32 s80, v254, 37
	v_readlane_b32 s81, v254, 38
	s_add_i32 s46, s75, s80
	s_or_b64 s[80:81], s[70:71], exec
	s_or_b64 exec, exec, vcc
	s_andn2_b64 s[70:71], s[70:71], exec
	s_and_b64 s[80:81], s[80:81], exec
	v_mov_b32_e32 v116, s46
	s_or_b64 s[70:71], s[70:71], s[80:81]
	v_mov_b64_e32 v[132:133], v[128:129]
	v_readlane_b32 s86, v254, 63
	v_readlane_b32 s87, v255, 0
	s_or_b64 exec, exec, s[78:79]
	s_and_saveexec_b64 s[78:79], s[70:71]
	v_ashrrev_i32_e32 v117, 31, v116
	v_lshl_add_u64 v[128:129], v[132:133], 2, v[156:157]
	v_lshlrev_b64 v[116:117], 16, v[116:117]
	v_lshl_add_u64 v[116:117], v[128:129], 0, v[116:117]
; __device__ __forceinline__ float shx16(float v, int odd  ) { const unsigned x = __builtin_bit_cast(unsigned, v); auto r = __builtin_amdgcn_permlane16_swap(x, x, false, false); return __builtin_bit_cast(float, odd ? r[0] : r[1]); }
; __device__ __forceinline__ void st_bf4(bf16_t* p, const f32x4 v) { u32x2 w; w.x = cvt_pk_bf16(v[0], v[1]); w.y = cvt_pk_bf16(v[2], v[3]); *(u32x2*)p = w; }
;     __device__ __forceinline__ void operator()(const f32x4 (&acc)[2][2][4][2], const Unit& u, int wr, int wc, int fr, int fq) const {
;     ...
;                     for (int n = 0; n < 2; ++n) { const int tc = bj * 128 + wc * 32 + 8 * fq + 4 * n; f32x4 v = acc[ai][bj][m][n];
;                         if (pn < 2) { *(f32x4*)(XA + (size_t)row * 512 + pn * 256 + tc) = v; }
;                         else if (pn <= 4) {
;                             const bool isv = (pn == 4 && bj == 1);
;                             if (!isv && (wc & 1) == 0) {
;                                 const int tix = row < cfg::MP ? (row & 2047) : 2048 + (row & 3);
;                                 const f32x4 cs = *(const f32x4*)(ropec + tix * 8 + 4 * n), sn = *(const f32x4*)(ropes + tix * 8 + 4 * n);
; #pragma unroll
;                                 for (int i = 0; i < 4; ++i) { const float p = shx16(v[i], fq & 1); const float rv = v[i] * cs[i] + (fq == 0 ? -p : p) * sn[i]; v[i] = fq < 2 ? rv : v[i]; }
;                             }
;                             if (pn < 4) st_bf4(Q + (size_t)row * 512 + (pn - 2) * 256 + tc, v);
;                             else { st_bf4((bj == 0 ? KB : VB) + (size_t)row * 128 + (tc & 127), v);
;                                 bool w = false; size_t o = 0;
;                                 if (row < cfg::MP) { const int t = row & 2047; if (t >= 1920) { w = true; o = (bj == 0 ? cfg::OFF_KP : cfg::OFF_VP) + ((size_t)(layer * 8 + (row >> 11)) * 128 + (t - 1920)) * 128 + (tc & 127); } }
;                                 else { const int rs = row - cfg::MP; w = true; o = (bj == 0 ? cfg::OFF_KS : cfg::OFF_VS) + ((size_t)(layer * 128 + (rs >> 2)) * 128 + 124 + (rs & 3)) * 128 + (tc & 127); }
;                                 if (w) *(f32x4*)(out + o) = v; }
	global_store_dwordx4 v[116:117], v[110:113], off offset:16
	s_or_b64 exec, exec, s[78:79]
	s_mov_b64 s[70:71], 0x1100000
	v_lshl_add_u64 v[110:111], v[126:127], 0, s[70:71]
	v_mov_b64_e32 v[108:109], v[104:105]
	v_mov_b64_e32 v[106:107], v[102:103]
	v_mov_b32_e32 v126, v102
	v_mov_b32_e32 v128, v103
	v_mov_b32_e32 v127, v104
	v_mov_b32_e32 v129, v105
	v_lshl_add_u64 v[112:113], v[158:159], 0, v[120:121]
	v_cvt_pk_bf16_f32 v116, v126, v128
	v_cvt_pk_bf16_f32 v117, v127, v129
	global_store_dwordx2 v[112:113], v[116:117], off
	s_and_saveexec_b64 s[78:79], s[20:21]
	s_xor_b64 s[78:79], exec, s[78:79]
	s_mov_b64 s[70:71], exec
	v_add_u32_e32 v112, s87, v173
	s_or_saveexec_b64 s[78:79], s[78:79]
	v_mov_b64_e32 v[116:117], v[162:163]
	s_xor_b64 exec, exec, s[78:79]
	s_and_saveexec_b64 vcc, s[18:19]
	v_readlane_b32 s80, v254, 37
	v_readlane_b32 s81, v254, 38
	s_add_i32 s46, s75, s80
	s_or_b64 s[80:81], s[70:71], exec
	s_or_b64 exec, exec, vcc
	s_andn2_b64 s[70:71], s[70:71], exec
	s_and_b64 s[80:81], s[80:81], exec
	v_mov_b32_e32 v112, s46
	s_or_b64 s[70:71], s[70:71], s[80:81]
	v_mov_b64_e32 v[116:117], v[110:111]
	v_readlane_b32 s86, v254, 63
	v_readlane_b32 s87, v255, 0
	s_or_b64 exec, exec, s[78:79]
	s_and_saveexec_b64 s[78:79], s[70:71]
	v_ashrrev_i32_e32 v113, 31, v112
	v_lshl_add_u64 v[116:117], v[116:117], 2, v[156:157]
	v_lshlrev_b64 v[112:113], 16, v[112:113]
	v_lshl_add_u64 v[112:113], v[116:117], 0, v[112:113]
	global_store_dwordx4 v[112:113], v[106:109], off
	s_or_b64 exec, exec, s[78:79]
	v_mov_b64_e32 v[104:105], v[100:101]
	v_mov_b64_e32 v[102:103], v[98:99]
	v_mov_b32_e32 v112, v98
	v_mov_b32_e32 v116, v99
	v_mov_b32_e32 v113, v100
	v_mov_b32_e32 v117, v101
	s_andn2_b64 vcc, exec, s[96:97]
	v_lshl_add_u64 v[106:107], v[166:167], 0, v[120:121]
	v_cvt_pk_bf16_f32 v108, v112, v116
	v_cvt_pk_bf16_f32 v109, v113, v117
	global_store_dwordx2 v[106:107], v[108:109], off
	s_and_saveexec_b64 s[78:79], s[20:21]
	s_xor_b64 s[20:21], exec, s[78:79]
	s_mov_b64 s[70:71], exec
	v_add_u32_e32 v106, s87, v173
	s_or_saveexec_b64 s[20:21], s[20:21]
	v_mov_b64_e32 v[108:109], v[162:163]
	s_xor_b64 exec, exec, s[20:21]
	s_and_saveexec_b64 s[80:81], s[18:19]
	v_readlane_b32 s18, v254, 37
	s_add_i32 s46, s75, s18
	s_or_b64 s[78:79], s[70:71], exec
	v_readlane_b32 s19, v254, 38
	s_or_b64 exec, exec, s[80:81]
	s_andn2_b64 s[18:19], s[70:71], exec
	s_and_b64 s[70:71], s[78:79], exec
	v_mov_b32_e32 v106, s46
	s_or_b64 s[70:71], s[18:19], s[70:71]
	v_mov_b64_e32 v[108:109], v[110:111]
	s_or_b64 exec, exec, s[20:21]
	s_and_saveexec_b64 s[18:19], s[70:71]
	v_ashrrev_i32_e32 v107, 31, v106
	v_lshl_add_u64 v[108:109], v[108:109], 2, v[156:157]
	v_lshlrev_b64 v[106:107], 16, v[106:107]
	v_lshl_add_u64 v[106:107], v[108:109], 0, v[106:107]
	global_store_dwordx4 v[106:107], v[102:105], off offset:16
	s_or_b64 exec, exec, s[18:19]
	v_or_b32_e32 v98, 32, v172
	v_mad_i64_i32 v[108:109], s[18:19], v98, s61, 0
	s_movk_i32 s18, 0x3fff
	s_nop 0
	v_cmp_lt_i32_e64 s[20:21], s18, v98
	s_movk_i32 s18, 0x7ef
	v_bitop3_b32 v96, v172, s18, 32 bitop3:0xc8
	s_movk_i32 s18, 0x4000
	v_cmp_gt_i32_e32 vcc, s18, v98
	s_movk_i32 s18, 0x77f
	v_cmp_lt_u32_e64 s[18:19], s18, v96
	v_cndmask_b32_e32 v100, v151, v96, vcc
	v_add_u32_e32 v96, 0xfffff880, v96
	v_ashrrev_i32_e32 v99, 31, v98
	v_lshlrev_b32_e32 v119, 3, v100
	v_add_u32_e32 v100, 0xffffc020, v172
	v_lshlrev_b64 v[110:111], 7, v[96:97]
	s_mov_b64 s[70:71], 0x1080000
	v_lshlrev_b64 v[104:105], 8, v[98:99]
	v_lshrrev_b32_e32 v118, 2, v100
	v_lshl_add_u64 v[112:113], v[110:111], 0, s[70:71]
	v_mov_b64_e32 v[100:101], v[94:95]
	v_mov_b64_e32 v[98:99], v[92:93]
	v_mov_b32_e32 v120, v92
	v_mov_b32_e32 v122, v93
	v_mov_b32_e32 v121, v94
	v_mov_b32_e32 v123, v95
	v_lshl_add_u64 v[114:115], v[154:155], 0, v[104:105]
	v_cvt_pk_bf16_f32 v116, v120, v122
	v_cvt_pk_bf16_f32 v117, v121, v123
	global_store_dwordx2 v[114:115], v[116:117], off
	s_and_saveexec_b64 s[78:79], s[20:21]
	s_xor_b64 s[78:79], exec, s[78:79]
	s_mov_b64 s[70:71], exec
	v_add_u32_e32 v114, s87, v118
	s_or_saveexec_b64 s[78:79], s[78:79]
	v_mov_b64_e32 v[116:117], v[160:161]
	s_xor_b64 exec, exec, s[78:79]
	s_and_saveexec_b64 vcc, s[18:19]
	v_readlane_b32 s80, v254, 37
	v_readlane_b32 s81, v254, 38
	s_add_i32 s46, s75, s80
	s_or_b64 s[80:81], s[70:71], exec
	s_or_b64 exec, exec, vcc
	s_andn2_b64 s[70:71], s[70:71], exec
	s_and_b64 s[80:81], s[80:81], exec
	v_mov_b32_e32 v114, s46
	s_or_b64 s[70:71], s[70:71], s[80:81]
	v_mov_b64_e32 v[116:117], v[112:113]
	v_readlane_b32 s86, v254, 63
	v_readlane_b32 s87, v255, 0
	s_or_b64 exec, exec, s[78:79]
	s_and_saveexec_b64 s[78:79], s[70:71]
	v_ashrrev_i32_e32 v115, 31, v114
	v_lshl_add_u64 v[116:117], v[116:117], 2, v[156:157]
	v_lshlrev_b64 v[114:115], 16, v[114:115]
	v_lshl_add_u64 v[114:115], v[116:117], 0, v[114:115]
	global_store_dwordx4 v[114:115], v[98:101], off
	s_or_b64 exec, exec, s[78:79]
	v_mov_b64_e32 v[94:95], v[90:91]
	v_mov_b64_e32 v[92:93], v[88:89]
	v_mov_b32_e32 v116, v88
	v_mov_b32_e32 v120, v89
	v_mov_b32_e32 v117, v90
	v_mov_b32_e32 v121, v91
	v_lshl_add_u64 v[100:101], v[164:165], 0, v[104:105]
	v_cvt_pk_bf16_f32 v114, v116, v120
	v_cvt_pk_bf16_f32 v115, v117, v121
	global_store_dwordx2 v[100:101], v[114:115], off
	s_and_saveexec_b64 s[78:79], s[20:21]
	s_xor_b64 s[78:79], exec, s[78:79]
	s_mov_b64 s[70:71], exec
	v_add_u32_e32 v100, s87, v118
	s_or_saveexec_b64 s[78:79], s[78:79]
	v_mov_b64_e32 v[114:115], v[160:161]
	s_xor_b64 exec, exec, s[78:79]
	s_and_saveexec_b64 vcc, s[18:19]
	v_readlane_b32 s80, v254, 37
	v_readlane_b32 s81, v254, 38
	s_add_i32 s46, s75, s80
	s_or_b64 s[80:81], s[70:71], exec
; __device__ __forceinline__ float shx16(float v, int odd  ) { const unsigned x = __builtin_bit_cast(unsigned, v); auto r = __builtin_amdgcn_permlane16_swap(x, x, false, false); return __builtin_bit_cast(float, odd ? r[0] : r[1]); }
; __device__ __forceinline__ void st_bf4(bf16_t* p, const f32x4 v) { u32x2 w; w.x = cvt_pk_bf16(v[0], v[1]); w.y = cvt_pk_bf16(v[2], v[3]); *(u32x2*)p = w; }
;     __device__ __forceinline__ void operator()(const f32x4 (&acc)[2][2][4][2], const Unit& u, int wr, int wc, int fr, int fq) const {
;     ...
;                     for (int n = 0; n < 2; ++n) { const int tc = bj * 128 + wc * 32 + 8 * fq + 4 * n; f32x4 v = acc[ai][bj][m][n];
;                         if (pn < 2) { *(f32x4*)(XA + (size_t)row * 512 + pn * 256 + tc) = v; }
;                         else if (pn <= 4) {
;                             const bool isv = (pn == 4 && bj == 1);
;                             if (!isv && (wc & 1) == 0) {
;                                 const int tix = row < cfg::MP ? (row & 2047) : 2048 + (row & 3);
;                                 const f32x4 cs = *(const f32x4*)(ropec + tix * 8 + 4 * n), sn = *(const f32x4*)(ropes + tix * 8 + 4 * n);
; #pragma unroll
;                                 for (int i = 0; i < 4; ++i) { const float p = shx16(v[i], fq & 1); const float rv = v[i] * cs[i] + (fq == 0 ? -p : p) * sn[i]; v[i] = fq < 2 ? rv : v[i]; }
;                             }
;                             if (pn < 4) st_bf4(Q + (size_t)row * 512 + (pn - 2) * 256 + tc, v);
;                             else { st_bf4((bj == 0 ? KB : VB) + (size_t)row * 128 + (tc & 127), v);
;                                 bool w = false; size_t o = 0;
;                                 if (row < cfg::MP) { const int t = row & 2047; if (t >= 1920) { w = true; o = (bj == 0 ? cfg::OFF_KP : cfg::OFF_VP) + ((size_t)(layer * 8 + (row >> 11)) * 128 + (t - 1920)) * 128 + (tc & 127); } }
;                                 else { const int rs = row - cfg::MP; w = true; o = (bj == 0 ? cfg::OFF_KS : cfg::OFF_VS) + ((size_t)(layer * 128 + (rs >> 2)) * 128 + 124 + (rs & 3)) * 128 + (tc & 127); }
;                                 if (w) *(f32x4*)(out + o) = v; }
	s_or_b64 exec, exec, vcc
	s_andn2_b64 s[70:71], s[70:71], exec
	s_and_b64 s[80:81], s[80:81], exec
	v_mov_b32_e32 v100, s46
	s_or_b64 s[70:71], s[70:71], s[80:81]
	v_mov_b64_e32 v[114:115], v[112:113]
	v_readlane_b32 s86, v254, 63
	v_readlane_b32 s87, v255, 0
	s_or_b64 exec, exec, s[78:79]
	s_and_saveexec_b64 s[78:79], s[70:71]
	v_ashrrev_i32_e32 v101, 31, v100
	v_lshl_add_u64 v[112:113], v[114:115], 2, v[156:157]
	v_lshlrev_b64 v[100:101], 16, v[100:101]
	v_lshl_add_u64 v[100:101], v[112:113], 0, v[100:101]
	global_store_dwordx4 v[100:101], v[92:95], off offset:16
	s_or_b64 exec, exec, s[78:79]
	s_mov_b64 s[70:71], 0x1100000
	v_lshl_add_u64 v[92:93], v[110:111], 0, s[70:71]
	v_mov_b64_e32 v[90:91], v[86:87]
	v_mov_b64_e32 v[88:89], v[84:85]
	v_mov_b32_e32 v110, v84
	v_mov_b32_e32 v112, v85
	v_mov_b32_e32 v111, v86
	v_mov_b32_e32 v113, v87
	v_lshl_add_u64 v[94:95], v[158:159], 0, v[104:105]
	v_cvt_pk_bf16_f32 v100, v110, v112
	v_cvt_pk_bf16_f32 v101, v111, v113
	global_store_dwordx2 v[94:95], v[100:101], off
	s_and_saveexec_b64 s[78:79], s[20:21]
	s_xor_b64 s[78:79], exec, s[78:79]
	s_mov_b64 s[70:71], exec
	v_add_u32_e32 v94, s87, v118
	s_or_saveexec_b64 s[78:79], s[78:79]
	v_mov_b64_e32 v[100:101], v[162:163]
	s_xor_b64 exec, exec, s[78:79]
	s_and_saveexec_b64 vcc, s[18:19]
	v_readlane_b32 s80, v254, 37
	v_readlane_b32 s81, v254, 38
	s_add_i32 s46, s75, s80
	s_or_b64 s[80:81], s[70:71], exec
	s_or_b64 exec, exec, vcc
	s_andn2_b64 s[70:71], s[70:71], exec
	s_and_b64 s[80:81], s[80:81], exec
	v_mov_b32_e32 v94, s46
	s_or_b64 s[70:71], s[70:71], s[80:81]
	v_mov_b64_e32 v[100:101], v[92:93]
	v_readlane_b32 s86, v254, 63
	v_readlane_b32 s87, v255, 0
	s_or_b64 exec, exec, s[78:79]
	s_and_saveexec_b64 s[78:79], s[70:71]
	v_ashrrev_i32_e32 v95, 31, v94
	v_lshl_add_u64 v[100:101], v[100:101], 2, v[156:157]
	v_lshlrev_b64 v[94:95], 16, v[94:95]
	v_lshl_add_u64 v[94:95], v[100:101], 0, v[94:95]
	global_store_dwordx4 v[94:95], v[88:91], off
	s_or_b64 exec, exec, s[78:79]
	v_mov_b64_e32 v[86:87], v[82:83]
	v_mov_b64_e32 v[84:85], v[80:81]
	v_mov_b32_e32 v94, v80
	v_mov_b32_e32 v100, v81
	v_mov_b32_e32 v95, v82
	v_mov_b32_e32 v101, v83
	s_andn2_b64 vcc, exec, s[96:97]
	v_lshl_add_u64 v[88:89], v[166:167], 0, v[104:105]
	v_cvt_pk_bf16_f32 v90, v94, v100
	v_cvt_pk_bf16_f32 v91, v95, v101
	global_store_dwordx2 v[88:89], v[90:91], off
	s_and_saveexec_b64 s[78:79], s[20:21]
	s_xor_b64 s[20:21], exec, s[78:79]
	s_mov_b64 s[70:71], exec
	v_add_u32_e32 v88, s87, v118
	s_or_saveexec_b64 s[20:21], s[20:21]
	v_mov_b64_e32 v[90:91], v[162:163]
	s_xor_b64 exec, exec, s[20:21]
	s_and_saveexec_b64 s[80:81], s[18:19]
	v_readlane_b32 s18, v254, 37
	s_add_i32 s46, s75, s18
	s_or_b64 s[78:79], s[70:71], exec
	v_readlane_b32 s19, v254, 38
	s_or_b64 exec, exec, s[80:81]
	s_andn2_b64 s[18:19], s[70:71], exec
	s_and_b64 s[70:71], s[78:79], exec
	v_mov_b32_e32 v88, s46
	s_or_b64 s[70:71], s[18:19], s[70:71]
	v_mov_b64_e32 v[90:91], v[92:93]
	s_or_b64 exec, exec, s[20:21]
	s_and_saveexec_b64 s[18:19], s[70:71]
	v_ashrrev_i32_e32 v89, 31, v88
	v_lshl_add_u64 v[90:91], v[90:91], 2, v[156:157]
	v_lshlrev_b64 v[88:89], 16, v[88:89]
	v_lshl_add_u64 v[88:89], v[90:91], 0, v[88:89]
	global_store_dwordx4 v[88:89], v[84:87], off offset:16
	s_or_b64 exec, exec, s[18:19]
	v_or_b32_e32 v80, 48, v172
	v_mad_i64_i32 v[90:91], s[18:19], v80, s61, 0
	s_movk_i32 s18, 0x3fff
	s_nop 0
	v_cmp_lt_i32_e64 s[20:21], s18, v80
	s_movk_i32 s18, 0x7ff
	v_bitop3_b32 v82, v172, s18, 48 bitop3:0xc8
	s_movk_i32 s18, 0x4000
	v_cmp_gt_i32_e32 vcc, s18, v80
	v_add_u32_e32 v96, 0xfffff880, v82
	v_ashrrev_i32_e32 v81, 31, v80
	v_cndmask_b32_e32 v83, v151, v82, vcc
	v_lshlrev_b32_e32 v103, 3, v83
	v_add_u32_e32 v83, 0xffffc030, v172
	s_movk_i32 s18, 0x77f
	v_lshlrev_b64 v[92:93], 7, v[96:97]
	s_mov_b64 s[70:71], 0x1080000
	v_lshlrev_b64 v[86:87], 8, v[80:81]
	v_lshrrev_b32_e32 v102, 2, v83
	v_cmp_lt_u32_e64 s[18:19], s18, v82
	v_lshl_add_u64 v[94:95], v[92:93], 0, s[70:71]
	v_mov_b64_e32 v[82:83], v[78:79]
	v_mov_b64_e32 v[80:81], v[76:77]
	v_mov_b32_e32 v104, v76
	v_mov_b32_e32 v106, v77
	v_mov_b32_e32 v105, v78
	v_mov_b32_e32 v107, v79
	v_lshl_add_u64 v[98:99], v[154:155], 0, v[86:87]
	v_cvt_pk_bf16_f32 v100, v104, v106
	v_cvt_pk_bf16_f32 v101, v105, v107
	global_store_dwordx2 v[98:99], v[100:101], off
	s_and_saveexec_b64 s[78:79], s[20:21]
	s_xor_b64 s[78:79], exec, s[78:79]
	s_mov_b64 s[70:71], exec
	v_add_u32_e32 v98, s87, v102
	s_or_saveexec_b64 s[78:79], s[78:79]
	v_mov_b64_e32 v[100:101], v[160:161]
	s_xor_b64 exec, exec, s[78:79]
	s_and_saveexec_b64 vcc, s[18:19]
	v_readlane_b32 s80, v254, 37
	v_readlane_b32 s81, v254, 38
	s_add_i32 s46, s75, s80
	s_or_b64 s[80:81], s[70:71], exec
	s_or_b64 exec, exec, vcc
	s_andn2_b64 s[70:71], s[70:71], exec
	s_and_b64 s[80:81], s[80:81], exec
	v_mov_b32_e32 v98, s46
	s_or_b64 s[70:71], s[70:71], s[80:81]
	v_mov_b64_e32 v[100:101], v[94:95]
	v_readlane_b32 s86, v254, 63
	v_readlane_b32 s87, v255, 0
	s_or_b64 exec, exec, s[78:79]
	s_and_saveexec_b64 s[78:79], s[70:71]
	v_ashrrev_i32_e32 v99, 31, v98
	v_lshl_add_u64 v[100:101], v[100:101], 2, v[156:157]
	v_lshlrev_b64 v[98:99], 16, v[98:99]
	v_lshl_add_u64 v[98:99], v[100:101], 0, v[98:99]
	global_store_dwordx4 v[98:99], v[80:83], off
	s_or_b64 exec, exec, s[78:79]
	v_mov_b64_e32 v[78:79], v[74:75]
	v_mov_b64_e32 v[76:77], v[72:73]
	v_mov_b32_e32 v100, v72
	v_mov_b32_e32 v104, v73
	v_mov_b32_e32 v101, v74
	v_mov_b32_e32 v105, v75
	v_lshl_add_u64 v[82:83], v[164:165], 0, v[86:87]
	v_cvt_pk_bf16_f32 v98, v100, v104
	v_cvt_pk_bf16_f32 v99, v101, v105
	global_store_dwordx2 v[82:83], v[98:99], off
	s_and_saveexec_b64 s[78:79], s[20:21]
; __device__ __forceinline__ float shx16(float v, int odd  ) { const unsigned x = __builtin_bit_cast(unsigned, v); auto r = __builtin_amdgcn_permlane16_swap(x, x, false, false); return __builtin_bit_cast(float, odd ? r[0] : r[1]); }
;     __device__ __forceinline__ void operator()(const f32x4 (&acc)[2][2][4][2], const Unit& u, int wr, int wc, int fr, int fq) const {
;     ...
;         for (int ai = 0; ai < 2; ++ai)
; #pragma unroll
;             for (int m = 0; m < 4; ++m) { const int row = u.pm * 256 + ai * 128 + wr * 64 + m * 16 + fr;
; #pragma unroll
;                 for (int bj = 0; bj < 2; ++bj)
; #pragma unroll
;                     for (int n = 0; n < 2; ++n) { const int tc = bj * 128 + wc * 32 + 8 * fq + 4 * n; f32x4 v = acc[ai][bj][m][n];
;                         if (pn < 2) { *(f32x4*)(XA + (size_t)row * 512 + pn * 256 + tc) = v; }
;                         else if (pn <= 4) {
;                             const bool isv = (pn == 4 && bj == 1);
;                             if (!isv && (wc & 1) == 0) {
;                                 const int tix = row < cfg::MP ? (row & 2047) : 2048 + (row & 3);
;                                 const f32x4 cs = *(const f32x4*)(ropec + tix * 8 + 4 * n), sn = *(const f32x4*)(ropes + tix * 8 + 4 * n);
; #pragma unroll
;                                 for (int i = 0; i < 4; ++i) { const float p = shx16(v[i], fq & 1); const float rv = v[i] * cs[i] + (fq == 0 ? -p : p) * sn[i]; v[i] = fq < 2 ? rv : v[i]; }
;                             }
;                             if (pn < 4) st_bf4(Q + (size_t)row * 512 + (pn - 2) * 256 + tc, v);
;                             else { st_bf4((bj == 0 ? KB : VB) + (size_t)row * 128 + (tc & 127), v);
;                                 bool w = false; size_t o = 0;
;                                 if (row < cfg::MP) { const int t = row & 2047; if (t >= 1920) { w = true; o = (bj == 0 ? cfg::OFF_KP : cfg::OFF_VP) + ((size_t)(layer * 8 + (row >> 11)) * 128 + (t - 1920)) * 128 + (tc & 127); } }
;                                 else { const int rs = row - cfg::MP; w = true; o = (bj == 0 ? cfg::OFF_KS : cfg::OFF_VS) + ((size_t)(layer * 128 + (rs >> 2)) * 128 + 124 + (rs & 3)) * 128 + (tc & 127); }
;                                 if (w) *(f32x4*)(out + o) = v; }
	s_xor_b64 s[78:79], exec, s[78:79]
	s_mov_b64 s[70:71], exec
	v_add_u32_e32 v82, s87, v102
	s_or_saveexec_b64 s[78:79], s[78:79]
	v_mov_b64_e32 v[98:99], v[160:161]
	s_xor_b64 exec, exec, s[78:79]
	s_and_saveexec_b64 vcc, s[18:19]
	v_readlane_b32 s80, v254, 37
	v_readlane_b32 s81, v254, 38
	s_add_i32 s46, s75, s80
	s_or_b64 s[80:81], s[70:71], exec
	s_or_b64 exec, exec, vcc
	s_andn2_b64 s[70:71], s[70:71], exec
	s_and_b64 s[80:81], s[80:81], exec
	v_mov_b32_e32 v82, s46
	s_or_b64 s[70:71], s[70:71], s[80:81]
	v_mov_b64_e32 v[98:99], v[94:95]
	v_readlane_b32 s86, v254, 63
	v_readlane_b32 s87, v255, 0
	s_or_b64 exec, exec, s[78:79]
	s_and_saveexec_b64 s[78:79], s[70:71]
	v_ashrrev_i32_e32 v83, 31, v82
	v_lshl_add_u64 v[94:95], v[98:99], 2, v[156:157]
	v_lshlrev_b64 v[82:83], 16, v[82:83]
	v_lshl_add_u64 v[82:83], v[94:95], 0, v[82:83]
	global_store_dwordx4 v[82:83], v[76:79], off offset:16
	s_or_b64 exec, exec, s[78:79]
	s_mov_b64 s[70:71], 0x1100000
	v_lshl_add_u64 v[76:77], v[92:93], 0, s[70:71]
	v_mov_b64_e32 v[74:75], v[70:71]
	v_mov_b64_e32 v[72:73], v[68:69]
	v_mov_b32_e32 v92, v68
	v_mov_b32_e32 v94, v69
	v_mov_b32_e32 v93, v70
	v_mov_b32_e32 v95, v71
	v_lshl_add_u64 v[78:79], v[158:159], 0, v[86:87]
	v_cvt_pk_bf16_f32 v82, v92, v94
	v_cvt_pk_bf16_f32 v83, v93, v95
	global_store_dwordx2 v[78:79], v[82:83], off
	s_and_saveexec_b64 s[78:79], s[20:21]
	s_xor_b64 s[78:79], exec, s[78:79]
	s_mov_b64 s[70:71], exec
	v_add_u32_e32 v78, s87, v102
	s_or_saveexec_b64 s[78:79], s[78:79]
	v_mov_b64_e32 v[82:83], v[162:163]
	s_xor_b64 exec, exec, s[78:79]
	s_and_saveexec_b64 vcc, s[18:19]
	v_readlane_b32 s80, v254, 37
	v_readlane_b32 s81, v254, 38
	s_add_i32 s46, s75, s80
	s_or_b64 s[80:81], s[70:71], exec
	s_or_b64 exec, exec, vcc
	s_andn2_b64 s[70:71], s[70:71], exec
	s_and_b64 s[80:81], s[80:81], exec
	v_mov_b32_e32 v78, s46
	s_or_b64 s[70:71], s[70:71], s[80:81]
	v_mov_b64_e32 v[82:83], v[76:77]
	v_readlane_b32 s86, v254, 63
	v_readlane_b32 s87, v255, 0
	s_or_b64 exec, exec, s[78:79]
	s_and_saveexec_b64 s[78:79], s[70:71]
	v_ashrrev_i32_e32 v79, 31, v78
	v_lshl_add_u64 v[82:83], v[82:83], 2, v[156:157]
	v_lshlrev_b64 v[78:79], 16, v[78:79]
	v_lshl_add_u64 v[78:79], v[82:83], 0, v[78:79]
	global_store_dwordx4 v[78:79], v[72:75], off
	s_or_b64 exec, exec, s[78:79]
	v_mov_b64_e32 v[70:71], v[66:67]
	v_mov_b64_e32 v[68:69], v[64:65]
	v_mov_b32_e32 v78, v64
	v_mov_b32_e32 v82, v65
	v_mov_b32_e32 v79, v66
	v_mov_b32_e32 v83, v67
	s_andn2_b64 vcc, exec, s[96:97]
	v_lshl_add_u64 v[72:73], v[166:167], 0, v[86:87]
	v_cvt_pk_bf16_f32 v74, v78, v82
	v_cvt_pk_bf16_f32 v75, v79, v83
	global_store_dwordx2 v[72:73], v[74:75], off
	s_and_saveexec_b64 s[78:79], s[20:21]
	s_xor_b64 s[20:21], exec, s[78:79]
	s_mov_b64 s[70:71], exec
	v_add_u32_e32 v72, s87, v102
	s_or_saveexec_b64 s[20:21], s[20:21]
	v_mov_b64_e32 v[74:75], v[162:163]
	s_xor_b64 exec, exec, s[20:21]
	s_and_saveexec_b64 s[80:81], s[18:19]
	v_readlane_b32 s18, v254, 37
	s_add_i32 s46, s75, s18
	s_or_b64 s[78:79], s[70:71], exec
	v_readlane_b32 s19, v254, 38
	s_or_b64 exec, exec, s[80:81]
	s_andn2_b64 s[18:19], s[70:71], exec
	s_and_b64 s[70:71], s[78:79], exec
	v_mov_b32_e32 v72, s46
	s_or_b64 s[70:71], s[18:19], s[70:71]
	v_mov_b64_e32 v[74:75], v[76:77]
	s_or_b64 exec, exec, s[20:21]
	s_and_saveexec_b64 s[18:19], s[70:71]
	v_ashrrev_i32_e32 v73, 31, v72
	v_lshl_add_u64 v[74:75], v[74:75], 2, v[156:157]
	v_lshlrev_b64 v[72:73], 16, v[72:73]
	v_lshl_add_u64 v[72:73], v[74:75], 0, v[72:73]
	global_store_dwordx4 v[72:73], v[68:71], off offset:16
	s_or_b64 exec, exec, s[18:19]
	s_add_i32 s46, s53, 0x80
	v_or_b32_e32 v68, s46, v143
	v_mad_i64_i32 v[76:77], s[18:19], v68, s61, 0
	s_movk_i32 s18, 0x3fff
	s_nop 0
	v_cmp_lt_i32_e64 s[20:21], s18, v68
	v_mov_b32_e32 v64, 0x7cf
	s_movk_i32 s18, 0x4000
	v_bitop3_b32 v64, s46, v64, v143 bitop3:0xc8
	v_cmp_gt_i32_e32 vcc, s18, v68
	v_add_u32_e32 v96, 0xfffff880, v64
	v_ashrrev_i32_e32 v69, 31, v68
	v_cndmask_b32_e32 v65, v151, v64, vcc
	v_lshlrev_b32_e32 v87, 3, v65
	v_add_u32_e32 v65, 0xffffc000, v68
	s_movk_i32 s18, 0x77f
	v_lshlrev_b64 v[78:79], 7, v[96:97]
	s_mov_b64 s[70:71], 0x1080000
	s_ashr_i32 s53, s46, 11
	v_lshlrev_b64 v[74:75], 11, v[68:69]
	v_lshlrev_b64 v[72:73], 8, v[68:69]
	v_lshrrev_b32_e32 v86, 2, v65
	v_cmp_lt_u32_e64 s[18:19], s18, v64
	v_lshl_add_u64 v[80:81], v[78:79], 0, s[70:71]
	s_mov_b32 s75, 0x400000
	v_mov_b64_e32 v[66:67], v[62:63]
	v_mov_b64_e32 v[64:65], v[60:61]
	v_mov_b32_e32 v69, v60
	v_mov_b32_e32 v89, v61
	v_mov_b32_e32 v88, v62
	v_mov_b32_e32 v90, v63
	v_lshl_add_u64 v[82:83], v[154:155], 0, v[72:73]
	v_cvt_pk_bf16_f32 v84, v69, v89
	v_cvt_pk_bf16_f32 v85, v88, v90
	global_store_dwordx2 v[82:83], v[84:85], off
	s_and_saveexec_b64 s[78:79], s[20:21]
	s_xor_b64 s[78:79], exec, s[78:79]
	s_mov_b64 s[70:71], exec
	v_add_u32_e32 v82, s87, v86
	s_or_saveexec_b64 s[78:79], s[78:79]
	v_mov_b64_e32 v[84:85], v[160:161]
	s_xor_b64 exec, exec, s[78:79]
	s_and_saveexec_b64 vcc, s[18:19]
	v_readlane_b32 s80, v254, 37
	v_readlane_b32 s81, v254, 38
	s_add_i32 s46, s53, s80
	s_or_b64 s[80:81], s[70:71], exec
	s_or_b64 exec, exec, vcc
	s_andn2_b64 s[70:71], s[70:71], exec
	s_and_b64 s[80:81], s[80:81], exec
	v_mov_b32_e32 v82, s46
	s_or_b64 s[70:71], s[70:71], s[80:81]
	v_mov_b64_e32 v[84:85], v[80:81]
	v_readlane_b32 s86, v254, 63
	v_readlane_b32 s87, v255, 0
	s_or_b64 exec, exec, s[78:79]
	s_and_saveexec_b64 s[78:79], s[70:71]
	v_ashrrev_i32_e32 v83, 31, v82
	v_lshl_add_u64 v[84:85], v[84:85], 2, v[156:157]
	v_lshlrev_b64 v[82:83], 16, v[82:83]
	v_lshl_add_u64 v[82:83], v[84:85], 0, v[82:83]
	global_store_dwordx4 v[82:83], v[64:67], off
; __device__ __forceinline__ float shx16(float v, int odd  ) { const unsigned x = __builtin_bit_cast(unsigned, v); auto r = __builtin_amdgcn_permlane16_swap(x, x, false, false); return __builtin_bit_cast(float, odd ? r[0] : r[1]); }
; __device__ __forceinline__ void st_bf4(bf16_t* p, const f32x4 v) { u32x2 w; w.x = cvt_pk_bf16(v[0], v[1]); w.y = cvt_pk_bf16(v[2], v[3]); *(u32x2*)p = w; }
;     __device__ __forceinline__ void operator()(const f32x4 (&acc)[2][2][4][2], const Unit& u, int wr, int wc, int fr, int fq) const {
;     ...
;                     for (int n = 0; n < 2; ++n) { const int tc = bj * 128 + wc * 32 + 8 * fq + 4 * n; f32x4 v = acc[ai][bj][m][n];
;                         if (pn < 2) { *(f32x4*)(XA + (size_t)row * 512 + pn * 256 + tc) = v; }
;                         else if (pn <= 4) {
;                             const bool isv = (pn == 4 && bj == 1);
;                             if (!isv && (wc & 1) == 0) {
;                                 const int tix = row < cfg::MP ? (row & 2047) : 2048 + (row & 3);
;                                 const f32x4 cs = *(const f32x4*)(ropec + tix * 8 + 4 * n), sn = *(const f32x4*)(ropes + tix * 8 + 4 * n);
; #pragma unroll
;                                 for (int i = 0; i < 4; ++i) { const float p = shx16(v[i], fq & 1); const float rv = v[i] * cs[i] + (fq == 0 ? -p : p) * sn[i]; v[i] = fq < 2 ? rv : v[i]; }
;                             }
;                             if (pn < 4) st_bf4(Q + (size_t)row * 512 + (pn - 2) * 256 + tc, v);
;                             else { st_bf4((bj == 0 ? KB : VB) + (size_t)row * 128 + (tc & 127), v);
;                                 bool w = false; size_t o = 0;
;                                 if (row < cfg::MP) { const int t = row & 2047; if (t >= 1920) { w = true; o = (bj == 0 ? cfg::OFF_KP : cfg::OFF_VP) + ((size_t)(layer * 8 + (row >> 11)) * 128 + (t - 1920)) * 128 + (tc & 127); } }
;                                 else { const int rs = row - cfg::MP; w = true; o = (bj == 0 ? cfg::OFF_KS : cfg::OFF_VS) + ((size_t)(layer * 128 + (rs >> 2)) * 128 + 124 + (rs & 3)) * 128 + (tc & 127); }
;                                 if (w) *(f32x4*)(out + o) = v; }
	s_or_b64 exec, exec, s[78:79]
	v_mov_b64_e32 v[62:63], v[58:59]
	v_mov_b64_e32 v[60:61], v[56:57]
	v_mov_b32_e32 v69, v56
	v_mov_b32_e32 v85, v57
	v_mov_b32_e32 v84, v58
	v_mov_b32_e32 v88, v59
	v_lshl_add_u64 v[66:67], v[164:165], 0, v[72:73]
	v_cvt_pk_bf16_f32 v82, v69, v85
	v_cvt_pk_bf16_f32 v83, v84, v88
	global_store_dwordx2 v[66:67], v[82:83], off
	s_and_saveexec_b64 s[78:79], s[20:21]
	s_xor_b64 s[78:79], exec, s[78:79]
	s_mov_b64 s[70:71], exec
	v_add_u32_e32 v66, s87, v86
	s_or_saveexec_b64 s[78:79], s[78:79]
	v_mov_b64_e32 v[82:83], v[160:161]
	s_xor_b64 exec, exec, s[78:79]
	s_and_saveexec_b64 vcc, s[18:19]
	v_readlane_b32 s80, v254, 37
	v_readlane_b32 s81, v254, 38
	s_add_i32 s46, s53, s80
	s_or_b64 s[80:81], s[70:71], exec
	s_or_b64 exec, exec, vcc
	s_andn2_b64 s[70:71], s[70:71], exec
	s_and_b64 s[80:81], s[80:81], exec
	v_mov_b32_e32 v66, s46
	s_or_b64 s[70:71], s[70:71], s[80:81]
	v_mov_b64_e32 v[82:83], v[80:81]
	v_readlane_b32 s86, v254, 63
	v_readlane_b32 s87, v255, 0
	s_or_b64 exec, exec, s[78:79]
	s_and_saveexec_b64 s[78:79], s[70:71]
	v_ashrrev_i32_e32 v67, 31, v66
	v_lshl_add_u64 v[80:81], v[82:83], 2, v[156:157]
	v_lshlrev_b64 v[66:67], 16, v[66:67]
	v_lshl_add_u64 v[66:67], v[80:81], 0, v[66:67]
	global_store_dwordx4 v[66:67], v[60:63], off offset:16
	s_or_b64 exec, exec, s[78:79]
	s_mov_b64 s[70:71], 0x1100000
	v_lshl_add_u64 v[60:61], v[78:79], 0, s[70:71]
	v_mov_b64_e32 v[58:59], v[54:55]
	v_mov_b64_e32 v[56:57], v[52:53]
	v_mov_b32_e32 v69, v52
	v_mov_b32_e32 v79, v53
	v_mov_b32_e32 v78, v54
	v_mov_b32_e32 v80, v55
	v_lshl_add_u64 v[62:63], v[158:159], 0, v[72:73]
	v_cvt_pk_bf16_f32 v66, v69, v79
	v_cvt_pk_bf16_f32 v67, v78, v80
	global_store_dwordx2 v[62:63], v[66:67], off
	s_and_saveexec_b64 s[78:79], s[20:21]
	s_xor_b64 s[78:79], exec, s[78:79]
	s_mov_b64 s[70:71], exec
	v_add_u32_e32 v62, s87, v86
	s_or_saveexec_b64 s[78:79], s[78:79]
	v_mov_b64_e32 v[66:67], v[162:163]
	s_xor_b64 exec, exec, s[78:79]
	s_and_saveexec_b64 vcc, s[18:19]
	v_readlane_b32 s80, v254, 37
	v_readlane_b32 s81, v254, 38
	s_add_i32 s46, s53, s80
	s_or_b64 s[80:81], s[70:71], exec
	s_or_b64 exec, exec, vcc
	s_andn2_b64 s[70:71], s[70:71], exec
	s_and_b64 s[80:81], s[80:81], exec
	v_mov_b32_e32 v62, s46
	s_or_b64 s[70:71], s[70:71], s[80:81]
	v_mov_b64_e32 v[66:67], v[60:61]
	v_readlane_b32 s86, v254, 63
	v_readlane_b32 s87, v255, 0
	s_or_b64 exec, exec, s[78:79]
	s_and_saveexec_b64 s[78:79], s[70:71]
	v_ashrrev_i32_e32 v63, 31, v62
	v_lshl_add_u64 v[66:67], v[66:67], 2, v[156:157]
	v_lshlrev_b64 v[62:63], 16, v[62:63]
	v_lshl_add_u64 v[62:63], v[66:67], 0, v[62:63]
	global_store_dwordx4 v[62:63], v[56:59], off
	s_or_b64 exec, exec, s[78:79]
	v_mov_b64_e32 v[54:55], v[50:51]
	v_mov_b64_e32 v[52:53], v[48:49]
	v_mov_b32_e32 v62, v48
	v_mov_b32_e32 v66, v49
	v_mov_b32_e32 v63, v50
	v_mov_b32_e32 v67, v51
	s_andn2_b64 vcc, exec, s[96:97]
	v_lshl_add_u64 v[56:57], v[166:167], 0, v[72:73]
	v_cvt_pk_bf16_f32 v58, v62, v66
	v_cvt_pk_bf16_f32 v59, v63, v67
	global_store_dwordx2 v[56:57], v[58:59], off
	s_and_saveexec_b64 s[78:79], s[20:21]
	s_xor_b64 s[20:21], exec, s[78:79]
	s_mov_b64 s[70:71], exec
	v_add_u32_e32 v56, s87, v86
	s_or_saveexec_b64 s[20:21], s[20:21]
	v_mov_b64_e32 v[58:59], v[162:163]
	s_xor_b64 exec, exec, s[20:21]
	s_and_saveexec_b64 s[80:81], s[18:19]
	v_readlane_b32 s18, v254, 37
	s_add_i32 s46, s53, s18
	s_or_b64 s[78:79], s[70:71], exec
	v_readlane_b32 s19, v254, 38
	s_or_b64 exec, exec, s[80:81]
	s_andn2_b64 s[18:19], s[70:71], exec
	s_and_b64 s[70:71], s[78:79], exec
	v_mov_b32_e32 v56, s46
	s_or_b64 s[70:71], s[18:19], s[70:71]
	v_mov_b64_e32 v[58:59], v[60:61]
	s_or_b64 exec, exec, s[20:21]
	s_and_saveexec_b64 s[18:19], s[70:71]
	v_ashrrev_i32_e32 v57, 31, v56
	v_lshl_add_u64 v[58:59], v[58:59], 2, v[156:157]
	v_lshlrev_b64 v[56:57], 16, v[56:57]
	v_lshl_add_u64 v[56:57], v[58:59], 0, v[56:57]
	global_store_dwordx4 v[56:57], v[52:55], off offset:16
	s_or_b64 exec, exec, s[18:19]
	v_or_b32_e32 v48, 16, v68
	v_mad_i64_i32 v[58:59], s[18:19], v48, s61, 0
	s_movk_i32 s18, 0x3fff
	s_nop 0
	v_cmp_lt_i32_e64 s[20:21], s18, v48
	s_movk_i32 s18, 0x7df
	v_bitop3_b32 v50, v68, s18, 16 bitop3:0xc8
	s_movk_i32 s18, 0x4000
	v_cmp_gt_i32_e32 vcc, s18, v48
	v_add_u32_e32 v96, 0xfffff880, v50
	v_ashrrev_i32_e32 v49, 31, v48
	v_cndmask_b32_e32 v51, v151, v50, vcc
	v_lshlrev_b32_e32 v70, 3, v51
	v_add_u32_e32 v51, 0xffffc010, v68
	s_movk_i32 s18, 0x77f
	v_lshlrev_b64 v[60:61], 7, v[96:97]
	s_mov_b64 s[70:71], 0x1080000
	v_lshlrev_b64 v[54:55], 8, v[48:49]
	v_lshrrev_b32_e32 v69, 2, v51
	v_cmp_lt_u32_e64 s[18:19], s18, v50
	v_lshl_add_u64 v[62:63], v[60:61], 0, s[70:71]
	v_mov_b64_e32 v[50:51], v[46:47]
	v_mov_b64_e32 v[48:49], v[44:45]
	v_mov_b32_e32 v71, v44
	v_mov_b32_e32 v73, v45
	v_mov_b32_e32 v72, v46
	v_mov_b32_e32 v74, v47
	v_lshl_add_u64 v[64:65], v[154:155], 0, v[54:55]
	v_cvt_pk_bf16_f32 v66, v71, v73
	v_cvt_pk_bf16_f32 v67, v72, v74
	global_store_dwordx2 v[64:65], v[66:67], off
	s_and_saveexec_b64 s[78:79], s[20:21]
	s_xor_b64 s[78:79], exec, s[78:79]
	s_mov_b64 s[70:71], exec
	v_add_u32_e32 v64, s87, v69
	s_or_saveexec_b64 s[78:79], s[78:79]
	v_mov_b64_e32 v[66:67], v[160:161]
	s_xor_b64 exec, exec, s[78:79]
	s_and_saveexec_b64 vcc, s[18:19]
	v_readlane_b32 s80, v254, 37
	v_readlane_b32 s81, v254, 38
	s_add_i32 s46, s53, s80
	s_or_b64 s[80:81], s[70:71], exec
	s_or_b64 exec, exec, vcc
	s_andn2_b64 s[70:71], s[70:71], exec
	s_and_b64 s[80:81], s[80:81], exec
	v_mov_b32_e32 v64, s46
	s_or_b64 s[70:71], s[70:71], s[80:81]
	v_mov_b64_e32 v[66:67], v[62:63]
	v_readlane_b32 s86, v254, 63
	v_readlane_b32 s87, v255, 0
; __device__ __forceinline__ float shx16(float v, int odd  ) { const unsigned x = __builtin_bit_cast(unsigned, v); auto r = __builtin_amdgcn_permlane16_swap(x, x, false, false); return __builtin_bit_cast(float, odd ? r[0] : r[1]); }
; __device__ __forceinline__ void st_bf4(bf16_t* p, const f32x4 v) { u32x2 w; w.x = cvt_pk_bf16(v[0], v[1]); w.y = cvt_pk_bf16(v[2], v[3]); *(u32x2*)p = w; }
;     __device__ __forceinline__ void operator()(const f32x4 (&acc)[2][2][4][2], const Unit& u, int wr, int wc, int fr, int fq) const {
;     ...
;                     for (int n = 0; n < 2; ++n) { const int tc = bj * 128 + wc * 32 + 8 * fq + 4 * n; f32x4 v = acc[ai][bj][m][n];
;                         if (pn < 2) { *(f32x4*)(XA + (size_t)row * 512 + pn * 256 + tc) = v; }
;                         else if (pn <= 4) {
;                             const bool isv = (pn == 4 && bj == 1);
;                             if (!isv && (wc & 1) == 0) {
;                                 const int tix = row < cfg::MP ? (row & 2047) : 2048 + (row & 3);
;                                 const f32x4 cs = *(const f32x4*)(ropec + tix * 8 + 4 * n), sn = *(const f32x4*)(ropes + tix * 8 + 4 * n);
; #pragma unroll
;                                 for (int i = 0; i < 4; ++i) { const float p = shx16(v[i], fq & 1); const float rv = v[i] * cs[i] + (fq == 0 ? -p : p) * sn[i]; v[i] = fq < 2 ? rv : v[i]; }
;                             }
;                             if (pn < 4) st_bf4(Q + (size_t)row * 512 + (pn - 2) * 256 + tc, v);
;                             else { st_bf4((bj == 0 ? KB : VB) + (size_t)row * 128 + (tc & 127), v);
;                                 bool w = false; size_t o = 0;
;                                 if (row < cfg::MP) { const int t = row & 2047; if (t >= 1920) { w = true; o = (bj == 0 ? cfg::OFF_KP : cfg::OFF_VP) + ((size_t)(layer * 8 + (row >> 11)) * 128 + (t - 1920)) * 128 + (tc & 127); } }
;                                 else { const int rs = row - cfg::MP; w = true; o = (bj == 0 ? cfg::OFF_KS : cfg::OFF_VS) + ((size_t)(layer * 128 + (rs >> 2)) * 128 + 124 + (rs & 3)) * 128 + (tc & 127); }
;                                 if (w) *(f32x4*)(out + o) = v; }
	s_or_b64 exec, exec, s[78:79]
	s_and_saveexec_b64 s[78:79], s[70:71]
	v_ashrrev_i32_e32 v65, 31, v64
	v_lshl_add_u64 v[66:67], v[66:67], 2, v[156:157]
	v_lshlrev_b64 v[64:65], 16, v[64:65]
	v_lshl_add_u64 v[64:65], v[66:67], 0, v[64:65]
	global_store_dwordx4 v[64:65], v[48:51], off
	s_or_b64 exec, exec, s[78:79]
	v_mov_b64_e32 v[46:47], v[42:43]
	v_mov_b64_e32 v[44:45], v[40:41]
	v_mov_b32_e32 v66, v40
	v_mov_b32_e32 v71, v41
	v_mov_b32_e32 v67, v42
	v_mov_b32_e32 v72, v43
	v_lshl_add_u64 v[50:51], v[164:165], 0, v[54:55]
	v_cvt_pk_bf16_f32 v64, v66, v71
	v_cvt_pk_bf16_f32 v65, v67, v72
	global_store_dwordx2 v[50:51], v[64:65], off
	s_and_saveexec_b64 s[78:79], s[20:21]
	s_xor_b64 s[78:79], exec, s[78:79]
	s_mov_b64 s[70:71], exec
	v_add_u32_e32 v50, s87, v69
	s_or_saveexec_b64 s[78:79], s[78:79]
	v_mov_b64_e32 v[64:65], v[160:161]
	s_xor_b64 exec, exec, s[78:79]
	s_and_saveexec_b64 vcc, s[18:19]
	v_readlane_b32 s80, v254, 37
	v_readlane_b32 s81, v254, 38
	s_add_i32 s46, s53, s80
	s_or_b64 s[80:81], s[70:71], exec
	s_or_b64 exec, exec, vcc
	s_andn2_b64 s[70:71], s[70:71], exec
	s_and_b64 s[80:81], s[80:81], exec
	v_mov_b32_e32 v50, s46
	s_or_b64 s[70:71], s[70:71], s[80:81]
	v_mov_b64_e32 v[64:65], v[62:63]
	v_readlane_b32 s86, v254, 63
	v_readlane_b32 s87, v255, 0
	s_or_b64 exec, exec, s[78:79]
	s_and_saveexec_b64 s[78:79], s[70:71]
	v_ashrrev_i32_e32 v51, 31, v50
	v_lshl_add_u64 v[62:63], v[64:65], 2, v[156:157]
	v_lshlrev_b64 v[50:51], 16, v[50:51]
	v_lshl_add_u64 v[50:51], v[62:63], 0, v[50:51]
	global_store_dwordx4 v[50:51], v[44:47], off offset:16
	s_or_b64 exec, exec, s[78:79]
	s_mov_b64 s[70:71], 0x1100000
	v_lshl_add_u64 v[44:45], v[60:61], 0, s[70:71]
	v_mov_b64_e32 v[42:43], v[38:39]
	v_mov_b64_e32 v[40:41], v[36:37]
	v_mov_b32_e32 v60, v36
	v_mov_b32_e32 v62, v37
	v_mov_b32_e32 v61, v38
	v_mov_b32_e32 v63, v39
	v_lshl_add_u64 v[46:47], v[158:159], 0, v[54:55]
	v_cvt_pk_bf16_f32 v50, v60, v62
	v_cvt_pk_bf16_f32 v51, v61, v63
	global_store_dwordx2 v[46:47], v[50:51], off
	s_and_saveexec_b64 s[78:79], s[20:21]
	s_xor_b64 s[78:79], exec, s[78:79]
	s_mov_b64 s[70:71], exec
	v_add_u32_e32 v46, s87, v69
	s_or_saveexec_b64 s[78:79], s[78:79]
	v_mov_b64_e32 v[50:51], v[162:163]
	s_xor_b64 exec, exec, s[78:79]
	s_and_saveexec_b64 vcc, s[18:19]
	v_readlane_b32 s80, v254, 37
	v_readlane_b32 s81, v254, 38
	s_add_i32 s46, s53, s80
	s_or_b64 s[80:81], s[70:71], exec
	s_or_b64 exec, exec, vcc
	s_andn2_b64 s[70:71], s[70:71], exec
	s_and_b64 s[80:81], s[80:81], exec
	v_mov_b32_e32 v46, s46
	s_or_b64 s[70:71], s[70:71], s[80:81]
	v_mov_b64_e32 v[50:51], v[44:45]
	v_readlane_b32 s86, v254, 63
	v_readlane_b32 s87, v255, 0
	s_or_b64 exec, exec, s[78:79]
	s_and_saveexec_b64 s[78:79], s[70:71]
	v_ashrrev_i32_e32 v47, 31, v46
	v_lshl_add_u64 v[50:51], v[50:51], 2, v[156:157]
	v_lshlrev_b64 v[46:47], 16, v[46:47]
	v_lshl_add_u64 v[46:47], v[50:51], 0, v[46:47]
	global_store_dwordx4 v[46:47], v[40:43], off
	s_or_b64 exec, exec, s[78:79]
	v_mov_b64_e32 v[38:39], v[34:35]
	v_mov_b64_e32 v[36:37], v[32:33]
	v_mov_b32_e32 v46, v32
	v_mov_b32_e32 v50, v33
	v_mov_b32_e32 v47, v34
	v_mov_b32_e32 v51, v35
	s_andn2_b64 vcc, exec, s[96:97]
	v_lshl_add_u64 v[40:41], v[166:167], 0, v[54:55]
	v_cvt_pk_bf16_f32 v42, v46, v50
	v_cvt_pk_bf16_f32 v43, v47, v51
	global_store_dwordx2 v[40:41], v[42:43], off
	s_and_saveexec_b64 s[78:79], s[20:21]
	s_xor_b64 s[20:21], exec, s[78:79]
	s_mov_b64 s[70:71], exec
	v_add_u32_e32 v40, s87, v69
	s_or_saveexec_b64 s[20:21], s[20:21]
	v_mov_b64_e32 v[42:43], v[162:163]
	s_xor_b64 exec, exec, s[20:21]
	s_and_saveexec_b64 s[80:81], s[18:19]
	v_readlane_b32 s18, v254, 37
	s_add_i32 s46, s53, s18
	s_or_b64 s[78:79], s[70:71], exec
	v_readlane_b32 s19, v254, 38
	s_or_b64 exec, exec, s[80:81]
	s_andn2_b64 s[18:19], s[70:71], exec
	s_and_b64 s[70:71], s[78:79], exec
	v_mov_b32_e32 v40, s46
	s_or_b64 s[70:71], s[18:19], s[70:71]
	v_mov_b64_e32 v[42:43], v[44:45]
	s_or_b64 exec, exec, s[20:21]
	s_and_saveexec_b64 s[18:19], s[70:71]
	v_ashrrev_i32_e32 v41, 31, v40
	v_lshl_add_u64 v[42:43], v[42:43], 2, v[156:157]
	v_lshlrev_b64 v[40:41], 16, v[40:41]
	v_lshl_add_u64 v[40:41], v[42:43], 0, v[40:41]
	global_store_dwordx4 v[40:41], v[36:39], off offset:16
	s_or_b64 exec, exec, s[18:19]
	v_or_b32_e32 v32, 32, v68
	v_mad_i64_i32 v[42:43], s[18:19], v32, s61, 0
	s_movk_i32 s18, 0x3fff
	s_nop 0
	v_cmp_lt_i32_e64 s[20:21], s18, v32
	s_movk_i32 s18, 0x7ef
	v_bitop3_b32 v34, v68, s18, 32 bitop3:0xc8
	s_movk_i32 s18, 0x4000
	v_cmp_gt_i32_e32 vcc, s18, v32
	v_add_u32_e32 v96, 0xfffff880, v34
	v_ashrrev_i32_e32 v33, 31, v32
	v_cndmask_b32_e32 v35, v151, v34, vcc
	v_lshlrev_b32_e32 v53, 3, v35
	v_add_u32_e32 v35, 0xffffc020, v68
	s_movk_i32 s18, 0x77f
	v_lshlrev_b64 v[44:45], 7, v[96:97]
	s_mov_b64 s[70:71], 0x1080000
	v_lshlrev_b64 v[38:39], 8, v[32:33]
	v_lshrrev_b32_e32 v52, 2, v35
	v_cmp_lt_u32_e64 s[18:19], s18, v34
	v_lshl_add_u64 v[46:47], v[44:45], 0, s[70:71]
	v_mov_b64_e32 v[34:35], v[30:31]
	v_mov_b64_e32 v[32:33], v[28:29]
	v_mov_b32_e32 v54, v28
	v_mov_b32_e32 v56, v29
	v_mov_b32_e32 v55, v30
	v_mov_b32_e32 v57, v31
	v_lshl_add_u64 v[48:49], v[154:155], 0, v[38:39]
	v_cvt_pk_bf16_f32 v50, v54, v56
	v_cvt_pk_bf16_f32 v51, v55, v57
	global_store_dwordx2 v[48:49], v[50:51], off
	s_and_saveexec_b64 s[78:79], s[20:21]
	s_xor_b64 s[78:79], exec, s[78:79]
	s_mov_b64 s[70:71], exec
	v_add_u32_e32 v48, s87, v52
	s_or_saveexec_b64 s[78:79], s[78:79]
	v_mov_b64_e32 v[50:51], v[160:161]
	s_xor_b64 exec, exec, s[78:79]
	s_and_saveexec_b64 vcc, s[18:19]
	v_readlane_b32 s80, v254, 37
	v_readlane_b32 s81, v254, 38
	s_add_i32 s46, s53, s80
; __device__ __forceinline__ float shx16(float v, int odd  ) { const unsigned x = __builtin_bit_cast(unsigned, v); auto r = __builtin_amdgcn_permlane16_swap(x, x, false, false); return __builtin_bit_cast(float, odd ? r[0] : r[1]); }
; __device__ __forceinline__ void st_bf4(bf16_t* p, const f32x4 v) { u32x2 w; w.x = cvt_pk_bf16(v[0], v[1]); w.y = cvt_pk_bf16(v[2], v[3]); *(u32x2*)p = w; }
;     __device__ __forceinline__ void operator()(const f32x4 (&acc)[2][2][4][2], const Unit& u, int wr, int wc, int fr, int fq) const {
;     ...
;                     for (int n = 0; n < 2; ++n) { const int tc = bj * 128 + wc * 32 + 8 * fq + 4 * n; f32x4 v = acc[ai][bj][m][n];
;                         if (pn < 2) { *(f32x4*)(XA + (size_t)row * 512 + pn * 256 + tc) = v; }
;                         else if (pn <= 4) {
;                             const bool isv = (pn == 4 && bj == 1);
;                             if (!isv && (wc & 1) == 0) {
;                                 const int tix = row < cfg::MP ? (row & 2047) : 2048 + (row & 3);
;                                 const f32x4 cs = *(const f32x4*)(ropec + tix * 8 + 4 * n), sn = *(const f32x4*)(ropes + tix * 8 + 4 * n);
; #pragma unroll
;                                 for (int i = 0; i < 4; ++i) { const float p = shx16(v[i], fq & 1); const float rv = v[i] * cs[i] + (fq == 0 ? -p : p) * sn[i]; v[i] = fq < 2 ? rv : v[i]; }
;                             }
;                             if (pn < 4) st_bf4(Q + (size_t)row * 512 + (pn - 2) * 256 + tc, v);
;                             else { st_bf4((bj == 0 ? KB : VB) + (size_t)row * 128 + (tc & 127), v);
;                                 bool w = false; size_t o = 0;
;                                 if (row < cfg::MP) { const int t = row & 2047; if (t >= 1920) { w = true; o = (bj == 0 ? cfg::OFF_KP : cfg::OFF_VP) + ((size_t)(layer * 8 + (row >> 11)) * 128 + (t - 1920)) * 128 + (tc & 127); } }
;                                 else { const int rs = row - cfg::MP; w = true; o = (bj == 0 ? cfg::OFF_KS : cfg::OFF_VS) + ((size_t)(layer * 128 + (rs >> 2)) * 128 + 124 + (rs & 3)) * 128 + (tc & 127); }
;                                 if (w) *(f32x4*)(out + o) = v; }
	s_or_b64 s[80:81], s[70:71], exec
	s_or_b64 exec, exec, vcc
	s_andn2_b64 s[70:71], s[70:71], exec
	s_and_b64 s[80:81], s[80:81], exec
	v_mov_b32_e32 v48, s46
	s_or_b64 s[70:71], s[70:71], s[80:81]
	v_mov_b64_e32 v[50:51], v[46:47]
	v_readlane_b32 s86, v254, 63
	v_readlane_b32 s87, v255, 0
	s_or_b64 exec, exec, s[78:79]
	s_and_saveexec_b64 s[78:79], s[70:71]
	v_ashrrev_i32_e32 v49, 31, v48
	v_lshl_add_u64 v[50:51], v[50:51], 2, v[156:157]
	v_lshlrev_b64 v[48:49], 16, v[48:49]
	v_lshl_add_u64 v[48:49], v[50:51], 0, v[48:49]
	global_store_dwordx4 v[48:49], v[32:35], off
	s_or_b64 exec, exec, s[78:79]
	v_mov_b64_e32 v[30:31], v[26:27]
	v_mov_b64_e32 v[28:29], v[24:25]
	v_mov_b32_e32 v50, v24
	v_mov_b32_e32 v54, v25
	v_mov_b32_e32 v51, v26
	v_mov_b32_e32 v55, v27
	v_lshl_add_u64 v[34:35], v[164:165], 0, v[38:39]
	v_cvt_pk_bf16_f32 v48, v50, v54
	v_cvt_pk_bf16_f32 v49, v51, v55
	global_store_dwordx2 v[34:35], v[48:49], off
	s_and_saveexec_b64 s[78:79], s[20:21]
	s_xor_b64 s[78:79], exec, s[78:79]
	s_mov_b64 s[70:71], exec
	v_add_u32_e32 v34, s87, v52
	s_or_saveexec_b64 s[78:79], s[78:79]
	v_mov_b64_e32 v[48:49], v[160:161]
	s_xor_b64 exec, exec, s[78:79]
	s_and_saveexec_b64 vcc, s[18:19]
	v_readlane_b32 s80, v254, 37
	v_readlane_b32 s81, v254, 38
	s_add_i32 s46, s53, s80
	s_or_b64 s[80:81], s[70:71], exec
	s_or_b64 exec, exec, vcc
	s_andn2_b64 s[70:71], s[70:71], exec
	s_and_b64 s[80:81], s[80:81], exec
	v_mov_b32_e32 v34, s46
	s_or_b64 s[70:71], s[70:71], s[80:81]
	v_mov_b64_e32 v[48:49], v[46:47]
	v_readlane_b32 s86, v254, 63
	v_readlane_b32 s87, v255, 0
	s_or_b64 exec, exec, s[78:79]
	s_and_saveexec_b64 s[78:79], s[70:71]
	v_ashrrev_i32_e32 v35, 31, v34
	v_lshl_add_u64 v[46:47], v[48:49], 2, v[156:157]
	v_lshlrev_b64 v[34:35], 16, v[34:35]
	v_lshl_add_u64 v[34:35], v[46:47], 0, v[34:35]
	global_store_dwordx4 v[34:35], v[28:31], off offset:16
	s_or_b64 exec, exec, s[78:79]
	s_mov_b64 s[70:71], 0x1100000
	v_lshl_add_u64 v[28:29], v[44:45], 0, s[70:71]
	v_mov_b64_e32 v[26:27], v[22:23]
	v_mov_b64_e32 v[24:25], v[20:21]
	v_mov_b32_e32 v44, v20
	v_mov_b32_e32 v46, v21
	v_mov_b32_e32 v45, v22
	v_mov_b32_e32 v47, v23
	v_lshl_add_u64 v[30:31], v[158:159], 0, v[38:39]
	v_cvt_pk_bf16_f32 v34, v44, v46
	v_cvt_pk_bf16_f32 v35, v45, v47
	global_store_dwordx2 v[30:31], v[34:35], off
	s_and_saveexec_b64 s[78:79], s[20:21]
	s_xor_b64 s[78:79], exec, s[78:79]
	s_mov_b64 s[70:71], exec
	v_add_u32_e32 v30, s87, v52
	s_or_saveexec_b64 s[78:79], s[78:79]
	v_mov_b64_e32 v[34:35], v[162:163]
	s_xor_b64 exec, exec, s[78:79]
	s_and_saveexec_b64 vcc, s[18:19]
	v_readlane_b32 s80, v254, 37
	v_readlane_b32 s81, v254, 38
	s_add_i32 s46, s53, s80
	s_or_b64 s[80:81], s[70:71], exec
	s_or_b64 exec, exec, vcc
	s_andn2_b64 s[70:71], s[70:71], exec
	s_and_b64 s[80:81], s[80:81], exec
	v_mov_b32_e32 v30, s46
	s_or_b64 s[70:71], s[70:71], s[80:81]
	v_mov_b64_e32 v[34:35], v[28:29]
	v_readlane_b32 s86, v254, 63
	v_readlane_b32 s87, v255, 0
	s_or_b64 exec, exec, s[78:79]
	s_and_saveexec_b64 s[78:79], s[70:71]
	v_ashrrev_i32_e32 v31, 31, v30
	v_lshl_add_u64 v[34:35], v[34:35], 2, v[156:157]
	v_lshlrev_b64 v[30:31], 16, v[30:31]
	v_lshl_add_u64 v[30:31], v[34:35], 0, v[30:31]
	global_store_dwordx4 v[30:31], v[24:27], off
	s_or_b64 exec, exec, s[78:79]
	v_mov_b64_e32 v[22:23], v[18:19]
	v_mov_b64_e32 v[20:21], v[16:17]
	v_mov_b32_e32 v30, v16
	v_mov_b32_e32 v34, v17
	v_mov_b32_e32 v31, v18
	v_mov_b32_e32 v35, v19
	s_andn2_b64 vcc, exec, s[96:97]
	v_lshl_add_u64 v[24:25], v[166:167], 0, v[38:39]
	v_cvt_pk_bf16_f32 v26, v30, v34
	v_cvt_pk_bf16_f32 v27, v31, v35
	global_store_dwordx2 v[24:25], v[26:27], off
	s_and_saveexec_b64 s[78:79], s[20:21]
	s_xor_b64 s[20:21], exec, s[78:79]
	s_mov_b64 s[70:71], exec
	v_add_u32_e32 v24, s87, v52
	s_or_saveexec_b64 s[20:21], s[20:21]
	v_mov_b64_e32 v[26:27], v[162:163]
	s_xor_b64 exec, exec, s[20:21]
	s_and_saveexec_b64 s[80:81], s[18:19]
	v_readlane_b32 s18, v254, 37
	s_add_i32 s46, s53, s18
	s_or_b64 s[78:79], s[70:71], exec
	v_readlane_b32 s19, v254, 38
	s_or_b64 exec, exec, s[80:81]
	s_andn2_b64 s[18:19], s[70:71], exec
	s_and_b64 s[70:71], s[78:79], exec
	v_mov_b32_e32 v24, s46
	s_or_b64 s[70:71], s[18:19], s[70:71]
	v_mov_b64_e32 v[26:27], v[28:29]
	s_or_b64 exec, exec, s[20:21]
	s_and_saveexec_b64 s[18:19], s[70:71]
	v_ashrrev_i32_e32 v25, 31, v24
	v_lshl_add_u64 v[26:27], v[26:27], 2, v[156:157]
	v_lshlrev_b64 v[24:25], 16, v[24:25]
	v_lshl_add_u64 v[24:25], v[26:27], 0, v[24:25]
	global_store_dwordx4 v[24:25], v[20:23], off offset:16
	s_or_b64 exec, exec, s[18:19]
	v_or_b32_e32 v16, 48, v68
	v_mad_i64_i32 v[26:27], s[18:19], v16, s61, 0
	s_movk_i32 s18, 0x3fff
	s_nop 0
	v_cmp_lt_i32_e64 s[20:21], s18, v16
	s_movk_i32 s18, 0x7ff
	v_bitop3_b32 v18, v68, s18, 48 bitop3:0xc8
	s_movk_i32 s18, 0x4000
	v_cmp_gt_i32_e32 vcc, s18, v16
	v_add_u32_e32 v96, 0xfffff880, v18
	v_ashrrev_i32_e32 v17, 31, v16
	v_cndmask_b32_e32 v19, v151, v18, vcc
	v_lshlrev_b32_e32 v37, 3, v19
	v_add_u32_e32 v19, 0xffffc030, v68
	s_movk_i32 s18, 0x77f
	v_lshlrev_b64 v[28:29], 7, v[96:97]
	s_mov_b64 s[70:71], 0x1080000
	v_lshlrev_b64 v[24:25], 11, v[16:17]
	v_lshlrev_b64 v[22:23], 8, v[16:17]
	v_lshrrev_b32_e32 v36, 2, v19
	v_cmp_lt_u32_e64 s[18:19], s18, v18
	v_lshlrev_b64 v[20:21], 10, v[16:17]
	v_lshl_add_u64 v[30:31], v[28:29], 0, s[70:71]
	v_mov_b64_e32 v[18:19], v[14:15]
	v_mov_b64_e32 v[16:17], v[12:13]
	v_mov_b32_e32 v38, v12
	v_mov_b32_e32 v40, v13
	v_mov_b32_e32 v39, v14
	v_mov_b32_e32 v41, v15
	v_lshl_add_u64 v[32:33], v[154:155], 0, v[22:23]
	v_cvt_pk_bf16_f32 v34, v38, v40
	v_cvt_pk_bf16_f32 v35, v39, v41
	global_store_dwordx2 v[32:33], v[34:35], off
; __device__ __forceinline__ float shx16(float v, int odd  ) { const unsigned x = __builtin_bit_cast(unsigned, v); auto r = __builtin_amdgcn_permlane16_swap(x, x, false, false); return __builtin_bit_cast(float, odd ? r[0] : r[1]); }
; __device__ __forceinline__ void st_bf4(bf16_t* p, const f32x4 v) { u32x2 w; w.x = cvt_pk_bf16(v[0], v[1]); w.y = cvt_pk_bf16(v[2], v[3]); *(u32x2*)p = w; }
;     __device__ __forceinline__ void operator()(const f32x4 (&acc)[2][2][4][2], const Unit& u, int wr, int wc, int fr, int fq) const {
;     ...
;                     for (int n = 0; n < 2; ++n) { const int tc = bj * 128 + wc * 32 + 8 * fq + 4 * n; f32x4 v = acc[ai][bj][m][n];
;                         if (pn < 2) { *(f32x4*)(XA + (size_t)row * 512 + pn * 256 + tc) = v; }
;                         else if (pn <= 4) {
;                             const bool isv = (pn == 4 && bj == 1);
;                             if (!isv && (wc & 1) == 0) {
;                                 const int tix = row < cfg::MP ? (row & 2047) : 2048 + (row & 3);
;                                 const f32x4 cs = *(const f32x4*)(ropec + tix * 8 + 4 * n), sn = *(const f32x4*)(ropes + tix * 8 + 4 * n);
; #pragma unroll
;                                 for (int i = 0; i < 4; ++i) { const float p = shx16(v[i], fq & 1); const float rv = v[i] * cs[i] + (fq == 0 ? -p : p) * sn[i]; v[i] = fq < 2 ? rv : v[i]; }
;                             }
;                             if (pn < 4) st_bf4(Q + (size_t)row * 512 + (pn - 2) * 256 + tc, v);
;                             else { st_bf4((bj == 0 ? KB : VB) + (size_t)row * 128 + (tc & 127), v);
;                                 bool w = false; size_t o = 0;
;                                 if (row < cfg::MP) { const int t = row & 2047; if (t >= 1920) { w = true; o = (bj == 0 ? cfg::OFF_KP : cfg::OFF_VP) + ((size_t)(layer * 8 + (row >> 11)) * 128 + (t - 1920)) * 128 + (tc & 127); } }
;                                 else { const int rs = row - cfg::MP; w = true; o = (bj == 0 ? cfg::OFF_KS : cfg::OFF_VS) + ((size_t)(layer * 128 + (rs >> 2)) * 128 + 124 + (rs & 3)) * 128 + (tc & 127); }
;                                 if (w) *(f32x4*)(out + o) = v; }
	s_and_saveexec_b64 s[78:79], s[20:21]
	s_xor_b64 s[78:79], exec, s[78:79]
	s_mov_b64 s[70:71], exec
	v_add_u32_e32 v32, s87, v36
	s_or_saveexec_b64 s[78:79], s[78:79]
	v_mov_b64_e32 v[34:35], v[160:161]
	s_xor_b64 exec, exec, s[78:79]
	s_and_saveexec_b64 vcc, s[18:19]
	v_readlane_b32 s80, v254, 37
	v_readlane_b32 s81, v254, 38
	s_add_i32 s46, s53, s80
	s_or_b64 s[80:81], s[70:71], exec
	s_or_b64 exec, exec, vcc
	s_andn2_b64 s[70:71], s[70:71], exec
	s_and_b64 s[80:81], s[80:81], exec
	v_mov_b32_e32 v32, s46
	s_or_b64 s[70:71], s[70:71], s[80:81]
	v_mov_b64_e32 v[34:35], v[30:31]
	v_readlane_b32 s86, v254, 63
	v_readlane_b32 s87, v255, 0
	s_or_b64 exec, exec, s[78:79]
	s_and_saveexec_b64 s[78:79], s[70:71]
	v_ashrrev_i32_e32 v33, 31, v32
	v_lshl_add_u64 v[34:35], v[34:35], 2, v[156:157]
	v_lshlrev_b64 v[32:33], 16, v[32:33]
	v_lshl_add_u64 v[32:33], v[34:35], 0, v[32:33]
	global_store_dwordx4 v[32:33], v[16:19], off
	s_or_b64 exec, exec, s[78:79]
	s_nop 0
	v_lshl_add_u64 v[16:17], s[30:31], 0, v[24:25]
	v_lshl_add_u64 v[16:17], s[92:93], 2, v[16:17]
	v_mov_b64_e32 v[14:15], v[10:11]
	v_mov_b64_e32 v[12:13], v[8:9]
	v_mov_b32_e32 v34, v8
	v_mov_b32_e32 v38, v9
	v_mov_b32_e32 v35, v10
	v_mov_b32_e32 v39, v11
	v_lshl_add_u64 v[18:19], v[164:165], 0, v[22:23]
	v_cvt_pk_bf16_f32 v32, v34, v38
	v_cvt_pk_bf16_f32 v33, v35, v39
	global_store_dwordx2 v[18:19], v[32:33], off
	s_and_saveexec_b64 s[78:79], s[20:21]
	s_xor_b64 s[78:79], exec, s[78:79]
	s_mov_b64 s[70:71], exec
	v_add_u32_e32 v18, s87, v36
	s_or_saveexec_b64 s[78:79], s[78:79]
	v_mov_b64_e32 v[32:33], v[160:161]
	s_xor_b64 exec, exec, s[78:79]
	s_and_saveexec_b64 s[92:93], s[18:19]
	v_readlane_b32 s80, v254, 37
	v_readlane_b32 s81, v254, 38
	s_add_i32 s46, s53, s80
	s_or_b64 s[80:81], s[70:71], exec
	s_or_b64 exec, exec, s[92:93]
	s_andn2_b64 s[70:71], s[70:71], exec
	s_and_b64 s[80:81], s[80:81], exec
	v_mov_b32_e32 v18, s46
	s_or_b64 s[70:71], s[70:71], s[80:81]
	v_mov_b64_e32 v[32:33], v[30:31]
	v_readlane_b32 s86, v254, 63
	v_readlane_b32 s87, v255, 0
	s_or_b64 exec, exec, s[78:79]
	s_and_saveexec_b64 s[78:79], s[70:71]
	v_ashrrev_i32_e32 v19, 31, v18
	v_lshl_add_u64 v[30:31], v[32:33], 2, v[156:157]
	v_lshlrev_b64 v[18:19], 16, v[18:19]
	v_lshl_add_u64 v[18:19], v[30:31], 0, v[18:19]
	global_store_dwordx4 v[18:19], v[12:15], off offset:16
	s_or_b64 exec, exec, s[78:79]
	s_mov_b64 s[70:71], 0x1100000
	v_lshl_add_u64 v[12:13], v[28:29], 0, s[70:71]
	v_mov_b64_e32 v[10:11], v[6:7]
	v_mov_b64_e32 v[8:9], v[4:5]
	v_mov_b32_e32 v28, v4
	v_mov_b32_e32 v30, v5
	v_mov_b32_e32 v29, v6
	v_mov_b32_e32 v31, v7
	v_lshl_add_u64 v[14:15], v[158:159], 0, v[22:23]
	v_cvt_pk_bf16_f32 v18, v28, v30
	v_cvt_pk_bf16_f32 v19, v29, v31
	global_store_dwordx2 v[14:15], v[18:19], off
	s_and_saveexec_b64 s[78:79], s[20:21]
	s_xor_b64 s[78:79], exec, s[78:79]
	s_mov_b64 s[70:71], exec
	v_add_u32_e32 v14, s87, v36
	s_or_saveexec_b64 s[78:79], s[78:79]
	v_mov_b64_e32 v[18:19], v[162:163]
	s_xor_b64 exec, exec, s[78:79]
	s_and_saveexec_b64 s[92:93], s[18:19]
	v_readlane_b32 s80, v254, 37
	v_readlane_b32 s81, v254, 38
	s_add_i32 s46, s53, s80
	s_or_b64 s[80:81], s[70:71], exec
	s_or_b64 exec, exec, s[92:93]
	s_andn2_b64 s[70:71], s[70:71], exec
	s_and_b64 s[80:81], s[80:81], exec
	v_mov_b32_e32 v14, s46
	s_or_b64 s[70:71], s[70:71], s[80:81]
	v_mov_b64_e32 v[18:19], v[12:13]
	v_readlane_b32 s86, v254, 63
	v_readlane_b32 s87, v255, 0
	s_or_b64 exec, exec, s[78:79]
	s_and_saveexec_b64 s[78:79], s[70:71]
	v_ashrrev_i32_e32 v15, 31, v14
	v_lshl_add_u64 v[18:19], v[18:19], 2, v[156:157]
	v_lshlrev_b64 v[14:15], 16, v[14:15]
	v_lshl_add_u64 v[14:15], v[18:19], 0, v[14:15]
	global_store_dwordx4 v[14:15], v[8:11], off
	s_or_b64 exec, exec, s[78:79]
	s_mov_b32 s70, 0x1200000
	s_mov_b32 s71, 0x1400000
	v_mov_b64_e32 v[6:7], v[2:3]
	v_mov_b64_e32 v[4:5], v[0:1]
	v_mov_b32_e32 v14, v0
	v_mov_b32_e32 v18, v1
	v_mov_b32_e32 v15, v2
	v_mov_b32_e32 v19, v3
	v_lshl_add_u64 v[8:9], v[166:167], 0, v[22:23]
	v_cvt_pk_bf16_f32 v10, v14, v18
	v_cvt_pk_bf16_f32 v11, v15, v19
	global_store_dwordx2 v[8:9], v[10:11], off
	s_and_saveexec_b64 s[16:17], s[20:21]
	s_xor_b64 s[16:17], exec, s[16:17]
	s_mov_b64 s[14:15], exec
	v_add_u32_e32 v8, s87, v36
	s_or_saveexec_b64 s[16:17], s[16:17]
	v_mov_b64_e32 v[10:11], v[162:163]
	s_xor_b64 exec, exec, s[16:17]
	s_and_saveexec_b64 s[28:29], s[18:19]
	v_readlane_b32 s18, v254, 37
	s_add_i32 s46, s53, s18
	s_or_b64 s[20:21], s[14:15], exec
	v_readlane_b32 s19, v254, 38
	s_or_b64 exec, exec, s[28:29]
	s_andn2_b64 s[14:15], s[14:15], exec
	s_and_b64 s[18:19], s[20:21], exec
	v_mov_b32_e32 v8, s46
	s_or_b64 s[14:15], s[14:15], s[18:19]
	v_mov_b64_e32 v[10:11], v[12:13]
	s_or_b64 exec, exec, s[16:17]
	s_and_saveexec_b64 s[16:17], s[14:15]
	v_ashrrev_i32_e32 v9, 31, v8
	v_lshl_add_u64 v[10:11], v[10:11], 2, v[156:157]
	v_lshlrev_b64 v[8:9], 16, v[8:9]
	v_lshl_add_u64 v[8:9], v[10:11], 0, v[8:9]
	global_store_dwordx4 v[8:9], v[4:7], off offset:16
	s_or_b64 exec, exec, s[16:17]
	s_branch .LBB0_1574
; #define PG8_WAIT_V(n) asm volatile("s_waitcnt vmcnt(" #n ")" ::: "memory")
; #define PG8_BAR __builtin_amdgcn_s_barrier()
; template <class Epi, class Sched, bool ALIGN_EPI = false, bool SP2 = false>
; __device__ __forceinline__ void gemm_phase(PG8_LAS unsigned char* lds, const Gemm g, const Sched& S, const Epi& E, const int tid_in) {
;     ...
;     PG8_WAIT_V(0);
;     if constexpr (!ALIGN_EPI) { if (wr == 0) PG8_BAR; }
;     PG8_BAR;
.LBB0_1577:
.LBB0_1578:
.LBB0_1580:
.LBB0_1581:
.LBB0_1582:
.LBB0_1583:
.LBB0_1584:
.LBB0_1586:
.LBB0_1587:
.LBB0_1588:
.LBB0_1589:
.LBB0_1590:
.LBB0_1592:
.LBB0_1593:
.LBB0_1594:
.LBB0_1595:
.LBB0_1596:
.LBB0_1598:
.LBB0_1599:
.LBB0_1600:
.LBB0_1601:
.LBB0_1602:
.LBB0_1604:
.LBB0_1605:
.LBB0_1606:
.LBB0_1607:
.LBB0_1608:
.LBB0_1610:
.LBB0_1611:
.LBB0_1612:
.LBB0_1613:
.LBB0_1614:
.LBB0_1616:
.LBB0_1617:
.LBB0_1618:
.LBB0_1619:
.LBB0_1620:
.LBB0_1622:
.LBB0_1623:
.LBB0_1624:
.LBB0_1625:
.LBB0_1626:
.LBB0_1628:
.LBB0_1629:
.LBB0_1630:
.LBB0_1631:
.LBB0_1632:
.LBB0_1634:
.LBB0_1635:
.LBB0_1636:
.LBB0_1637:
.LBB0_1638:
.LBB0_1640:
.LBB0_1641:
.LBB0_1642:
.LBB0_1643:
.LBB0_1644:
.LBB0_1646:
.LBB0_1647:
.LBB0_1648:
.LBB0_1649:
.LBB0_1650:
.LBB0_1652:
.LBB0_1653:
.LBB0_1654:
.LBB0_1655:
.LBB0_1656:
.LBB0_1658:
.LBB0_1659:
.LBB0_1660:
.LBB0_1661:
.LBB0_1662:
.LBB0_1664:
.LBB0_1665:
.LBB0_1666:
.LBB0_1667:
.LBB0_1668:
.LBB0_1670:
.LBB0_1671:
.LBB0_1672:
.LBB0_1673:
.LBB0_1674:
.LBB0_1676:
.LBB0_1677:
.LBB0_1678:
.LBB0_1679:
.LBB0_1680:
.LBB0_1682:
.LBB0_1683:
.LBB0_1684:
.LBB0_1685:
.LBB0_1686:
.LBB0_1688:
.LBB0_1689:
.LBB0_1690:
.LBB0_1691:
.LBB0_1692:
.LBB0_1694:
.LBB0_1695:
.LBB0_1696:
.LBB0_1697:
.LBB0_1698:
.LBB0_1700:
.LBB0_1701:
.LBB0_1702:
.LBB0_1703:
.LBB0_1704:
.LBB0_1706:
.LBB0_1707:
.LBB0_1708:
.LBB0_1709:
.LBB0_1710:
.LBB0_1712:
.LBB0_1713:
.LBB0_1714:
.LBB0_1715:
.LBB0_1716:
.LBB0_1718:
.LBB0_1719:
.LBB0_1720:
.LBB0_1721:
.LBB0_1722:
.LBB0_1724:
.LBB0_1725:
.LBB0_1726:
.LBB0_1727:
.LBB0_1728:
.LBB0_1730:
.LBB0_1731:
.LBB0_1732:
.LBB0_1733:
.LBB0_1734:
.LBB0_1736:
.LBB0_1737:
.LBB0_1738:
.LBB0_1739:
.LBB0_1740:
.LBB0_1742:
.LBB0_1743:
.LBB0_1744:
.LBB0_1745:
.LBB0_1746:
.LBB0_1748:
.LBB0_1749:
.LBB0_1750:
.LBB0_1751:
.LBB0_1752:
.LBB0_1754:
.LBB0_1755:
.LBB0_1756:
.LBB0_1757:
.LBB0_1758:
.LBB0_1760:
.LBB0_1761:
.LBB0_1762:
.LBB0_1763:
.LBB0_1764:
.LBB0_1766:
.LBB0_1767:
.LBB0_1768:
.LBB0_1769:
.LBB0_1770:
.LBB0_1772:
.LBB0_1773:
.LBB0_1774:
.LBB0_1776:
.LBB0_1777:
.LBB0_1778:
.LBB0_1780:
.LBB0_1781:
.LBB0_1782:
.LBB0_1784:
.LBB0_1785:
.LBB0_1786:
.LBB0_1788:
.LBB0_1789:
.LBB0_1790:
.LBB0_1792:
.LBB0_1793:
.LBB0_1794:
.LBB0_1796:
.LBB0_1797:
.LBB0_1798:
.LBB0_1800:
.LBB0_1801:
.LBB0_1802:
.LBB0_1804:
.LBB0_1805:
.LBB0_1806:
.LBB0_1808:
.LBB0_1809:
.LBB0_1810:
.LBB0_1812:
.LBB0_1813:
.LBB0_1814:
.LBB0_1816:
.LBB0_1817:
.LBB0_1818:
.LBB0_1820:
.LBB0_1821:
.LBB0_1822:
.LBB0_1824:
.LBB0_1825:
.LBB0_1826:
.LBB0_1828:
.LBB0_1829:
.LBB0_1830:
.LBB0_1832:
.LBB0_1833:
.LBB0_1834:
.LBB0_1836:
.LBB0_1837:
.LBB0_1838:
.LBB0_1840:
.LBB0_1841:
.LBB0_1842:
.LBB0_1844:
.LBB0_1845:
.LBB0_1846:
.LBB0_1848:
.LBB0_1849:
.LBB0_1850:
.LBB0_1852:
.LBB0_1853:
.LBB0_1854:
.LBB0_1856:
.LBB0_1857:
.LBB0_1858:
.LBB0_1860:
.LBB0_1861:
.LBB0_1862:
.LBB0_1864:
.LBB0_1865:
.LBB0_1866:
.LBB0_1868:
.LBB0_1869:
.LBB0_1870:
.LBB0_1872:
.LBB0_1873:
.LBB0_1874:
.LBB0_1876:
.LBB0_1877:
.LBB0_1878:
.LBB0_1880:
.LBB0_1881:
.LBB0_1882:
.LBB0_1884:
.LBB0_1885:
.LBB0_1886:
.LBB0_1888:
.LBB0_1889:
.LBB0_1890:
.LBB0_1892:
.LBB0_1893:
.LBB0_1894:
.LBB0_1896:
.LBB0_1897:
	s_waitcnt vmcnt(0)
	v_readlane_b32 s82, v254, 45
	v_readlane_b32 s78, v254, 49
	v_readlane_b32 s80, v254, 47
	v_readlane_b32 s83, v254, 46
	v_readlane_b32 s76, v254, 51
	v_readlane_b32 s79, v254, 50
	v_readlane_b32 s81, v254, 48
	v_readlane_b32 s77, v254, 44
	v_readlane_b32 s90, v254, 43
	v_readlane_b32 s83, v254, 42
	v_readlane_b32 s91, v254, 41
	v_readlane_b32 s92, v254, 40
	s_movk_i32 s93, 0x3ff
	v_readlane_b32 s95, v254, 39
	s_mov_b32 s74, 0x600000
	s_mov_b32 s72, 0xa00000
	s_mov_b32 s73, 0xc00000
	s_mov_b32 s46, 0xe00000
	s_mov_b32 s60, 0x1000000
	s_barrier
